# GEMM K-loops: per-segment s_setprio flips removed, one static s_setprio 1 for waves 4-7 before each loop (reset at phase exit); on top of v42
# speedup vs baseline: 1.0051x; 1.0046x over previous
;     DI const char* aptr(const Unit& u) const { return A + (size_t)u.pm * ta + (size_t)kofs(u.seg) * 2; }
;     DI const char* bptr(const Unit& u) const { return B + (size_t)u.pn * tb + (size_t)kofs(u.seg) * 2; }
; #define PG8_STAGE(bufoff, gbase, voff) do { _Pragma("unroll") for (int _i = 0; _i < 2; ++_i) \
;         __builtin_amdgcn_global_load_lds((const unsigned*)((const char*)(gbase) + (voff)[_i]), (LAS unsigned*)(lds + (bufoff) + ldsw + _i * 8192), 16, 0, 0); } while (0)
; #define PG8_WAIT_V(n) asm volatile("s_waitcnt vmcnt(" #n ")" ::: "memory")
; #define PG8_BAR __builtin_amdgcn_s_barrier()
; template <class Epi, class Sched>
; DI void gemm_phase(LAS unsigned char* lds, const int wv, const int lda, const int ldb, const Sched& S, const Epi& E) {
;     ...
;     const int tid = tid_, wid = __builtin_amdgcn_readfirstlane(tid >> 6), lane = tid & 63, wr = wid >> 2, wc = wid & 3, fr = lane & 15, fq = lane >> 4;
;     unsigned voffA[2], voffB[2];
; #pragma unroll
;     for (int i = 0; i < 2; ++i) { int R, C; stage_rc(tid * 16 + i * 8192, R, C); const int Rb = Epi::PERM ? ((R & ~31) + perm32(R & 31)) : R;
;         voffA[i] = (unsigned)(R * lda + C) * 2u; voffB[i] = (unsigned)(Rb * ldb + C) * 2u; }
;     const size_t kstep = (size_t)(BK * 2);
;     const size_t hstepA = (size_t)HALF * lda * 2, hstepB = (size_t)HALF * ldb * 2;
;     const unsigned ldsw = (unsigned)wid * 1024u;
;     const int aoff = lds_byte(wr * 64 + fr, fq * 8), boff = lds_byte(wc * 32 + fr, fq * 8);
;     ...
;     const char* cA = S.aptr(cur); const char* cB = S.bptr(cur); int nt = S.ntiles(cur);
;     PG8_STAGE(PG8_SB(0, 0), cB, voffB); PG8_STAGE(PG8_SB(0, 1), cB + hstepB, voffB); PG8_STAGE(PG8_SA(0, 0), cA, voffA); PG8_STAGE(PG8_SA(0, 1), cA + hstepA, voffA);
;     if (wr == 1) PG8_BAR;
;     PG8_WAIT_V(2); PG8_BAR;
;     PG8_STAGE(PG8_SB(1, 0), cB + kstep, voffB); PG8_STAGE(PG8_SA(1, 0), cA + kstep, voffA); PG8_STAGE(PG8_SB(1, 1), cB + hstepB + kstep, voffB);
;     PG8_WAIT_V(6); PG8_BAR;
.LBB0_372:
	s_lshl_b32 s5, s43, 13
	s_and_b32 s5, s5, 0xe000
	s_sub_i32 s51, 0, s5
	s_add_i32 s51, s51, 0x20000
	s_add_u32 s6, s10, 0x23c28000
	s_mul_i32 s16, s71, 0x1800
	s_mov_b32 s17, s21
	s_addc_u32 s7, s11, 0
	s_lshl_b64 s[16:17], s[16:17], 2
	s_waitcnt lgkmcnt(0)
	s_add_u32 s12, s12, s16
	s_addc_u32 s13, s13, s17
	s_add_u32 s10, s10, 0x561b8000
	s_addc_u32 s11, s11, 0
	s_lshl_b32 s15, s15, 5
	s_and_b32 s18, s15, 0x60
	s_add_i32 m0, s31, 0x18000
	v_lshl_add_u64 v[6:7], v[6:7], 0, s[28:29]
	s_lshl_b32 s5, s14, 13
	s_lshl_b32 s15, s18, 7
	s_waitcnt vmcnt(2)
	s_barrier
	global_load_lds_dwordx4 v[6:7], off
	v_lshl_add_u64 v[4:5], v[4:5], 0, s[28:29]
	s_add_i32 m0, s31, 0x1a000
	s_add_i32 s52, s31, 0x8000
	s_add_i32 s53, s31, 0xa000
	global_load_lds_dwordx4 v[4:5], off
	v_lshl_add_u64 v[0:1], v[0:1], 0, s[28:29]
	s_mov_b32 m0, s52
	s_add_u32 s16, s36, 0x80080
	global_load_lds_dwordx4 v[0:1], off
	v_lshl_add_u64 v[0:1], v[2:3], 0, s[28:29]
	s_mov_b32 m0, s53
	s_addc_u32 s17, s37, 0
	global_load_lds_dwordx4 v[0:1], off
	s_add_i32 m0, s31, 0x1c000
	v_lshl_add_u64 v[0:1], s[16:17], 0, v[138:139]
	global_load_lds_dwordx4 v[0:1], off
	v_lshl_add_u64 v[0:1], s[16:17], 0, v[142:143]
	s_add_i32 m0, s31, 0x1e000
	s_cmpk_lt_u32 s1, 0x100
	global_load_lds_dwordx4 v[0:1], off
	v_lshrrev_b32_e32 v1, 1, v8
	v_and_b32_e32 v2, 24, v1
	v_and_b32_e32 v0, 15, v8
	v_lshlrev_b32_e32 v3, 1, v2
	v_lshl_or_b32 v145, s14, 6, v0
	v_lshl_or_b32 v0, v0, 6, v3
	v_lshlrev_b32_e32 v3, 2, v8
	v_and_b32_e32 v3, 32, v3
	v_bitop3_b32 v170, v0, s15, v3 bitop3:0xde
	s_cselect_b64 s[14:15], -1, 0
	s_lshl_b32 s54, s0, 3
	s_abs_i32 s55, s54
	v_bitop3_b32 v4, v0, s5, v3 bitop3:0xde
	v_cvt_f32_u32_e32 v0, s55
	v_and_b32_e32 v144, 8, v1
	v_and_b32_e32 v1, 1, v9
	s_bfe_i32 s58, s0, 0x1001c
	v_rcp_iflag_f32_e32 v0, v0
	s_sub_i32 s0, 0, s55
	s_waitcnt vmcnt(6)
	s_ashr_i32 s56, s44, 31
	v_mul_f32_e32 v0, 0x4f7ffffe, v0
	v_cvt_u32_f32_e32 v0, v0
	s_ashr_i32 s57, s43, 31
	v_or_b32_e32 v171, s18, v2
	s_mov_b32 s59, 0
	v_readfirstlane_b32 s1, v0
	v_lshlrev_b32_e32 v0, 15, v9
	v_and_b32_e32 v0, 0xffff0000, v0
	v_lshl_add_u32 v0, v10, 12, v0
	v_lshl_or_b32 v0, v1, 6, v0
	v_lshl_add_u32 v146, v11, 1, v0
	v_lshlrev_b32_e32 v0, 15, v12
	v_and_b32_e32 v0, 0xffff0000, v0
	s_mul_i32 s0, s0, s1
	v_lshl_add_u32 v0, v13, 12, v0
	v_and_b32_e32 v1, 1, v12
	s_mul_hi_u32 s0, s1, s0
	v_lshl_or_b32 v0, v1, 6, v0
	s_add_i32 s67, s1, s0
	v_mov_b32_e32 v147, v185
	v_lshl_add_u32 v148, v14, 1, v0
	v_mov_b32_e32 v149, v185
	v_add_u32_e32 v172, 0, v4
	s_barrier
	s_cmp_ge_u32 s90, 4
	s_cbranch_scc0 .Lprio_375_done
	s_setprio 1
.Lprio_375_done:
	s_branch .LBB0_375

; #define PG8_STAGE(bufoff, gbase, voff) do { _Pragma("unroll") for (int _i = 0; _i < 2; ++_i) \
;         __builtin_amdgcn_global_load_lds((const unsigned*)((const char*)(gbase) + (voff)[_i]), (LAS unsigned*)(lds + (bufoff) + ldsw + _i * 8192), 16, 0, 0); } while (0)
; #define PG8_LDA(dst, b, h) do { _Pragma("unroll") for (int m = 0; m < 4; ++m) _Pragma("unroll") for (int k = 0; k < 2; ++k) dst[m][k] = *(const LAS bf16x8*)(lds + PG8_SA(b, h) + aoff + m * 2048 + k * 1024); } while (0)
; #define PG8_LDB(dst, b, h) do { _Pragma("unroll") for (int n = 0; n < 2; ++n) _Pragma("unroll") for (int k = 0; k < 2; ++k) dst[n][k] = *(const LAS bf16x8*)(lds + PG8_SB(b, h) + boff + n * 2048 + k * 1024); } while (0)
; #define PG8_MMA(ai, bj, At, Bt) do { __builtin_amdgcn_s_setprio(1); _Pragma("unroll") for (int m = 0; m < 4; ++m) _Pragma("unroll") for (int n = 0; n < 2; ++n) _Pragma("unroll") for (int k = 0; k < 2; ++k) \
;         acc[ai][bj][m][n] = __builtin_amdgcn_mfma_f32_16x16x32_bf16(Bt[n][k], At[m][k], acc[ai][bj][m][n], 0, 0, 0); __builtin_amdgcn_s_setprio(0); } while (0)
; #define PG8_WAIT_V(n) asm volatile("s_waitcnt vmcnt(" #n ")" ::: "memory")
; #define PG8_WAIT_L(n) asm volatile("s_waitcnt lgkmcnt(" #n ")" ::: "memory")
; #define PG8_BAR __builtin_amdgcn_s_barrier()
; #define PG8_SCHED __builtin_amdgcn_sched_barrier(0)
; template <class Epi, class Sched>
; DI void gemm_phase(LAS unsigned char* lds, const int wv, const int lda, const int ldb, const Sched& S, const Epi& E) {
;     ...
;             const char* a1 = cA + (size_t)(t + 1) * kstep;
;             const char* a2 = last ? nA : cA + (size_t)(t + 2) * kstep; const char* b2 = last ? nB : cB + (size_t)(t + 2) * kstep;
;             const char* a3 = a2 + kstep; const char* b3 = b2 + kstep;
;             PG8_LDB(B0, 0, 0); PG8_LDB(B1, 0, 1); PG8_SCHED; PG8_LDA(At, 0, 0); PG8_STAGE(PG8_SA(1, 1), a1 + hstepA, voffA);
;             PG8_WAIT_V(8); PG8_WAIT_L(0); PG8_BAR; PG8_MMA(0, 0, At, B0); PG8_MMA(0, 1, At, B1); PG8_BAR; PG8_SCHED;
;             PG8_LDA(At, 0, 1); PG8_STAGE(PG8_SB(0, 0), b2, voffB); PG8_STAGE(PG8_SB(0, 1), b2 + hstepB, voffB); PG8_STAGE(PG8_SA(0, 0), a2, voffA);
;             PG8_WAIT_V(8); PG8_WAIT_L(0); PG8_BAR; PG8_MMA(1, 0, At, B0); PG8_MMA(1, 1, At, B1); PG8_BAR; PG8_SCHED;
.LBB0_378:
	s_add_u32 s33, s34, 0xfff80080
	s_addc_u32 s36, s35, -1
	s_add_i32 s61, 0, 0x10000
	s_cmp_eq_u32 s23, 28
	s_cselect_b32 s39, s0, s36
	s_cselect_b32 s38, s1, s33
	s_cselect_b32 s37, s5, s19
	s_cselect_b32 s36, s16, s17
	s_add_i32 s33, 0, 0x14000
	v_add_u32_e32 v154, s61, v170
	v_add_u32_e32 v173, s33, v170
	ds_read_b128 v[104:107], v154
	ds_read_b128 v[108:111], v154 offset:1024
	ds_read_b128 v[150:153], v154 offset:2048
	ds_read_b128 v[154:157], v154 offset:3072
	ds_read_b128 v[158:161], v173
	ds_read_b128 v[162:165], v173 offset:1024
	ds_read_b128 v[166:169], v173 offset:2048
	ds_read_b128 v[174:177], v173 offset:3072
	v_lshl_add_u64 v[182:183], s[34:35], 0, v[146:147]
	s_add_i32 m0, s31, 0xc000
	ds_read_b128 v[178:181], v172
	ds_read_b128 v[200:203], v172 offset:1024
	ds_read_b128 v[204:207], v172 offset:2048
	ds_read_b128 v[208:211], v172 offset:3072
	ds_read_b128 v[212:215], v172 offset:4096
	ds_read_b128 v[216:219], v172 offset:5120
	ds_read_b128 v[220:223], v172 offset:6144
	ds_read_b128 v[234:237], v172 offset:7168
	global_load_lds_dwordx4 v[182:183], off
	v_lshl_add_u64 v[182:183], s[34:35], 0, v[148:149]
	s_add_i32 m0, s31, 0xe000
	s_nop 0
	global_load_lds_dwordx4 v[182:183], off
	s_waitcnt vmcnt(8)
	s_waitcnt lgkmcnt(0)
	s_barrier
	s_waitcnt lgkmcnt(0)
	v_mfma_f32_16x16x32_bf16 v[132:135], v[104:107], v[178:181], v[132:135]
	v_mfma_f32_16x16x32_bf16 v[128:131], v[150:153], v[178:181], v[128:131]
	v_mfma_f32_16x16x32_bf16 v[124:127], v[104:107], v[204:207], v[124:127]
	v_mfma_f32_16x16x32_bf16 v[120:123], v[150:153], v[204:207], v[120:123]
	v_mfma_f32_16x16x32_bf16 v[116:119], v[104:107], v[212:215], v[116:119]
	v_mfma_f32_16x16x32_bf16 v[112:115], v[150:153], v[212:215], v[112:115]
	v_mfma_f32_16x16x32_bf16 v[100:103], v[104:107], v[220:223], v[100:103]
	v_mfma_f32_16x16x32_bf16 v[96:99], v[150:153], v[220:223], v[96:99]
	v_mfma_f32_16x16x32_bf16 v[132:135], v[108:111], v[200:203], v[132:135]
	v_mfma_f32_16x16x32_bf16 v[128:131], v[154:157], v[200:203], v[128:131]
	v_mfma_f32_16x16x32_bf16 v[124:127], v[108:111], v[208:211], v[124:127]
	v_mfma_f32_16x16x32_bf16 v[120:123], v[154:157], v[208:211], v[120:123]
	v_mfma_f32_16x16x32_bf16 v[116:119], v[108:111], v[216:219], v[116:119]
	v_mfma_f32_16x16x32_bf16 v[112:115], v[154:157], v[216:219], v[112:115]
	v_mfma_f32_16x16x32_bf16 v[100:103], v[108:111], v[234:237], v[100:103]
	v_mfma_f32_16x16x32_bf16 v[96:99], v[154:157], v[234:237], v[96:99]
	v_mfma_f32_16x16x32_bf16 v[60:63], v[158:161], v[178:181], v[60:63]
	v_mfma_f32_16x16x32_bf16 v[56:59], v[166:169], v[178:181], v[56:59]
	v_mfma_f32_16x16x32_bf16 v[52:55], v[158:161], v[204:207], v[52:55]
	v_mfma_f32_16x16x32_bf16 v[48:51], v[166:169], v[204:207], v[48:51]
	v_mfma_f32_16x16x32_bf16 v[44:47], v[158:161], v[212:215], v[44:47]
	v_mfma_f32_16x16x32_bf16 v[40:43], v[166:169], v[212:215], v[40:43]
	v_mfma_f32_16x16x32_bf16 v[36:39], v[158:161], v[220:223], v[36:39]
	v_mfma_f32_16x16x32_bf16 v[32:35], v[166:169], v[220:223], v[32:35]
	v_mfma_f32_16x16x32_bf16 v[60:63], v[162:165], v[200:203], v[60:63]
	v_mfma_f32_16x16x32_bf16 v[56:59], v[174:177], v[200:203], v[56:59]
	v_mfma_f32_16x16x32_bf16 v[52:55], v[162:165], v[208:211], v[52:55]
	v_mfma_f32_16x16x32_bf16 v[48:51], v[174:177], v[208:211], v[48:51]
	v_mfma_f32_16x16x32_bf16 v[44:47], v[162:165], v[216:219], v[44:47]
	v_mfma_f32_16x16x32_bf16 v[40:43], v[174:177], v[216:219], v[40:43]
	v_mfma_f32_16x16x32_bf16 v[36:39], v[162:165], v[234:237], v[36:39]
	v_mfma_f32_16x16x32_bf16 v[32:35], v[174:177], v[234:237], v[32:35]
	s_barrier
	s_add_i32 s61, s61, s47
	v_lshl_add_u64 v[182:183], s[36:37], 0, v[138:139]
	s_mov_b32 m0, s61
	ds_read_b128 v[178:181], v172 offset:16384
	ds_read_b128 v[200:203], v172 offset:17408
	ds_read_b128 v[204:207], v172 offset:18432
	ds_read_b128 v[208:211], v172 offset:19456
	ds_read_b128 v[212:215], v172 offset:20480
	ds_read_b128 v[216:219], v172 offset:21504
	ds_read_b128 v[220:223], v172 offset:22528
	ds_read_b128 v[234:237], v172 offset:23552
	global_load_lds_dwordx4 v[182:183], off
	s_add_i32 m0, s61, 0x2000
	s_add_u32 s62, s36, 0x80000
	v_lshl_add_u64 v[188:189], s[36:37], 0, v[142:143]
	s_addc_u32 s63, s37, 0
	s_add_i32 s33, s33, s47
	global_load_lds_dwordx4 v[188:189], off
	v_lshl_add_u64 v[190:191], s[62:63], 0, v[138:139]
	s_mov_b32 m0, s33
	v_lshl_add_u64 v[196:197], s[38:39], 0, v[140:141]
	global_load_lds_dwordx4 v[190:191], off
	v_lshl_add_u64 v[190:191], s[62:63], 0, v[142:143]
	s_add_i32 m0, s33, 0x2000
	s_nop 0
	global_load_lds_dwordx4 v[190:191], off
	v_lshl_add_u64 v[190:191], s[38:39], 0, v[136:137]
	s_mov_b32 m0, s31
	s_nop 0
	global_load_lds_dwordx4 v[190:191], off
	s_mov_b32 m0, s48
	s_nop 0
	global_load_lds_dwordx4 v[196:197], off
	s_waitcnt vmcnt(8)
	s_waitcnt lgkmcnt(0)
	s_barrier
; #define PG8_STAGE(bufoff, gbase, voff) do { _Pragma("unroll") for (int _i = 0; _i < 2; ++_i) \
;         __builtin_amdgcn_global_load_lds((const unsigned*)((const char*)(gbase) + (voff)[_i]), (LAS unsigned*)(lds + (bufoff) + ldsw + _i * 8192), 16, 0, 0); } while (0)
; #define PG8_LDA(dst, b, h) do { _Pragma("unroll") for (int m = 0; m < 4; ++m) _Pragma("unroll") for (int k = 0; k < 2; ++k) dst[m][k] = *(const LAS bf16x8*)(lds + PG8_SA(b, h) + aoff + m * 2048 + k * 1024); } while (0)
; #define PG8_LDB(dst, b, h) do { _Pragma("unroll") for (int n = 0; n < 2; ++n) _Pragma("unroll") for (int k = 0; k < 2; ++k) dst[n][k] = *(const LAS bf16x8*)(lds + PG8_SB(b, h) + boff + n * 2048 + k * 1024); } while (0)
; #define PG8_MMA(ai, bj, At, Bt) do { __builtin_amdgcn_s_setprio(1); _Pragma("unroll") for (int m = 0; m < 4; ++m) _Pragma("unroll") for (int n = 0; n < 2; ++n) _Pragma("unroll") for (int k = 0; k < 2; ++k) \
;         acc[ai][bj][m][n] = __builtin_amdgcn_mfma_f32_16x16x32_bf16(Bt[n][k], At[m][k], acc[ai][bj][m][n], 0, 0, 0); __builtin_amdgcn_s_setprio(0); } while (0)
; #define PG8_WAIT_V(n) asm volatile("s_waitcnt vmcnt(" #n ")" ::: "memory")
; #define PG8_WAIT_L(n) asm volatile("s_waitcnt lgkmcnt(" #n ")" ::: "memory")
; #define PG8_BAR __builtin_amdgcn_s_barrier()
; #define PG8_SCHED __builtin_amdgcn_sched_barrier(0)
; template <class Epi, class Sched>
; DI void gemm_phase(LAS unsigned char* lds, const int wv, const int lda, const int ldb, const Sched& S, const Epi& E) {
;     ...
;             PG8_WAIT_V(8); PG8_WAIT_L(0); PG8_BAR; PG8_MMA(1, 0, At, B0); PG8_MMA(1, 1, At, B1); PG8_BAR; PG8_SCHED;
;             PG8_LDB(B0, 1, 0); PG8_LDB(B1, 1, 1); PG8_SCHED; PG8_LDA(At, 1, 0); PG8_STAGE(PG8_SA(0, 1), a2 + hstepA, voffA);
;             PG8_WAIT_V(8); PG8_WAIT_L(0); PG8_BAR; PG8_MMA(0, 0, At, B0); PG8_MMA(0, 1, At, B1); PG8_BAR; PG8_SCHED;
	s_waitcnt lgkmcnt(0)
	v_mfma_f32_16x16x32_bf16 v[92:95], v[104:107], v[178:181], v[92:95]
	v_mfma_f32_16x16x32_bf16 v[88:91], v[150:153], v[178:181], v[88:91]
	v_mfma_f32_16x16x32_bf16 v[84:87], v[104:107], v[204:207], v[84:87]
	v_mfma_f32_16x16x32_bf16 v[80:83], v[150:153], v[204:207], v[80:83]
	v_mfma_f32_16x16x32_bf16 v[76:79], v[104:107], v[212:215], v[76:79]
	v_mfma_f32_16x16x32_bf16 v[72:75], v[150:153], v[212:215], v[72:75]
	v_mfma_f32_16x16x32_bf16 v[68:71], v[104:107], v[220:223], v[68:71]
	v_mfma_f32_16x16x32_bf16 v[64:67], v[150:153], v[220:223], v[64:67]
	v_mfma_f32_16x16x32_bf16 v[92:95], v[108:111], v[200:203], v[92:95]
	v_mfma_f32_16x16x32_bf16 v[88:91], v[154:157], v[200:203], v[88:91]
	v_mfma_f32_16x16x32_bf16 v[84:87], v[108:111], v[208:211], v[84:87]
	v_mfma_f32_16x16x32_bf16 v[80:83], v[154:157], v[208:211], v[80:83]
	v_mfma_f32_16x16x32_bf16 v[76:79], v[108:111], v[216:219], v[76:79]
	v_mfma_f32_16x16x32_bf16 v[72:75], v[154:157], v[216:219], v[72:75]
	v_mfma_f32_16x16x32_bf16 v[68:71], v[108:111], v[234:237], v[68:71]
	v_mfma_f32_16x16x32_bf16 v[64:67], v[154:157], v[234:237], v[64:67]
	v_mfma_f32_16x16x32_bf16 v[28:31], v[158:161], v[178:181], v[28:31]
	v_mfma_f32_16x16x32_bf16 v[24:27], v[166:169], v[178:181], v[24:27]
	v_mfma_f32_16x16x32_bf16 v[20:23], v[158:161], v[204:207], v[20:23]
	v_mfma_f32_16x16x32_bf16 v[16:19], v[166:169], v[204:207], v[16:19]
	v_mfma_f32_16x16x32_bf16 v[12:15], v[158:161], v[212:215], v[12:15]
	v_mfma_f32_16x16x32_bf16 v[8:11], v[166:169], v[212:215], v[8:11]
	v_mfma_f32_16x16x32_bf16 v[4:7], v[158:161], v[220:223], v[4:7]
	v_mfma_f32_16x16x32_bf16 v[0:3], v[166:169], v[220:223], v[0:3]
	v_mfma_f32_16x16x32_bf16 v[28:31], v[162:165], v[200:203], v[28:31]
	v_mfma_f32_16x16x32_bf16 v[24:27], v[174:177], v[200:203], v[24:27]
	v_mfma_f32_16x16x32_bf16 v[20:23], v[162:165], v[208:211], v[20:23]
	v_mfma_f32_16x16x32_bf16 v[16:19], v[174:177], v[208:211], v[16:19]
	v_mfma_f32_16x16x32_bf16 v[12:15], v[162:165], v[216:219], v[12:15]
	v_mfma_f32_16x16x32_bf16 v[8:11], v[174:177], v[216:219], v[8:11]
	v_mfma_f32_16x16x32_bf16 v[4:7], v[162:165], v[234:237], v[4:7]
	v_mfma_f32_16x16x32_bf16 v[0:3], v[174:177], v[234:237], v[0:3]
	s_barrier
	s_add_i32 s33, 0, 0x18000
	s_add_i32 s61, 0, 0x1c000
	v_add_u32_e32 v154, s33, v170
	v_add_u32_e32 v173, s61, v170
	ds_read_b128 v[104:107], v154
	ds_read_b128 v[108:111], v154 offset:1024
	ds_read_b128 v[150:153], v154 offset:2048
	ds_read_b128 v[154:157], v154 offset:3072
	ds_read_b128 v[158:161], v173
	ds_read_b128 v[162:165], v173 offset:1024
	ds_read_b128 v[166:169], v173 offset:2048
	ds_read_b128 v[174:177], v173 offset:3072
	s_add_u32 s38, s38, 0x80000
	s_addc_u32 s39, s39, 0
	s_mov_b32 m0, s49
	v_lshl_add_u64 v[198:199], s[38:39], 0, v[136:137]
	ds_read_b128 v[178:181], v172 offset:32768
	ds_read_b128 v[200:203], v172 offset:33792
	ds_read_b128 v[204:207], v172 offset:34816
	ds_read_b128 v[208:211], v172 offset:35840
	ds_read_b128 v[212:215], v172 offset:36864
	ds_read_b128 v[216:219], v172 offset:37888
	ds_read_b128 v[220:223], v172 offset:38912
	ds_read_b128 v[234:237], v172 offset:39936
	global_load_lds_dwordx4 v[198:199], off
	v_lshl_add_u64 v[198:199], s[38:39], 0, v[140:141]
	s_mov_b32 m0, s50
	s_nop 0
	global_load_lds_dwordx4 v[198:199], off
	s_waitcnt vmcnt(8)
	s_waitcnt lgkmcnt(0)
	s_barrier
	s_waitcnt lgkmcnt(0)
	v_mfma_f32_16x16x32_bf16 v[132:135], v[104:107], v[178:181], v[132:135]
	v_mfma_f32_16x16x32_bf16 v[128:131], v[150:153], v[178:181], v[128:131]
	v_mfma_f32_16x16x32_bf16 v[124:127], v[104:107], v[204:207], v[124:127]
	v_mfma_f32_16x16x32_bf16 v[120:123], v[150:153], v[204:207], v[120:123]
	v_mfma_f32_16x16x32_bf16 v[116:119], v[104:107], v[212:215], v[116:119]
	v_mfma_f32_16x16x32_bf16 v[112:115], v[150:153], v[212:215], v[112:115]
	v_mfma_f32_16x16x32_bf16 v[100:103], v[104:107], v[220:223], v[100:103]
	v_mfma_f32_16x16x32_bf16 v[96:99], v[150:153], v[220:223], v[96:99]
	v_mfma_f32_16x16x32_bf16 v[132:135], v[108:111], v[200:203], v[132:135]
	v_mfma_f32_16x16x32_bf16 v[128:131], v[154:157], v[200:203], v[128:131]
	v_mfma_f32_16x16x32_bf16 v[124:127], v[108:111], v[208:211], v[124:127]
	v_mfma_f32_16x16x32_bf16 v[120:123], v[154:157], v[208:211], v[120:123]
	v_mfma_f32_16x16x32_bf16 v[116:119], v[108:111], v[216:219], v[116:119]
	v_mfma_f32_16x16x32_bf16 v[112:115], v[154:157], v[216:219], v[112:115]
	v_mfma_f32_16x16x32_bf16 v[100:103], v[108:111], v[234:237], v[100:103]
	v_mfma_f32_16x16x32_bf16 v[96:99], v[154:157], v[234:237], v[96:99]
	v_mfma_f32_16x16x32_bf16 v[60:63], v[158:161], v[178:181], v[60:63]
	v_mfma_f32_16x16x32_bf16 v[56:59], v[166:169], v[178:181], v[56:59]
	v_mfma_f32_16x16x32_bf16 v[52:55], v[158:161], v[204:207], v[52:55]
	v_mfma_f32_16x16x32_bf16 v[48:51], v[166:169], v[204:207], v[48:51]
	v_mfma_f32_16x16x32_bf16 v[44:47], v[158:161], v[212:215], v[44:47]
	v_mfma_f32_16x16x32_bf16 v[40:43], v[166:169], v[212:215], v[40:43]
	v_mfma_f32_16x16x32_bf16 v[36:39], v[158:161], v[220:223], v[36:39]
	v_mfma_f32_16x16x32_bf16 v[32:35], v[166:169], v[220:223], v[32:35]
	v_mfma_f32_16x16x32_bf16 v[60:63], v[162:165], v[200:203], v[60:63]
	v_mfma_f32_16x16x32_bf16 v[56:59], v[174:177], v[200:203], v[56:59]
	v_mfma_f32_16x16x32_bf16 v[52:55], v[162:165], v[208:211], v[52:55]
	v_mfma_f32_16x16x32_bf16 v[48:51], v[174:177], v[208:211], v[48:51]
	v_mfma_f32_16x16x32_bf16 v[44:47], v[162:165], v[216:219], v[44:47]
	v_mfma_f32_16x16x32_bf16 v[40:43], v[174:177], v[216:219], v[40:43]
	v_mfma_f32_16x16x32_bf16 v[36:39], v[162:165], v[234:237], v[36:39]
	v_mfma_f32_16x16x32_bf16 v[32:35], v[174:177], v[234:237], v[32:35]
	s_barrier
; #define PG8_STAGE(bufoff, gbase, voff) do { _Pragma("unroll") for (int _i = 0; _i < 2; ++_i) \
;         __builtin_amdgcn_global_load_lds((const unsigned*)((const char*)(gbase) + (voff)[_i]), (LAS unsigned*)(lds + (bufoff) + ldsw + _i * 8192), 16, 0, 0); } while (0)
; #define PG8_LDA(dst, b, h) do { _Pragma("unroll") for (int m = 0; m < 4; ++m) _Pragma("unroll") for (int k = 0; k < 2; ++k) dst[m][k] = *(const LAS bf16x8*)(lds + PG8_SA(b, h) + aoff + m * 2048 + k * 1024); } while (0)
; #define PG8_MMA(ai, bj, At, Bt) do { __builtin_amdgcn_s_setprio(1); _Pragma("unroll") for (int m = 0; m < 4; ++m) _Pragma("unroll") for (int n = 0; n < 2; ++n) _Pragma("unroll") for (int k = 0; k < 2; ++k) \
;         acc[ai][bj][m][n] = __builtin_amdgcn_mfma_f32_16x16x32_bf16(Bt[n][k], At[m][k], acc[ai][bj][m][n], 0, 0, 0); __builtin_amdgcn_s_setprio(0); } while (0)
; #define PG8_WAIT_V(n) asm volatile("s_waitcnt vmcnt(" #n ")" ::: "memory")
; #define PG8_WAIT_L(n) asm volatile("s_waitcnt lgkmcnt(" #n ")" ::: "memory")
; #define PG8_BAR __builtin_amdgcn_s_barrier()
; #define PG8_SCHED __builtin_amdgcn_sched_barrier(0)
; template <class Epi, class Sched>
; DI void gemm_phase(LAS unsigned char* lds, const int wv, const int lda, const int ldb, const Sched& S, const Epi& E) {
;     ...
;             PG8_LDA(At, 1, 1); PG8_STAGE(PG8_SB(1, 0), b3, voffB); PG8_STAGE(PG8_SB(1, 1), b3 + hstepB, voffB); PG8_STAGE(PG8_SA(1, 0), a3, voffA);
;             PG8_WAIT_V(8); PG8_WAIT_L(0); PG8_BAR; PG8_MMA(1, 0, At, B0); PG8_MMA(1, 1, At, B1); PG8_BAR; PG8_SCHED;
;         }
;         if (wr == 0) PG8_BAR;
	s_add_i32 s33, s33, s47
	v_lshl_add_u64 v[182:183], v[182:183], 0, s[28:29]
	s_mov_b32 m0, s33
	ds_read_b128 v[178:181], v172 offset:49152
	ds_read_b128 v[200:203], v172 offset:50176
	ds_read_b128 v[204:207], v172 offset:51200
	ds_read_b128 v[208:211], v172 offset:52224
	ds_read_b128 v[212:215], v172 offset:53248
	ds_read_b128 v[216:219], v172 offset:54272
	ds_read_b128 v[220:223], v172 offset:55296
	ds_read_b128 v[234:237], v172 offset:56320
	global_load_lds_dwordx4 v[182:183], off
	s_add_i32 m0, s33, 0x2000
	s_add_u32 s36, s36, 0x80080
	v_lshl_add_u64 v[182:183], v[188:189], 0, s[28:29]
	s_addc_u32 s37, s37, 0
	s_add_i32 s33, s61, s47
	global_load_lds_dwordx4 v[182:183], off
	v_lshl_add_u64 v[182:183], s[36:37], 0, v[138:139]
	s_mov_b32 m0, s33
	s_nop 0
	global_load_lds_dwordx4 v[182:183], off
	v_lshl_add_u64 v[182:183], s[36:37], 0, v[142:143]
	s_add_i32 m0, s33, 0x2000
	s_nop 0
	global_load_lds_dwordx4 v[182:183], off
	v_lshl_add_u64 v[182:183], v[190:191], 0, s[28:29]
	s_mov_b32 m0, s52
	s_nop 0
	global_load_lds_dwordx4 v[182:183], off
	v_lshl_add_u64 v[182:183], v[196:197], 0, s[28:29]
	s_mov_b32 m0, s53
	s_nop 0
	global_load_lds_dwordx4 v[182:183], off
	s_waitcnt vmcnt(8)
	s_waitcnt lgkmcnt(0)
	s_barrier
	s_waitcnt lgkmcnt(0)
	v_mfma_f32_16x16x32_bf16 v[92:95], v[104:107], v[178:181], v[92:95]
	v_mfma_f32_16x16x32_bf16 v[88:91], v[150:153], v[178:181], v[88:91]
	v_mfma_f32_16x16x32_bf16 v[84:87], v[104:107], v[204:207], v[84:87]
	v_mfma_f32_16x16x32_bf16 v[80:83], v[150:153], v[204:207], v[80:83]
	v_mfma_f32_16x16x32_bf16 v[76:79], v[104:107], v[212:215], v[76:79]
	v_mfma_f32_16x16x32_bf16 v[72:75], v[150:153], v[212:215], v[72:75]
	v_mfma_f32_16x16x32_bf16 v[68:71], v[104:107], v[220:223], v[68:71]
	v_mfma_f32_16x16x32_bf16 v[64:67], v[150:153], v[220:223], v[64:67]
	v_mfma_f32_16x16x32_bf16 v[92:95], v[108:111], v[200:203], v[92:95]
	v_mfma_f32_16x16x32_bf16 v[88:91], v[154:157], v[200:203], v[88:91]
	v_mfma_f32_16x16x32_bf16 v[84:87], v[108:111], v[208:211], v[84:87]
	v_mfma_f32_16x16x32_bf16 v[80:83], v[154:157], v[208:211], v[80:83]
	v_mfma_f32_16x16x32_bf16 v[76:79], v[108:111], v[216:219], v[76:79]
	v_mfma_f32_16x16x32_bf16 v[72:75], v[154:157], v[216:219], v[72:75]
	v_mfma_f32_16x16x32_bf16 v[68:71], v[108:111], v[234:237], v[68:71]
	v_mfma_f32_16x16x32_bf16 v[64:67], v[154:157], v[234:237], v[64:67]
	v_mfma_f32_16x16x32_bf16 v[28:31], v[158:161], v[178:181], v[28:31]
	v_mfma_f32_16x16x32_bf16 v[24:27], v[166:169], v[178:181], v[24:27]
	v_mfma_f32_16x16x32_bf16 v[20:23], v[158:161], v[204:207], v[20:23]
	v_mfma_f32_16x16x32_bf16 v[16:19], v[166:169], v[204:207], v[16:19]
	v_mfma_f32_16x16x32_bf16 v[12:15], v[158:161], v[212:215], v[12:15]
	v_mfma_f32_16x16x32_bf16 v[8:11], v[166:169], v[212:215], v[8:11]
	v_mfma_f32_16x16x32_bf16 v[4:7], v[158:161], v[220:223], v[4:7]
	v_mfma_f32_16x16x32_bf16 v[0:3], v[166:169], v[220:223], v[0:3]
	v_mfma_f32_16x16x32_bf16 v[28:31], v[162:165], v[200:203], v[28:31]
	v_mfma_f32_16x16x32_bf16 v[24:27], v[174:177], v[200:203], v[24:27]
	v_mfma_f32_16x16x32_bf16 v[20:23], v[162:165], v[208:211], v[20:23]
	v_mfma_f32_16x16x32_bf16 v[16:19], v[174:177], v[208:211], v[16:19]
	v_mfma_f32_16x16x32_bf16 v[12:15], v[162:165], v[216:219], v[12:15]
	v_mfma_f32_16x16x32_bf16 v[8:11], v[174:177], v[216:219], v[8:11]
	v_mfma_f32_16x16x32_bf16 v[4:7], v[162:165], v[234:237], v[4:7]
	v_mfma_f32_16x16x32_bf16 v[0:3], v[174:177], v[234:237], v[0:3]
	s_barrier
	s_add_i32 s23, s23, 2
	s_add_u32 s34, s34, 0x100
	s_addc_u32 s35, s35, 0
	s_add_u32 s17, s17, 0x100
	s_addc_u32 s19, s19, 0
	s_cmp_gt_u32 s23, 29
	s_cbranch_scc0 .LBB0_378
	s_and_b64 vcc, exec, s[14:15]
	s_cbranch_vccz .LBB0_381
	s_barrier

; #define SEAM(k) do { if (IN((k) + 1) && IN(k)) xcd_barrier(bar); } while (0)
; __global__ void __launch_bounds__(512, 2) trunk_fwd(Args args_unused) {
;     ...
;             gemm_phase<EpiInproj, SchedPlain>(F.lds, F.wave, XP, D, S, E);
;             SEAM(s0 + 1);
.LBB0_489:
	s_setprio 0
	s_cmp_eq_u32 s71, 0
	s_cbranch_scc1 .Lvres_done
	s_load_dwordx4 s[4:7], s[88:89], 0x130
	v_mbcnt_lo_u32_b32 v238, -1, 0
	v_mbcnt_hi_u32_b32 v238, -1, v238
	v_readlane_b32 s0, v252, 0
	s_nop 0
	s_mov_b32 m0, s0

;     DI void init(const bf16* A_, int lda, const bf16* B_, int ldb, int nM, int nN, int K, int G_, int c_) { T.init(nM, nN); G = G_; c = c_; nt = K / BK; A = (const char*)A_; B = (const char*)B_; ta = (size_t)BM * lda * 2; tb = (size_t)BM * ldb * 2; }
;     DI void init(const bf16* A_, int lda, const bf16* B_, int ldb, int nM, int nN, int G_, int c_) { T.init(nM, nN); G = G_; c = c_; A = (const char*)A_; B = (const char*)B_; ta = (size_t)BM * lda * 2; tb = (size_t)BM * ldb * 2; }
;     DI const char* aptr(const Unit& u) const { return A + (size_t)u.pm * ta + (size_t)kofs(u.seg) * 2; }
;     DI const char* bptr(const Unit& u) const { return B + (size_t)u.pn * tb + (size_t)kofs(u.seg) * 2; }
; #define PG8_STAGE(bufoff, gbase, voff) do { _Pragma("unroll") for (int _i = 0; _i < 2; ++_i) \
;         __builtin_amdgcn_global_load_lds((const unsigned*)((const char*)(gbase) + (voff)[_i]), (LAS unsigned*)(lds + (bufoff) + ldsw + _i * 8192), 16, 0, 0); } while (0)
; #define PG8_WAIT_V(n) asm volatile("s_waitcnt vmcnt(" #n ")" ::: "memory")
; #define PG8_BAR __builtin_amdgcn_s_barrier()
; #define FRAME() const CAS Args* ap; const Frame F = make_frame(lds, ap, wv); const CAS Args& A = *ap; (void)A
; template <class Epi, class Sched>
; DI void gemm_phase(LAS unsigned char* lds, const int wv, const int lda, const int ldb, const Sched& S, const Epi& E) {
;     ...
;     const char* cA = S.aptr(cur); const char* cB = S.bptr(cur); int nt = S.ntiles(cur);
;     PG8_STAGE(PG8_SB(0, 0), cB, voffB); PG8_STAGE(PG8_SB(0, 1), cB + hstepB, voffB); PG8_STAGE(PG8_SA(0, 0), cA, voffA); PG8_STAGE(PG8_SA(0, 1), cA + hstepA, voffA);
;     if (wr == 1) PG8_BAR;
;     PG8_WAIT_V(2); PG8_BAR;
;     PG8_STAGE(PG8_SB(1, 0), cB + kstep, voffB); PG8_STAGE(PG8_SA(1, 0), cA + kstep, voffA); PG8_STAGE(PG8_SB(1, 1), cB + hstepB + kstep, voffB);
;     PG8_WAIT_V(6); PG8_BAR;
; __global__ void __launch_bounds__(512, 2) trunk_fwd(Args args_unused) {
;     ...
;         if (PHEN(6) && IN(s0 + 6)) { FRAME();
;             const bf16* ypre = (const bf16*)(F.ws + WS_R1 + (size_t)M * RW * 4);
;             SchedPlain S; S.init(ypre, S5W, (const bf16*)lw(F, l, LW_GLU), S5W, M / BM, 3, S5W, F.G, F.bid);
;             EpiGlu E{ypre, (bf16*)(F.ws + WS_R3), A.in[13] + (size_t)l * S5W};
;             gemm_phase<EpiGlu, SchedPlain>(F.lds, F.wave, S5W, S5W, S, E);
.LBB0_1089:
	s_sext_i32_i8 s48, s10
	s_add_u32 s10, s6, 0x3a428000
	s_mul_i32 s20, s71, 0x300
	s_addc_u32 s11, s7, 0
	s_lshl_b64 s[6:7], s[20:21], 2
	s_add_u32 s12, s4, s6
	v_lshrrev_b32_e32 v18, 1, v14
	s_addc_u32 s13, s5, s7
	v_and_b32_e32 v18, 24, v18
	s_lshl_b32 s0, s0, 5
	v_and_b32_e32 v17, 15, v14
	v_lshlrev_b32_e32 v19, 1, v18
	v_lshlrev_b32_e32 v14, 2, v14
	s_and_b32 s4, s0, 0x60
	s_add_i32 m0, s38, 0x18000
	v_lshl_add_u64 v[6:7], v[6:7], 0, s[28:29]
	v_lshl_or_b32 v186, s1, 6, v17
	v_lshl_or_b32 v17, v17, 6, v19
	s_lshl_b32 s1, s1, 13
	v_and_b32_e32 v14, 32, v14
	s_lshl_b32 s0, s4, 7
	s_waitcnt vmcnt(2)
	s_barrier
	global_load_lds_dwordx4 v[6:7], off
	v_lshl_add_u64 v[4:5], v[4:5], 0, s[28:29]
	s_add_i32 m0, s38, 0x1a000
	s_add_i32 s20, s38, 0x8000
	s_add_i32 s42, s38, 0xa000
	v_bitop3_b32 v204, v17, s0, v14 bitop3:0xde
	global_load_lds_dwordx4 v[4:5], off
	v_lshl_add_u64 v[0:1], v[0:1], 0, s[28:29]
	s_mov_b32 m0, s20
	s_add_u32 s0, s24, 0x30080
	v_bitop3_b32 v19, v17, s1, v14 bitop3:0xde
	global_load_lds_dwordx4 v[0:1], off
	v_lshl_add_u64 v[0:1], v[2:3], 0, s[28:29]
	s_mov_b32 m0, s42
	s_addc_u32 s1, s25, 0
	global_load_lds_dwordx4 v[0:1], off
	s_add_i32 m0, s38, 0x1c000
	v_lshl_add_u64 v[0:1], s[0:1], 0, v[184:185]
	global_load_lds_dwordx4 v[0:1], off
	v_lshl_add_u64 v[0:1], s[0:1], 0, v[168:169]
	s_add_i32 m0, s38, 0x1e000
	s_movk_i32 s5, 0x300
	global_load_lds_dwordx4 v[0:1], off
	v_or_b32_e32 v205, s4, v18
	v_lshrrev_b32_e32 v1, 1, v13
	v_mul_lo_u32 v0, v12, s5
	s_movk_i32 s4, 0x3000
	v_mad_u64_u32 v[0:1], s[0:1], v1, s4, v[0:1]
	v_or_b32_e32 v0, v0, v15
	v_add_lshl_u32 v0, v0, v16, 1
	v_mov_b32_e32 v1, v185
	s_mov_b64 s[6:7], 0x30080
	v_lshl_add_u64 v[174:175], v[0:1], 0, s[6:7]
	v_lshrrev_b32_e32 v1, 1, v8
	v_mul_lo_u32 v0, v9, s5
	v_mad_u64_u32 v[0:1], s[0:1], v1, s4, v[0:1]
	s_waitcnt vmcnt(6)
	v_or_b32_e32 v0, v0, v10
	s_cmpk_lt_u32 s14, 0x100
	v_add_lshl_u32 v0, v0, v11, 1
	v_mov_b32_e32 v1, v185
	s_cselect_b64 s[14:15], -1, 0
	s_ashr_i32 s43, s33, 31
	v_lshl_add_u64 v[176:177], v[0:1], 0, s[6:7]
	s_mov_b32 s44, 0
	v_add_u32_e32 v206, 0, v19
	s_barrier
	s_cmp_ge_u32 s90, 4
	s_cbranch_scc0 .Lprio_1092_done
	s_setprio 1

; #define PG8_STAGE(bufoff, gbase, voff) do { _Pragma("unroll") for (int _i = 0; _i < 2; ++_i) \
;         __builtin_amdgcn_global_load_lds((const unsigned*)((const char*)(gbase) + (voff)[_i]), (LAS unsigned*)(lds + (bufoff) + ldsw + _i * 8192), 16, 0, 0); } while (0)
; #define PG8_LDA(dst, b, h) do { _Pragma("unroll") for (int m = 0; m < 4; ++m) _Pragma("unroll") for (int k = 0; k < 2; ++k) dst[m][k] = *(const LAS bf16x8*)(lds + PG8_SA(b, h) + aoff + m * 2048 + k * 1024); } while (0)
; #define PG8_LDB(dst, b, h) do { _Pragma("unroll") for (int n = 0; n < 2; ++n) _Pragma("unroll") for (int k = 0; k < 2; ++k) dst[n][k] = *(const LAS bf16x8*)(lds + PG8_SB(b, h) + boff + n * 2048 + k * 1024); } while (0)
; #define PG8_MMA(ai, bj, At, Bt) do { __builtin_amdgcn_s_setprio(1); _Pragma("unroll") for (int m = 0; m < 4; ++m) _Pragma("unroll") for (int n = 0; n < 2; ++n) _Pragma("unroll") for (int k = 0; k < 2; ++k) \
;         acc[ai][bj][m][n] = __builtin_amdgcn_mfma_f32_16x16x32_bf16(Bt[n][k], At[m][k], acc[ai][bj][m][n], 0, 0, 0); __builtin_amdgcn_s_setprio(0); } while (0)
; #define PG8_WAIT_V(n) asm volatile("s_waitcnt vmcnt(" #n ")" ::: "memory")
; #define PG8_WAIT_L(n) asm volatile("s_waitcnt lgkmcnt(" #n ")" ::: "memory")
; #define PG8_BAR __builtin_amdgcn_s_barrier()
; #define PG8_SCHED __builtin_amdgcn_sched_barrier(0)
; template <class Epi, class Sched>
; DI void gemm_phase(LAS unsigned char* lds, const int wv, const int lda, const int ldb, const Sched& S, const Epi& E) {
;     ...
;             const char* a1 = cA + (size_t)(t + 1) * kstep;
;             const char* a2 = last ? nA : cA + (size_t)(t + 2) * kstep; const char* b2 = last ? nB : cB + (size_t)(t + 2) * kstep;
;             const char* a3 = a2 + kstep; const char* b3 = b2 + kstep;
;             PG8_LDB(B0, 0, 0); PG8_LDB(B1, 0, 1); PG8_SCHED; PG8_LDA(At, 0, 0); PG8_STAGE(PG8_SA(1, 1), a1 + hstepA, voffA);
;             PG8_WAIT_V(8); PG8_WAIT_L(0); PG8_BAR; PG8_MMA(0, 0, At, B0); PG8_MMA(0, 1, At, B1); PG8_BAR; PG8_SCHED;
;             PG8_LDA(At, 0, 1); PG8_STAGE(PG8_SB(0, 0), b2, voffB); PG8_STAGE(PG8_SB(0, 1), b2 + hstepB, voffB); PG8_STAGE(PG8_SA(0, 0), a2, voffA);
;             PG8_WAIT_V(8); PG8_WAIT_L(0); PG8_BAR; PG8_MMA(1, 0, At, B0); PG8_MMA(1, 1, At, B1); PG8_BAR; PG8_SCHED;
.LBB0_1099:
	s_add_u32 s24, s22, 0x100
	s_addc_u32 s25, s23, 0
	s_add_i32 s50, 0, 0x10000
	s_cmp_eq_u32 s49, 8
	s_cselect_b32 s31, s7, s25
	s_cselect_b32 s30, s6, s24
	s_cselect_b32 s27, s19, s1
	s_cselect_b32 s26, s18, s0
	s_add_i32 s51, 0, 0x14000
	v_add_u32_e32 v108, s50, v204
	v_add_u32_e32 v156, s51, v204
	ds_read_b128 v[64:67], v108
	ds_read_b128 v[68:71], v108 offset:1024
	ds_read_b128 v[104:107], v108 offset:2048
	ds_read_b128 v[108:111], v108 offset:3072
	ds_read_b128 v[144:147], v156
	ds_read_b128 v[148:151], v156 offset:1024
	ds_read_b128 v[152:155], v156 offset:2048
	ds_read_b128 v[156:159], v156 offset:3072
	v_lshl_add_u64 v[182:183], s[22:23], 0, v[174:175]
	s_add_i32 m0, s38, 0xc000
	ds_read_b128 v[160:163], v206
	ds_read_b128 v[164:167], v206 offset:1024
	ds_read_b128 v[178:181], v206 offset:2048
	ds_read_b128 v[188:191], v206 offset:3072
	ds_read_b128 v[196:199], v206 offset:4096
	ds_read_b128 v[200:203], v206 offset:5120
	ds_read_b128 v[208:211], v206 offset:6144
	ds_read_b128 v[212:215], v206 offset:7168
	global_load_lds_dwordx4 v[182:183], off
	v_lshl_add_u64 v[182:183], s[22:23], 0, v[176:177]
	s_add_i32 m0, s38, 0xe000
	s_nop 0
	global_load_lds_dwordx4 v[182:183], off
	s_waitcnt vmcnt(8)
	s_waitcnt lgkmcnt(0)
	s_barrier
	s_waitcnt lgkmcnt(0)
	v_mfma_f32_16x16x32_bf16 v[140:143], v[64:67], v[160:163], v[140:143]
	v_mfma_f32_16x16x32_bf16 v[136:139], v[104:107], v[160:163], v[136:139]
	v_mfma_f32_16x16x32_bf16 v[132:135], v[64:67], v[178:181], v[132:135]
	v_mfma_f32_16x16x32_bf16 v[128:131], v[104:107], v[178:181], v[128:131]
	v_mfma_f32_16x16x32_bf16 v[124:127], v[64:67], v[196:199], v[124:127]
	v_mfma_f32_16x16x32_bf16 v[120:123], v[104:107], v[196:199], v[120:123]
	v_mfma_f32_16x16x32_bf16 v[116:119], v[64:67], v[208:211], v[116:119]
	v_mfma_f32_16x16x32_bf16 v[112:115], v[104:107], v[208:211], v[112:115]
	v_mfma_f32_16x16x32_bf16 v[140:143], v[68:71], v[164:167], v[140:143]
	v_mfma_f32_16x16x32_bf16 v[136:139], v[108:111], v[164:167], v[136:139]
	v_mfma_f32_16x16x32_bf16 v[132:135], v[68:71], v[188:191], v[132:135]
	v_mfma_f32_16x16x32_bf16 v[128:131], v[108:111], v[188:191], v[128:131]
	v_mfma_f32_16x16x32_bf16 v[124:127], v[68:71], v[200:203], v[124:127]
	v_mfma_f32_16x16x32_bf16 v[120:123], v[108:111], v[200:203], v[120:123]
	v_mfma_f32_16x16x32_bf16 v[116:119], v[68:71], v[212:215], v[116:119]
	v_mfma_f32_16x16x32_bf16 v[112:115], v[108:111], v[212:215], v[112:115]
	v_mfma_f32_16x16x32_bf16 v[100:103], v[144:147], v[160:163], v[100:103]
	v_mfma_f32_16x16x32_bf16 v[96:99], v[152:155], v[160:163], v[96:99]
	v_mfma_f32_16x16x32_bf16 v[92:95], v[144:147], v[178:181], v[92:95]
	v_mfma_f32_16x16x32_bf16 v[88:91], v[152:155], v[178:181], v[88:91]
	v_mfma_f32_16x16x32_bf16 v[84:87], v[144:147], v[196:199], v[84:87]
	v_mfma_f32_16x16x32_bf16 v[80:83], v[152:155], v[196:199], v[80:83]
	v_mfma_f32_16x16x32_bf16 v[76:79], v[144:147], v[208:211], v[76:79]
	v_mfma_f32_16x16x32_bf16 v[72:75], v[152:155], v[208:211], v[72:75]
	v_mfma_f32_16x16x32_bf16 v[100:103], v[148:151], v[164:167], v[100:103]
	v_mfma_f32_16x16x32_bf16 v[96:99], v[156:159], v[164:167], v[96:99]
	v_mfma_f32_16x16x32_bf16 v[92:95], v[148:151], v[188:191], v[92:95]
	v_mfma_f32_16x16x32_bf16 v[88:91], v[156:159], v[188:191], v[88:91]
	v_mfma_f32_16x16x32_bf16 v[84:87], v[148:151], v[200:203], v[84:87]
	v_mfma_f32_16x16x32_bf16 v[80:83], v[156:159], v[200:203], v[80:83]
	v_mfma_f32_16x16x32_bf16 v[76:79], v[148:151], v[212:215], v[76:79]
	v_mfma_f32_16x16x32_bf16 v[72:75], v[156:159], v[212:215], v[72:75]
	s_barrier
	s_add_i32 s22, s50, s36
	v_lshl_add_u64 v[182:183], s[26:27], 0, v[184:185]
	s_mov_b32 m0, s22
	ds_read_b128 v[160:163], v206 offset:16384
	ds_read_b128 v[164:167], v206 offset:17408
	ds_read_b128 v[178:181], v206 offset:18432
	ds_read_b128 v[188:191], v206 offset:19456
	ds_read_b128 v[196:199], v206 offset:20480
	ds_read_b128 v[200:203], v206 offset:21504
	ds_read_b128 v[208:211], v206 offset:22528
	ds_read_b128 v[212:215], v206 offset:23552
	global_load_lds_dwordx4 v[182:183], off
	s_add_i32 m0, s22, 0x2000
	s_add_u32 s22, s26, 0x30000
	v_lshl_add_u64 v[216:217], s[26:27], 0, v[168:169]
	s_addc_u32 s23, s27, 0
	s_add_i32 s50, s51, s36
	global_load_lds_dwordx4 v[216:217], off
	v_lshl_add_u64 v[218:219], s[22:23], 0, v[184:185]
	s_mov_b32 m0, s50
	v_lshl_add_u64 v[220:221], s[30:31], 0, v[170:171]
	global_load_lds_dwordx4 v[218:219], off
	v_lshl_add_u64 v[218:219], s[22:23], 0, v[168:169]
	s_add_i32 m0, s50, 0x2000
	s_nop 0
	global_load_lds_dwordx4 v[218:219], off
	v_lshl_add_u64 v[218:219], s[30:31], 0, v[172:173]
	s_mov_b32 m0, s38
	s_nop 0
	global_load_lds_dwordx4 v[218:219], off
	s_mov_b32 m0, s39
	s_nop 0
	global_load_lds_dwordx4 v[220:221], off
	s_waitcnt vmcnt(8)
	s_waitcnt lgkmcnt(0)
	s_barrier
; #define PG8_STAGE(bufoff, gbase, voff) do { _Pragma("unroll") for (int _i = 0; _i < 2; ++_i) \
;         __builtin_amdgcn_global_load_lds((const unsigned*)((const char*)(gbase) + (voff)[_i]), (LAS unsigned*)(lds + (bufoff) + ldsw + _i * 8192), 16, 0, 0); } while (0)
; #define PG8_LDA(dst, b, h) do { _Pragma("unroll") for (int m = 0; m < 4; ++m) _Pragma("unroll") for (int k = 0; k < 2; ++k) dst[m][k] = *(const LAS bf16x8*)(lds + PG8_SA(b, h) + aoff + m * 2048 + k * 1024); } while (0)
; #define PG8_LDB(dst, b, h) do { _Pragma("unroll") for (int n = 0; n < 2; ++n) _Pragma("unroll") for (int k = 0; k < 2; ++k) dst[n][k] = *(const LAS bf16x8*)(lds + PG8_SB(b, h) + boff + n * 2048 + k * 1024); } while (0)
; #define PG8_MMA(ai, bj, At, Bt) do { __builtin_amdgcn_s_setprio(1); _Pragma("unroll") for (int m = 0; m < 4; ++m) _Pragma("unroll") for (int n = 0; n < 2; ++n) _Pragma("unroll") for (int k = 0; k < 2; ++k) \
;         acc[ai][bj][m][n] = __builtin_amdgcn_mfma_f32_16x16x32_bf16(Bt[n][k], At[m][k], acc[ai][bj][m][n], 0, 0, 0); __builtin_amdgcn_s_setprio(0); } while (0)
; #define PG8_WAIT_V(n) asm volatile("s_waitcnt vmcnt(" #n ")" ::: "memory")
; #define PG8_WAIT_L(n) asm volatile("s_waitcnt lgkmcnt(" #n ")" ::: "memory")
; #define PG8_BAR __builtin_amdgcn_s_barrier()
; #define PG8_SCHED __builtin_amdgcn_sched_barrier(0)
; template <class Epi, class Sched>
; DI void gemm_phase(LAS unsigned char* lds, const int wv, const int lda, const int ldb, const Sched& S, const Epi& E) {
;     ...
;             PG8_WAIT_V(8); PG8_WAIT_L(0); PG8_BAR; PG8_MMA(1, 0, At, B0); PG8_MMA(1, 1, At, B1); PG8_BAR; PG8_SCHED;
;             PG8_LDB(B0, 1, 0); PG8_LDB(B1, 1, 1); PG8_SCHED; PG8_LDA(At, 1, 0); PG8_STAGE(PG8_SA(0, 1), a2 + hstepA, voffA);
;             PG8_WAIT_V(8); PG8_WAIT_L(0); PG8_BAR; PG8_MMA(0, 0, At, B0); PG8_MMA(0, 1, At, B1); PG8_BAR; PG8_SCHED;
	s_waitcnt lgkmcnt(0)
	v_mfma_f32_16x16x32_bf16 v[60:63], v[64:67], v[160:163], v[60:63]
	v_mfma_f32_16x16x32_bf16 v[56:59], v[104:107], v[160:163], v[56:59]
	v_mfma_f32_16x16x32_bf16 v[52:55], v[64:67], v[178:181], v[52:55]
	v_mfma_f32_16x16x32_bf16 v[48:51], v[104:107], v[178:181], v[48:51]
	v_mfma_f32_16x16x32_bf16 v[44:47], v[64:67], v[196:199], v[44:47]
	v_mfma_f32_16x16x32_bf16 v[40:43], v[104:107], v[196:199], v[40:43]
	v_mfma_f32_16x16x32_bf16 v[36:39], v[64:67], v[208:211], v[36:39]
	v_mfma_f32_16x16x32_bf16 v[32:35], v[104:107], v[208:211], v[32:35]
	v_mfma_f32_16x16x32_bf16 v[60:63], v[68:71], v[164:167], v[60:63]
	v_mfma_f32_16x16x32_bf16 v[56:59], v[108:111], v[164:167], v[56:59]
	v_mfma_f32_16x16x32_bf16 v[52:55], v[68:71], v[188:191], v[52:55]
	v_mfma_f32_16x16x32_bf16 v[48:51], v[108:111], v[188:191], v[48:51]
	v_mfma_f32_16x16x32_bf16 v[44:47], v[68:71], v[200:203], v[44:47]
	v_mfma_f32_16x16x32_bf16 v[40:43], v[108:111], v[200:203], v[40:43]
	v_mfma_f32_16x16x32_bf16 v[36:39], v[68:71], v[212:215], v[36:39]
	v_mfma_f32_16x16x32_bf16 v[32:35], v[108:111], v[212:215], v[32:35]
	v_mfma_f32_16x16x32_bf16 v[28:31], v[144:147], v[160:163], v[28:31]
	v_mfma_f32_16x16x32_bf16 v[24:27], v[152:155], v[160:163], v[24:27]
	v_mfma_f32_16x16x32_bf16 v[20:23], v[144:147], v[178:181], v[20:23]
	v_mfma_f32_16x16x32_bf16 v[16:19], v[152:155], v[178:181], v[16:19]
	v_mfma_f32_16x16x32_bf16 v[12:15], v[144:147], v[196:199], v[12:15]
	v_mfma_f32_16x16x32_bf16 v[8:11], v[152:155], v[196:199], v[8:11]
	v_mfma_f32_16x16x32_bf16 v[4:7], v[144:147], v[208:211], v[4:7]
	v_mfma_f32_16x16x32_bf16 v[0:3], v[152:155], v[208:211], v[0:3]
	v_mfma_f32_16x16x32_bf16 v[28:31], v[148:151], v[164:167], v[28:31]
	v_mfma_f32_16x16x32_bf16 v[24:27], v[156:159], v[164:167], v[24:27]
	v_mfma_f32_16x16x32_bf16 v[20:23], v[148:151], v[188:191], v[20:23]
	v_mfma_f32_16x16x32_bf16 v[16:19], v[156:159], v[188:191], v[16:19]
	v_mfma_f32_16x16x32_bf16 v[12:15], v[148:151], v[200:203], v[12:15]
	v_mfma_f32_16x16x32_bf16 v[8:11], v[156:159], v[200:203], v[8:11]
	v_mfma_f32_16x16x32_bf16 v[4:7], v[148:151], v[212:215], v[4:7]
	v_mfma_f32_16x16x32_bf16 v[0:3], v[156:159], v[212:215], v[0:3]
	s_barrier
	s_add_i32 s50, 0, 0x18000
	s_add_i32 s51, 0, 0x1c000
	v_add_u32_e32 v108, s50, v204
	v_add_u32_e32 v156, s51, v204
	ds_read_b128 v[64:67], v108
	ds_read_b128 v[68:71], v108 offset:1024
	ds_read_b128 v[104:107], v108 offset:2048
	ds_read_b128 v[108:111], v108 offset:3072
	ds_read_b128 v[144:147], v156
	ds_read_b128 v[148:151], v156 offset:1024
	ds_read_b128 v[152:155], v156 offset:2048
	ds_read_b128 v[156:159], v156 offset:3072
	s_add_u32 s22, s30, 0x30000
	s_addc_u32 s23, s31, 0
	s_mov_b32 m0, s40
	v_lshl_add_u64 v[222:223], s[22:23], 0, v[172:173]
	ds_read_b128 v[160:163], v206 offset:32768
	ds_read_b128 v[164:167], v206 offset:33792
	ds_read_b128 v[178:181], v206 offset:34816
	ds_read_b128 v[188:191], v206 offset:35840
	ds_read_b128 v[196:199], v206 offset:36864
	ds_read_b128 v[200:203], v206 offset:37888
	ds_read_b128 v[208:211], v206 offset:38912
	ds_read_b128 v[212:215], v206 offset:39936
	global_load_lds_dwordx4 v[222:223], off
	v_lshl_add_u64 v[222:223], s[22:23], 0, v[170:171]
	s_mov_b32 m0, s41
	s_nop 0
	global_load_lds_dwordx4 v[222:223], off
	s_waitcnt vmcnt(8)
	s_waitcnt lgkmcnt(0)
	s_barrier
	s_waitcnt lgkmcnt(0)
	v_mfma_f32_16x16x32_bf16 v[140:143], v[64:67], v[160:163], v[140:143]
	v_mfma_f32_16x16x32_bf16 v[136:139], v[104:107], v[160:163], v[136:139]
	v_mfma_f32_16x16x32_bf16 v[132:135], v[64:67], v[178:181], v[132:135]
	v_mfma_f32_16x16x32_bf16 v[128:131], v[104:107], v[178:181], v[128:131]
	v_mfma_f32_16x16x32_bf16 v[124:127], v[64:67], v[196:199], v[124:127]
	v_mfma_f32_16x16x32_bf16 v[120:123], v[104:107], v[196:199], v[120:123]
	v_mfma_f32_16x16x32_bf16 v[116:119], v[64:67], v[208:211], v[116:119]
	v_mfma_f32_16x16x32_bf16 v[112:115], v[104:107], v[208:211], v[112:115]
	v_mfma_f32_16x16x32_bf16 v[140:143], v[68:71], v[164:167], v[140:143]
	v_mfma_f32_16x16x32_bf16 v[136:139], v[108:111], v[164:167], v[136:139]
	v_mfma_f32_16x16x32_bf16 v[132:135], v[68:71], v[188:191], v[132:135]
	v_mfma_f32_16x16x32_bf16 v[128:131], v[108:111], v[188:191], v[128:131]
	v_mfma_f32_16x16x32_bf16 v[124:127], v[68:71], v[200:203], v[124:127]
	v_mfma_f32_16x16x32_bf16 v[120:123], v[108:111], v[200:203], v[120:123]
	v_mfma_f32_16x16x32_bf16 v[116:119], v[68:71], v[212:215], v[116:119]
	v_mfma_f32_16x16x32_bf16 v[112:115], v[108:111], v[212:215], v[112:115]
	v_mfma_f32_16x16x32_bf16 v[100:103], v[144:147], v[160:163], v[100:103]
	v_mfma_f32_16x16x32_bf16 v[96:99], v[152:155], v[160:163], v[96:99]
	v_mfma_f32_16x16x32_bf16 v[92:95], v[144:147], v[178:181], v[92:95]
	v_mfma_f32_16x16x32_bf16 v[88:91], v[152:155], v[178:181], v[88:91]
	v_mfma_f32_16x16x32_bf16 v[84:87], v[144:147], v[196:199], v[84:87]
	v_mfma_f32_16x16x32_bf16 v[80:83], v[152:155], v[196:199], v[80:83]
	v_mfma_f32_16x16x32_bf16 v[76:79], v[144:147], v[208:211], v[76:79]
	v_mfma_f32_16x16x32_bf16 v[72:75], v[152:155], v[208:211], v[72:75]
	v_mfma_f32_16x16x32_bf16 v[100:103], v[148:151], v[164:167], v[100:103]
	v_mfma_f32_16x16x32_bf16 v[96:99], v[156:159], v[164:167], v[96:99]
	v_mfma_f32_16x16x32_bf16 v[92:95], v[148:151], v[188:191], v[92:95]
	v_mfma_f32_16x16x32_bf16 v[88:91], v[156:159], v[188:191], v[88:91]
	v_mfma_f32_16x16x32_bf16 v[84:87], v[148:151], v[200:203], v[84:87]
	v_mfma_f32_16x16x32_bf16 v[80:83], v[156:159], v[200:203], v[80:83]
	v_mfma_f32_16x16x32_bf16 v[76:79], v[148:151], v[212:215], v[76:79]
	v_mfma_f32_16x16x32_bf16 v[72:75], v[156:159], v[212:215], v[72:75]
	s_barrier
; #define PG8_STAGE(bufoff, gbase, voff) do { _Pragma("unroll") for (int _i = 0; _i < 2; ++_i) \
;         __builtin_amdgcn_global_load_lds((const unsigned*)((const char*)(gbase) + (voff)[_i]), (LAS unsigned*)(lds + (bufoff) + ldsw + _i * 8192), 16, 0, 0); } while (0)
; #define PG8_LDA(dst, b, h) do { _Pragma("unroll") for (int m = 0; m < 4; ++m) _Pragma("unroll") for (int k = 0; k < 2; ++k) dst[m][k] = *(const LAS bf16x8*)(lds + PG8_SA(b, h) + aoff + m * 2048 + k * 1024); } while (0)
; #define PG8_MMA(ai, bj, At, Bt) do { __builtin_amdgcn_s_setprio(1); _Pragma("unroll") for (int m = 0; m < 4; ++m) _Pragma("unroll") for (int n = 0; n < 2; ++n) _Pragma("unroll") for (int k = 0; k < 2; ++k) \
;         acc[ai][bj][m][n] = __builtin_amdgcn_mfma_f32_16x16x32_bf16(Bt[n][k], At[m][k], acc[ai][bj][m][n], 0, 0, 0); __builtin_amdgcn_s_setprio(0); } while (0)
; #define PG8_WAIT_V(n) asm volatile("s_waitcnt vmcnt(" #n ")" ::: "memory")
; #define PG8_WAIT_L(n) asm volatile("s_waitcnt lgkmcnt(" #n ")" ::: "memory")
; #define PG8_BAR __builtin_amdgcn_s_barrier()
; #define PG8_SCHED __builtin_amdgcn_sched_barrier(0)
; template <class Epi, class Sched>
; DI void gemm_phase(LAS unsigned char* lds, const int wv, const int lda, const int ldb, const Sched& S, const Epi& E) {
;     ...
;             PG8_LDA(At, 1, 1); PG8_STAGE(PG8_SB(1, 0), b3, voffB); PG8_STAGE(PG8_SB(1, 1), b3 + hstepB, voffB); PG8_STAGE(PG8_SA(1, 0), a3, voffA);
;             PG8_WAIT_V(8); PG8_WAIT_L(0); PG8_BAR; PG8_MMA(1, 0, At, B0); PG8_MMA(1, 1, At, B1); PG8_BAR; PG8_SCHED;
;         }
;         if (wr == 0) PG8_BAR;
	s_add_i32 s22, s50, s36
	v_lshl_add_u64 v[182:183], v[182:183], 0, s[28:29]
	s_mov_b32 m0, s22
	ds_read_b128 v[160:163], v206 offset:49152
	ds_read_b128 v[164:167], v206 offset:50176
	ds_read_b128 v[178:181], v206 offset:51200
	ds_read_b128 v[188:191], v206 offset:52224
	ds_read_b128 v[196:199], v206 offset:53248
	ds_read_b128 v[200:203], v206 offset:54272
	ds_read_b128 v[208:211], v206 offset:55296
	ds_read_b128 v[212:215], v206 offset:56320
	global_load_lds_dwordx4 v[182:183], off
	s_add_i32 m0, s22, 0x2000
	s_add_u32 s22, s26, 0x30080
	v_lshl_add_u64 v[182:183], v[216:217], 0, s[28:29]
	s_addc_u32 s23, s27, 0
	s_add_i32 s26, s51, s36
	global_load_lds_dwordx4 v[182:183], off
	v_lshl_add_u64 v[182:183], s[22:23], 0, v[184:185]
	s_mov_b32 m0, s26
	s_nop 0
	global_load_lds_dwordx4 v[182:183], off
	v_lshl_add_u64 v[182:183], s[22:23], 0, v[168:169]
	s_add_i32 m0, s26, 0x2000
	s_nop 0
	global_load_lds_dwordx4 v[182:183], off
	v_lshl_add_u64 v[182:183], v[218:219], 0, s[28:29]
	s_mov_b32 m0, s20
	s_nop 0
	global_load_lds_dwordx4 v[182:183], off
	v_lshl_add_u64 v[182:183], v[220:221], 0, s[28:29]
	s_mov_b32 m0, s42
	s_nop 0
	global_load_lds_dwordx4 v[182:183], off
	s_waitcnt vmcnt(8)
	s_waitcnt lgkmcnt(0)
	s_barrier
	s_waitcnt lgkmcnt(0)
	v_mfma_f32_16x16x32_bf16 v[60:63], v[64:67], v[160:163], v[60:63]
	v_mfma_f32_16x16x32_bf16 v[56:59], v[104:107], v[160:163], v[56:59]
	v_mfma_f32_16x16x32_bf16 v[52:55], v[64:67], v[178:181], v[52:55]
	v_mfma_f32_16x16x32_bf16 v[48:51], v[104:107], v[178:181], v[48:51]
	v_mfma_f32_16x16x32_bf16 v[44:47], v[64:67], v[196:199], v[44:47]
	v_mfma_f32_16x16x32_bf16 v[40:43], v[104:107], v[196:199], v[40:43]
	v_mfma_f32_16x16x32_bf16 v[36:39], v[64:67], v[208:211], v[36:39]
	v_mfma_f32_16x16x32_bf16 v[32:35], v[104:107], v[208:211], v[32:35]
	v_mfma_f32_16x16x32_bf16 v[60:63], v[68:71], v[164:167], v[60:63]
	v_mfma_f32_16x16x32_bf16 v[56:59], v[108:111], v[164:167], v[56:59]
	v_mfma_f32_16x16x32_bf16 v[52:55], v[68:71], v[188:191], v[52:55]
	v_mfma_f32_16x16x32_bf16 v[48:51], v[108:111], v[188:191], v[48:51]
	v_mfma_f32_16x16x32_bf16 v[44:47], v[68:71], v[200:203], v[44:47]
	v_mfma_f32_16x16x32_bf16 v[40:43], v[108:111], v[200:203], v[40:43]
	v_mfma_f32_16x16x32_bf16 v[36:39], v[68:71], v[212:215], v[36:39]
	v_mfma_f32_16x16x32_bf16 v[32:35], v[108:111], v[212:215], v[32:35]
	v_mfma_f32_16x16x32_bf16 v[28:31], v[144:147], v[160:163], v[28:31]
	v_mfma_f32_16x16x32_bf16 v[24:27], v[152:155], v[160:163], v[24:27]
	v_mfma_f32_16x16x32_bf16 v[20:23], v[144:147], v[178:181], v[20:23]
	v_mfma_f32_16x16x32_bf16 v[16:19], v[152:155], v[178:181], v[16:19]
	v_mfma_f32_16x16x32_bf16 v[12:15], v[144:147], v[196:199], v[12:15]
	v_mfma_f32_16x16x32_bf16 v[8:11], v[152:155], v[196:199], v[8:11]
	v_mfma_f32_16x16x32_bf16 v[4:7], v[144:147], v[208:211], v[4:7]
	v_mfma_f32_16x16x32_bf16 v[0:3], v[152:155], v[208:211], v[0:3]
	v_mfma_f32_16x16x32_bf16 v[28:31], v[148:151], v[164:167], v[28:31]
	v_mfma_f32_16x16x32_bf16 v[24:27], v[156:159], v[164:167], v[24:27]
	v_mfma_f32_16x16x32_bf16 v[20:23], v[148:151], v[188:191], v[20:23]
	v_mfma_f32_16x16x32_bf16 v[16:19], v[156:159], v[188:191], v[16:19]
	v_mfma_f32_16x16x32_bf16 v[12:15], v[148:151], v[200:203], v[12:15]
	v_mfma_f32_16x16x32_bf16 v[8:11], v[156:159], v[200:203], v[8:11]
	v_mfma_f32_16x16x32_bf16 v[4:7], v[148:151], v[212:215], v[4:7]
	v_mfma_f32_16x16x32_bf16 v[0:3], v[156:159], v[212:215], v[0:3]
	s_barrier
	s_add_i32 s49, s49, 2
	s_add_u32 s0, s0, 0x100
	s_addc_u32 s1, s1, 0
	s_cmp_gt_u32 s49, 9
	s_mov_b64 s[22:23], s[24:25]
	s_cbranch_scc0 .LBB0_1099
	s_and_b64 vcc, exec, s[14:15]
	s_cbranch_vccz .LBB0_1102
	s_barrier

; DI int lane_id_fresh() { int l; asm volatile("v_mbcnt_lo_u32_b32 %0, -1, 0\n\tv_mbcnt_hi_u32_b32 %0, -1, %0" : "=v"(l)); return l; }
; #define SEAM(k) do { if (IN((k) + 1) && IN(k)) xcd_barrier(bar); } while (0)
; __device__ __forceinline__ void xcd_barrier(const XcdBarrier& b) {
;     asm volatile("s_waitcnt vmcnt(0)" ::: "memory");
;     __syncthreads();
;     if (b.w0 && lane_id_fresh() == 0) {
;         unsigned* bar = b.bar;
;         __builtin_amdgcn_s_waitcnt(0);
;         unsigned nloc = b.st[0], nx = b.st[1];
;         if (nloc == 0u) { xcd_barrier_complete(bar, b.x, nloc, nx); b.st[0] = nloc; b.st[1] = nx; }
; __global__ void __launch_bounds__(512, 2) trunk_fwd(Args args_unused) {
;     ...
;             SEAM(s0 + 6);
.LBB0_1106:
	s_setprio 0
	v_readlane_b32 s0, v254, 37
	s_add_i32 s17, s0, 8
	v_readlane_b32 s0, v252, 10
	v_readlane_b32 s3, v252, 13
	s_cmp_ge_i32 s17, s3
	v_readlane_b32 s1, v252, 11
	v_readlane_b32 s2, v252, 12
	s_cbranch_scc1 .LBB0_1119
	s_waitcnt vmcnt(0)
	v_readlane_b32 s0, v252, 5
	v_readlane_b32 s1, v252, 6
	s_and_b64 vcc, exec, s[0:1]
	v_readlane_b32 s33, v254, 29
	s_barrier
	s_cbranch_vccnz .LBB0_1158
	v_mbcnt_lo_u32_b32 v0, -1, 0
	v_mbcnt_hi_u32_b32 v0, -1, v0
	s_nop 0
	v_cmp_eq_u32_e32 vcc, 0, v0
	s_and_saveexec_b64 s[2:3], vcc
	s_cbranch_execz .LBB0_1157
	v_readlane_b32 s0, v254, 5
	s_waitcnt vmcnt(0) expcnt(0) lgkmcnt(0)
	s_nop 0
	v_mov_b32_e32 v0, s0
	ds_read_b32 v2, v0
	v_readlane_b32 s0, v254, 6
	s_waitcnt lgkmcnt(0)
	v_cmp_ne_u32_e32 vcc, 0, v2
	v_mov_b32_e32 v0, s0
	ds_read_b32 v0, v0
	s_cbranch_vccnz .LBB0_1125
	v_readlane_b32 s4, v252, 7
	v_readlane_b32 s5, v252, 8
	s_load_dwordx2 s[0:1], s[4:5], 0x4
	s_mov_b32 s9, 1
	s_waitcnt lgkmcnt(0)
	s_mul_i32 s8, s0, s16
	s_mul_i32 s8, s8, s1
	s_branch .LBB0_1112

;     DI void init(const bf16* A_, int lda, const bf16* B_, int ldb, int nM, int nN, int K, int G_, int c_) { T.init(nM, nN); G = G_; c = c_; nt = K / BK; A = (const char*)A_; B = (const char*)B_; ta = (size_t)BM * lda * 2; tb = (size_t)BM * ldb * 2; }
;     DI void init(const bf16* A_, int lda, const bf16* B_, int ldb, int nM, int nN, int G_, int c_) { T.init(nM, nN); G = G_; c = c_; A = (const char*)A_; B = (const char*)B_; ta = (size_t)BM * lda * 2; tb = (size_t)BM * ldb * 2; }
;     DI const char* aptr(const Unit& u) const { return A + (size_t)u.pm * ta + (size_t)kofs(u.seg) * 2; }
;     DI const char* bptr(const Unit& u) const { return B + (size_t)u.pn * tb + (size_t)kofs(u.seg) * 2; }
; #define PG8_STAGE(bufoff, gbase, voff) do { _Pragma("unroll") for (int _i = 0; _i < 2; ++_i) \
;         __builtin_amdgcn_global_load_lds((const unsigned*)((const char*)(gbase) + (voff)[_i]), (LAS unsigned*)(lds + (bufoff) + ldsw + _i * 8192), 16, 0, 0); } while (0)
; template <class Epi, class Sched>
; DI void gemm_phase(LAS unsigned char* lds, const int wv, const int lda, const int ldb, const Sched& S, const Epi& E) {
;     ...
;     f32x4 acc[2][2][4][2];
; #pragma unroll
;     for (int a = 0; a < 2; ++a)
; #pragma unroll
;         for (int b = 0; b < 2; ++b)
; #pragma unroll
;             for (int m = 0; m < 4; ++m)
; #pragma unroll
;                 for (int n = 0; n < 2; ++n) acc[a][b][m][n] = (f32x4){0.f, 0.f, 0.f, 0.f};
;     bf16x8 At[4][2], B0[2][2], B1[2][2];
;     const char* cA = S.aptr(cur); const char* cB = S.bptr(cur); int nt = S.ntiles(cur);
;     PG8_STAGE(PG8_SB(0, 0), cB, voffB); PG8_STAGE(PG8_SB(0, 1), cB + hstepB, voffB); PG8_STAGE(PG8_SA(0, 0), cA, voffA); PG8_STAGE(PG8_SA(0, 1), cA + hstepA, voffA);
;     if (wr == 1) PG8_BAR;
;     PG8_WAIT_V(2); PG8_BAR;
;     PG8_STAGE(PG8_SB(1, 0), cB + kstep, voffB); PG8_STAGE(PG8_SA(1, 0), cA + kstep, voffA); PG8_STAGE(PG8_SB(1, 1), cB + hstepB + kstep, voffB);
;     PG8_WAIT_V(6); PG8_BAR;
; __global__ void __launch_bounds__(512, 2) trunk_fwd(Args args_unused) {
;     ...
;         if (PHEN(7) && IN(s0 + 7)) { FRAME();
;             SchedSeg3 S; S.init((const bf16*)(F.ws + WS_R3), D, (const bf16*)lw(F, l, LW_WUP), D, M / BM, D / BM, F.G, F.bid);
;             EpiMerged E{(const bf16*)(F.ws + WS_R2), (bf16*)(F.ws + WS_R1)};
;             gemm_phase<EpiMerged, SchedSeg3>(F.lds, F.wave, D, D, S, E);
.LBB0_1171:
	s_add_u32 s8, s4, 0x23c28000
	v_lshrrev_b32_e32 v16, 1, v8
	s_addc_u32 s9, s5, 0
	v_and_b32_e32 v16, 24, v16
	s_add_u32 s10, s4, 0x1fc28000
	v_and_b32_e32 v15, 15, v8
	v_lshlrev_b32_e32 v17, 1, v16
	v_lshlrev_b32_e32 v8, 2, v8
	s_addc_u32 s11, s5, 0
	v_lshl_or_b32 v186, s0, 6, v15
	v_lshl_or_b32 v15, v15, 6, v17
	s_lshl_b32 s0, s0, 13
	v_and_b32_e32 v8, 32, v8
	v_bitop3_b32 v17, v15, s0, v8 bitop3:0xde
	s_lshl_b32 s0, s1, 5
	s_and_b32 s4, s0, 0x60
	s_add_i32 m0, s45, 0x18000
	v_lshl_add_u64 v[6:7], v[6:7], 0, s[28:29]
	s_lshl_b32 s0, s4, 7
	s_waitcnt vmcnt(2)
	s_barrier
	global_load_lds_dwordx4 v[6:7], off
	v_lshl_add_u64 v[4:5], v[4:5], 0, s[28:29]
	s_add_i32 m0, s45, 0x1a000
	s_add_i32 s49, s45, 0x8000
	s_add_i32 s50, s45, 0xa000
	v_bitop3_b32 v233, v15, s0, v8 bitop3:0xde
	global_load_lds_dwordx4 v[4:5], off
	v_lshl_add_u64 v[0:1], v[0:1], 0, s[28:29]
	s_mov_b32 m0, s49
	s_add_u32 s0, s34, 0x80080
	global_load_lds_dwordx4 v[0:1], off
	v_lshl_add_u64 v[0:1], v[2:3], 0, s[28:29]
	s_mov_b32 m0, s50
	s_addc_u32 s1, s35, 0
	global_load_lds_dwordx4 v[0:1], off
	s_add_i32 m0, s45, 0x1c000
	v_lshl_add_u64 v[0:1], s[0:1], 0, v[184:185]
	global_load_lds_dwordx4 v[0:1], off
	v_lshl_add_u64 v[0:1], s[0:1], 0, v[204:205]
	s_add_i32 m0, s45, 0x1e000
	s_cmpk_lt_u32 s6, 0x100
	global_load_lds_dwordx4 v[0:1], off
	v_lshlrev_b32_e32 v0, 15, v9
	v_and_b32_e32 v0, 0xffff0000, v0
	v_lshl_add_u32 v0, v10, 12, v0
	v_and_b32_e32 v1, 1, v9
	v_lshl_or_b32 v0, v1, 6, v0
	v_lshl_add_u32 v206, v11, 1, v0
	v_lshlrev_b32_e32 v0, 15, v12
	v_and_b32_e32 v0, 0xffff0000, v0
	v_lshl_add_u32 v0, v13, 12, v0
	v_and_b32_e32 v1, 1, v12
	s_waitcnt vmcnt(6)
	v_lshl_or_b32 v0, v1, 6, v0
	v_lshl_add_u32 v208, v14, 1, v0
	v_mov_b32_e32 v0, 0
	s_cselect_b64 s[12:13], -1, 0
	s_ashr_i32 s51, s17, 31
	v_or_b32_e32 v234, s4, v16
	s_mov_b32 s27, 12
	v_mov_b32_e32 v207, v185
	v_mov_b32_e32 v209, v185
	s_mov_b32 s33, 0
	v_add_u32_e32 v235, 0, v17
	s_mov_b32 s52, 0
	v_mov_b32_e32 v1, v0
	v_mov_b32_e32 v2, v0
	v_mov_b32_e32 v3, v0
	v_mov_b32_e32 v4, v0
	v_mov_b32_e32 v5, v0
	v_mov_b32_e32 v6, v0
	v_mov_b32_e32 v7, v0
	v_mov_b32_e32 v8, v0
	v_mov_b32_e32 v9, v0
	v_mov_b32_e32 v10, v0
	v_mov_b32_e32 v11, v0
	v_mov_b32_e32 v12, v0
	v_mov_b32_e32 v13, v0
	v_mov_b32_e32 v14, v0
	v_mov_b32_e32 v15, v0
	v_mov_b32_e32 v16, v0
	v_mov_b32_e32 v17, v0
	v_mov_b32_e32 v18, v0
	v_mov_b32_e32 v19, v0
	v_mov_b32_e32 v20, v0
	v_mov_b32_e32 v21, v0
	v_mov_b32_e32 v22, v0
	v_mov_b32_e32 v23, v0
	v_mov_b32_e32 v24, v0
	v_mov_b32_e32 v25, v0
	v_mov_b32_e32 v26, v0
	v_mov_b32_e32 v27, v0
	v_mov_b32_e32 v28, v0
	v_mov_b32_e32 v29, v0
	v_mov_b32_e32 v30, v0
	v_mov_b32_e32 v31, v0
	v_mov_b32_e32 v32, v0
	v_mov_b32_e32 v33, v0
	v_mov_b32_e32 v34, v0
	v_mov_b32_e32 v35, v0
	v_mov_b32_e32 v36, v0
	v_mov_b32_e32 v37, v0
	v_mov_b32_e32 v38, v0
	v_mov_b32_e32 v39, v0
	v_mov_b32_e32 v40, v0
	v_mov_b32_e32 v41, v0
	v_mov_b32_e32 v42, v0
	v_mov_b32_e32 v43, v0
	v_mov_b32_e32 v44, v0
	v_mov_b32_e32 v45, v0
	v_mov_b32_e32 v46, v0
	v_mov_b32_e32 v47, v0
	v_mov_b32_e32 v48, v0
	v_mov_b32_e32 v49, v0
	v_mov_b32_e32 v50, v0
	v_mov_b32_e32 v51, v0
	v_mov_b32_e32 v52, v0
	v_mov_b32_e32 v53, v0
	v_mov_b32_e32 v54, v0
	v_mov_b32_e32 v55, v0
	v_mov_b32_e32 v56, v0
	v_mov_b32_e32 v57, v0
	v_mov_b32_e32 v58, v0
	v_mov_b32_e32 v59, v0
	v_mov_b32_e32 v60, v0
	v_mov_b32_e32 v61, v0
	v_mov_b32_e32 v62, v0
	v_mov_b32_e32 v63, v0
	v_mov_b32_e32 v64, v0
	v_mov_b32_e32 v65, v0
	v_mov_b32_e32 v66, v0
	v_mov_b32_e32 v67, v0
	v_mov_b32_e32 v68, v0
	v_mov_b32_e32 v69, v0
	v_mov_b32_e32 v70, v0
	v_mov_b32_e32 v71, v0
	v_mov_b32_e32 v72, v0
	v_mov_b32_e32 v73, v0
	v_mov_b32_e32 v74, v0
	v_mov_b32_e32 v75, v0
	v_mov_b32_e32 v76, v0
	v_mov_b32_e32 v77, v0
	v_mov_b32_e32 v78, v0
	v_mov_b32_e32 v79, v0
	v_mov_b32_e32 v80, v0
	v_mov_b32_e32 v81, v0
	v_mov_b32_e32 v82, v0
	v_mov_b32_e32 v83, v0
	v_mov_b32_e32 v84, v0
	v_mov_b32_e32 v85, v0
	v_mov_b32_e32 v86, v0
	v_mov_b32_e32 v87, v0
	v_mov_b32_e32 v88, v0
	v_mov_b32_e32 v89, v0
	v_mov_b32_e32 v90, v0
	v_mov_b32_e32 v91, v0
	v_mov_b32_e32 v92, v0
	v_mov_b32_e32 v93, v0
	v_mov_b32_e32 v94, v0
	v_mov_b32_e32 v95, v0
	v_mov_b32_e32 v96, v0
	v_mov_b32_e32 v97, v0
	v_mov_b32_e32 v98, v0
	v_mov_b32_e32 v99, v0
	v_mov_b32_e32 v100, v0
	v_mov_b32_e32 v101, v0
	v_mov_b32_e32 v102, v0
	v_mov_b32_e32 v103, v0
	v_mov_b32_e32 v104, v0
	v_mov_b32_e32 v105, v0
	v_mov_b32_e32 v106, v0
	v_mov_b32_e32 v107, v0
	v_mov_b32_e32 v108, v0
	v_mov_b32_e32 v109, v0
	v_mov_b32_e32 v110, v0
	v_mov_b32_e32 v111, v0
	v_mov_b32_e32 v112, v0
	v_mov_b32_e32 v113, v0
	v_mov_b32_e32 v114, v0
	v_mov_b32_e32 v115, v0
	v_mov_b32_e32 v116, v0
	v_mov_b32_e32 v117, v0
	v_mov_b32_e32 v118, v0
	v_mov_b32_e32 v119, v0
	v_mov_b32_e32 v120, v0
	v_mov_b32_e32 v121, v0
	v_mov_b32_e32 v122, v0
	v_mov_b32_e32 v123, v0
	v_mov_b32_e32 v124, v0
	v_mov_b32_e32 v125, v0
	v_mov_b32_e32 v126, v0
	v_mov_b32_e32 v127, v0
	s_barrier
	v_mbcnt_lo_u32_b32 v248, -1, 0
	v_mbcnt_hi_u32_b32 v248, -1, v248
	s_lshl_b32 s98, s90, 10
	s_add_i32 s98, s98, 0x22000
	v_lshl_add_u32 v246, v248, 4, s98
	v_and_b32_e32 v249, 15, v248
	v_lshrrev_b32_e32 v242, 4, v248
	v_lshrrev_b32_e32 v243, 2, v249
	v_lshl_add_u32 v242, v243, 4, v242
	v_and_b32_e32 v243, 3, v249
	v_lshl_add_u32 v242, v243, 2, v242
	v_lshl_add_u32 v247, v242, 4, s98
	v_lshrrev_b32_e32 v242, 4, v248
	v_bfe_u32 v243, v248, 2, 2
	v_lshl_add_u32 v243, v242, 2, v243
	v_sub_u32_e32 v243, v243, v249
	v_and_b32_e32 v249, 3, v248
	v_sub_u32_e32 v249, v249, v242
	v_lshlrev_b32_e32 v249, 4, v249
	s_movk_i32 s98, 0x5a00
	v_mad_i32_i24 v240, v243, s98, v249
	v_ashrrev_i32_e32 v241, 31, v240
	s_cmp_ge_u32 s90, 4
	s_cbranch_scc0 .Lprio_1174_done
	s_setprio 1

; #define PG8_STAGE(bufoff, gbase, voff) do { _Pragma("unroll") for (int _i = 0; _i < 2; ++_i) \
;         __builtin_amdgcn_global_load_lds((const unsigned*)((const char*)(gbase) + (voff)[_i]), (LAS unsigned*)(lds + (bufoff) + ldsw + _i * 8192), 16, 0, 0); } while (0)
; #define PG8_LDA(dst, b, h) do { _Pragma("unroll") for (int m = 0; m < 4; ++m) _Pragma("unroll") for (int k = 0; k < 2; ++k) dst[m][k] = *(const LAS bf16x8*)(lds + PG8_SA(b, h) + aoff + m * 2048 + k * 1024); } while (0)
; #define PG8_LDB(dst, b, h) do { _Pragma("unroll") for (int n = 0; n < 2; ++n) _Pragma("unroll") for (int k = 0; k < 2; ++k) dst[n][k] = *(const LAS bf16x8*)(lds + PG8_SB(b, h) + boff + n * 2048 + k * 1024); } while (0)
; #define PG8_MMA(ai, bj, At, Bt) do { __builtin_amdgcn_s_setprio(1); _Pragma("unroll") for (int m = 0; m < 4; ++m) _Pragma("unroll") for (int n = 0; n < 2; ++n) _Pragma("unroll") for (int k = 0; k < 2; ++k) \
;         acc[ai][bj][m][n] = __builtin_amdgcn_mfma_f32_16x16x32_bf16(Bt[n][k], At[m][k], acc[ai][bj][m][n], 0, 0, 0); __builtin_amdgcn_s_setprio(0); } while (0)
; #define PG8_WAIT_V(n) asm volatile("s_waitcnt vmcnt(" #n ")" ::: "memory")
; #define PG8_WAIT_L(n) asm volatile("s_waitcnt lgkmcnt(" #n ")" ::: "memory")
; #define PG8_BAR __builtin_amdgcn_s_barrier()
; #define PG8_SCHED __builtin_amdgcn_sched_barrier(0)
; template <class Epi, class Sched>
; DI void gemm_phase(LAS unsigned char* lds, const int wv, const int lda, const int ldb, const Sched& S, const Epi& E) {
;     ...
;             const char* a1 = cA + (size_t)(t + 1) * kstep;
;             const char* a2 = last ? nA : cA + (size_t)(t + 2) * kstep; const char* b2 = last ? nB : cB + (size_t)(t + 2) * kstep;
;             const char* a3 = a2 + kstep; const char* b3 = b2 + kstep;
;             PG8_LDB(B0, 0, 0); PG8_LDB(B1, 0, 1); PG8_SCHED; PG8_LDA(At, 0, 0); PG8_STAGE(PG8_SA(1, 1), a1 + hstepA, voffA);
;             PG8_WAIT_V(8); PG8_WAIT_L(0); PG8_BAR; PG8_MMA(0, 0, At, B0); PG8_MMA(0, 1, At, B1); PG8_BAR; PG8_SCHED;
;             PG8_LDA(At, 0, 1); PG8_STAGE(PG8_SB(0, 0), b2, voffB); PG8_STAGE(PG8_SB(0, 1), b2 + hstepB, voffB); PG8_STAGE(PG8_SA(0, 0), a2, voffA);
;             PG8_WAIT_V(8); PG8_WAIT_L(0); PG8_BAR; PG8_MMA(1, 0, At, B0); PG8_MMA(1, 1, At, B1); PG8_BAR; PG8_SCHED;
.LBB0_1185:
	s_add_i32 s31, s19, 2
	s_add_u32 s34, s6, 0xfff80080
	s_addc_u32 s35, s7, -1
	s_add_i32 s40, 0, 0x10000
	s_cmp_eq_u32 s0, s19
	s_cselect_b32 s37, s23, s35
	s_cselect_b32 s36, s22, s34
	s_cselect_b32 s35, s25, s15
	s_cselect_b32 s34, s24, s1
	s_add_i32 s19, 0, 0x14000
	v_add_u32_e32 v140, s40, v233
	v_add_u32_e32 v156, s19, v233
	ds_read_b128 v[128:131], v140
	ds_read_b128 v[132:135], v140 offset:1024
	ds_read_b128 v[136:139], v140 offset:2048
	ds_read_b128 v[140:143], v140 offset:3072
	ds_read_b128 v[144:147], v156
	ds_read_b128 v[148:151], v156 offset:1024
	ds_read_b128 v[152:155], v156 offset:2048
	ds_read_b128 v[156:159], v156 offset:3072
	v_lshl_add_u64 v[210:211], s[6:7], 0, v[206:207]
	s_add_i32 m0, s45, 0xc000
	ds_read_b128 v[160:163], v235
	ds_read_b128 v[164:167], v235 offset:1024
	ds_read_b128 v[168:171], v235 offset:2048
	ds_read_b128 v[172:175], v235 offset:3072
	ds_read_b128 v[176:179], v235 offset:4096
	ds_read_b128 v[180:183], v235 offset:5120
	ds_read_b128 v[188:191], v235 offset:6144
	ds_read_b128 v[196:199], v235 offset:7168
	global_load_lds_dwordx4 v[210:211], off
	v_lshl_add_u64 v[210:211], s[6:7], 0, v[208:209]
	s_add_i32 m0, s45, 0xe000
	s_nop 0
	global_load_lds_dwordx4 v[210:211], off
	s_waitcnt vmcnt(8)
	s_waitcnt lgkmcnt(0)
	s_barrier
	s_waitcnt lgkmcnt(0)
	v_mfma_f32_16x16x32_bf16 v[124:127], v[128:131], v[160:163], v[124:127]
	v_mfma_f32_16x16x32_bf16 v[120:123], v[136:139], v[160:163], v[120:123]
	v_mfma_f32_16x16x32_bf16 v[116:119], v[128:131], v[168:171], v[116:119]
	v_mfma_f32_16x16x32_bf16 v[112:115], v[136:139], v[168:171], v[112:115]
	v_mfma_f32_16x16x32_bf16 v[108:111], v[128:131], v[176:179], v[108:111]
	v_mfma_f32_16x16x32_bf16 v[104:107], v[136:139], v[176:179], v[104:107]
	v_mfma_f32_16x16x32_bf16 v[100:103], v[128:131], v[188:191], v[100:103]
	v_mfma_f32_16x16x32_bf16 v[96:99], v[136:139], v[188:191], v[96:99]
	v_mfma_f32_16x16x32_bf16 v[124:127], v[132:135], v[164:167], v[124:127]
	v_mfma_f32_16x16x32_bf16 v[120:123], v[140:143], v[164:167], v[120:123]
	v_mfma_f32_16x16x32_bf16 v[116:119], v[132:135], v[172:175], v[116:119]
	v_mfma_f32_16x16x32_bf16 v[112:115], v[140:143], v[172:175], v[112:115]
	v_mfma_f32_16x16x32_bf16 v[108:111], v[132:135], v[180:183], v[108:111]
	v_mfma_f32_16x16x32_bf16 v[104:107], v[140:143], v[180:183], v[104:107]
	v_mfma_f32_16x16x32_bf16 v[100:103], v[132:135], v[196:199], v[100:103]
	v_mfma_f32_16x16x32_bf16 v[96:99], v[140:143], v[196:199], v[96:99]
	v_mfma_f32_16x16x32_bf16 v[92:95], v[144:147], v[160:163], v[92:95]
	v_mfma_f32_16x16x32_bf16 v[88:91], v[152:155], v[160:163], v[88:91]
	v_mfma_f32_16x16x32_bf16 v[84:87], v[144:147], v[168:171], v[84:87]
	v_mfma_f32_16x16x32_bf16 v[80:83], v[152:155], v[168:171], v[80:83]
	v_mfma_f32_16x16x32_bf16 v[76:79], v[144:147], v[176:179], v[76:79]
	v_mfma_f32_16x16x32_bf16 v[72:75], v[152:155], v[176:179], v[72:75]
	v_mfma_f32_16x16x32_bf16 v[68:71], v[144:147], v[188:191], v[68:71]
	v_mfma_f32_16x16x32_bf16 v[64:67], v[152:155], v[188:191], v[64:67]
	v_mfma_f32_16x16x32_bf16 v[92:95], v[148:151], v[164:167], v[92:95]
	v_mfma_f32_16x16x32_bf16 v[88:91], v[156:159], v[164:167], v[88:91]
	v_mfma_f32_16x16x32_bf16 v[84:87], v[148:151], v[172:175], v[84:87]
	v_mfma_f32_16x16x32_bf16 v[80:83], v[156:159], v[172:175], v[80:83]
	v_mfma_f32_16x16x32_bf16 v[76:79], v[148:151], v[180:183], v[76:79]
	v_mfma_f32_16x16x32_bf16 v[72:75], v[156:159], v[180:183], v[72:75]
	v_mfma_f32_16x16x32_bf16 v[68:71], v[148:151], v[196:199], v[68:71]
	v_mfma_f32_16x16x32_bf16 v[64:67], v[156:159], v[196:199], v[64:67]
	s_barrier
	s_add_i32 s40, s40, s44
	v_lshl_add_u64 v[210:211], s[34:35], 0, v[184:185]
	s_mov_b32 m0, s40
	ds_read_b128 v[160:163], v235 offset:16384
	ds_read_b128 v[164:167], v235 offset:17408
	ds_read_b128 v[168:171], v235 offset:18432
	ds_read_b128 v[172:175], v235 offset:19456
	ds_read_b128 v[176:179], v235 offset:20480
	ds_read_b128 v[180:183], v235 offset:21504
	ds_read_b128 v[188:191], v235 offset:22528
	ds_read_b128 v[196:199], v235 offset:23552
	global_load_lds_dwordx4 v[210:211], off
	s_add_i32 m0, s40, 0x2000
	s_add_u32 s40, s34, 0x80000
	v_lshl_add_u64 v[212:213], s[34:35], 0, v[204:205]
	s_addc_u32 s41, s35, 0
	s_add_i32 s19, s19, s44
	global_load_lds_dwordx4 v[212:213], off
	v_lshl_add_u64 v[214:215], s[40:41], 0, v[184:185]
	s_mov_b32 m0, s19
	v_lshl_add_u64 v[216:217], s[36:37], 0, v[202:203]
	global_load_lds_dwordx4 v[214:215], off
	v_lshl_add_u64 v[214:215], s[40:41], 0, v[204:205]
	s_add_i32 m0, s19, 0x2000
	s_nop 0
	global_load_lds_dwordx4 v[214:215], off
	v_lshl_add_u64 v[214:215], s[36:37], 0, v[200:201]
	s_mov_b32 m0, s45
	s_nop 0
	global_load_lds_dwordx4 v[214:215], off
	s_mov_b32 m0, s46
	s_nop 0
	global_load_lds_dwordx4 v[216:217], off
	s_waitcnt vmcnt(8)
	s_waitcnt lgkmcnt(0)
	s_barrier
; #define PG8_STAGE(bufoff, gbase, voff) do { _Pragma("unroll") for (int _i = 0; _i < 2; ++_i) \
;         __builtin_amdgcn_global_load_lds((const unsigned*)((const char*)(gbase) + (voff)[_i]), (LAS unsigned*)(lds + (bufoff) + ldsw + _i * 8192), 16, 0, 0); } while (0)
; #define PG8_LDA(dst, b, h) do { _Pragma("unroll") for (int m = 0; m < 4; ++m) _Pragma("unroll") for (int k = 0; k < 2; ++k) dst[m][k] = *(const LAS bf16x8*)(lds + PG8_SA(b, h) + aoff + m * 2048 + k * 1024); } while (0)
; #define PG8_LDB(dst, b, h) do { _Pragma("unroll") for (int n = 0; n < 2; ++n) _Pragma("unroll") for (int k = 0; k < 2; ++k) dst[n][k] = *(const LAS bf16x8*)(lds + PG8_SB(b, h) + boff + n * 2048 + k * 1024); } while (0)
; #define PG8_MMA(ai, bj, At, Bt) do { __builtin_amdgcn_s_setprio(1); _Pragma("unroll") for (int m = 0; m < 4; ++m) _Pragma("unroll") for (int n = 0; n < 2; ++n) _Pragma("unroll") for (int k = 0; k < 2; ++k) \
;         acc[ai][bj][m][n] = __builtin_amdgcn_mfma_f32_16x16x32_bf16(Bt[n][k], At[m][k], acc[ai][bj][m][n], 0, 0, 0); __builtin_amdgcn_s_setprio(0); } while (0)
; #define PG8_WAIT_V(n) asm volatile("s_waitcnt vmcnt(" #n ")" ::: "memory")
; #define PG8_WAIT_L(n) asm volatile("s_waitcnt lgkmcnt(" #n ")" ::: "memory")
; #define PG8_BAR __builtin_amdgcn_s_barrier()
; #define PG8_SCHED __builtin_amdgcn_sched_barrier(0)
; template <class Epi, class Sched>
; DI void gemm_phase(LAS unsigned char* lds, const int wv, const int lda, const int ldb, const Sched& S, const Epi& E) {
;     ...
;             PG8_WAIT_V(8); PG8_WAIT_L(0); PG8_BAR; PG8_MMA(1, 0, At, B0); PG8_MMA(1, 1, At, B1); PG8_BAR; PG8_SCHED;
;             PG8_LDB(B0, 1, 0); PG8_LDB(B1, 1, 1); PG8_SCHED; PG8_LDA(At, 1, 0); PG8_STAGE(PG8_SA(0, 1), a2 + hstepA, voffA);
;             PG8_WAIT_V(8); PG8_WAIT_L(0); PG8_BAR; PG8_MMA(0, 0, At, B0); PG8_MMA(0, 1, At, B1); PG8_BAR; PG8_SCHED;
	s_waitcnt lgkmcnt(0)
	v_mfma_f32_16x16x32_bf16 v[60:63], v[128:131], v[160:163], v[60:63]
	v_mfma_f32_16x16x32_bf16 v[56:59], v[136:139], v[160:163], v[56:59]
	v_mfma_f32_16x16x32_bf16 v[52:55], v[128:131], v[168:171], v[52:55]
	v_mfma_f32_16x16x32_bf16 v[48:51], v[136:139], v[168:171], v[48:51]
	v_mfma_f32_16x16x32_bf16 v[44:47], v[128:131], v[176:179], v[44:47]
	v_mfma_f32_16x16x32_bf16 v[40:43], v[136:139], v[176:179], v[40:43]
	v_mfma_f32_16x16x32_bf16 v[36:39], v[128:131], v[188:191], v[36:39]
	v_mfma_f32_16x16x32_bf16 v[32:35], v[136:139], v[188:191], v[32:35]
	v_mfma_f32_16x16x32_bf16 v[60:63], v[132:135], v[164:167], v[60:63]
	v_mfma_f32_16x16x32_bf16 v[56:59], v[140:143], v[164:167], v[56:59]
	v_mfma_f32_16x16x32_bf16 v[52:55], v[132:135], v[172:175], v[52:55]
	v_mfma_f32_16x16x32_bf16 v[48:51], v[140:143], v[172:175], v[48:51]
	v_mfma_f32_16x16x32_bf16 v[44:47], v[132:135], v[180:183], v[44:47]
	v_mfma_f32_16x16x32_bf16 v[40:43], v[140:143], v[180:183], v[40:43]
	v_mfma_f32_16x16x32_bf16 v[36:39], v[132:135], v[196:199], v[36:39]
	v_mfma_f32_16x16x32_bf16 v[32:35], v[140:143], v[196:199], v[32:35]
	v_mfma_f32_16x16x32_bf16 v[28:31], v[144:147], v[160:163], v[28:31]
	v_mfma_f32_16x16x32_bf16 v[24:27], v[152:155], v[160:163], v[24:27]
	v_mfma_f32_16x16x32_bf16 v[20:23], v[144:147], v[168:171], v[20:23]
	v_mfma_f32_16x16x32_bf16 v[16:19], v[152:155], v[168:171], v[16:19]
	v_mfma_f32_16x16x32_bf16 v[12:15], v[144:147], v[176:179], v[12:15]
	v_mfma_f32_16x16x32_bf16 v[8:11], v[152:155], v[176:179], v[8:11]
	v_mfma_f32_16x16x32_bf16 v[4:7], v[144:147], v[188:191], v[4:7]
	v_mfma_f32_16x16x32_bf16 v[0:3], v[152:155], v[188:191], v[0:3]
	v_mfma_f32_16x16x32_bf16 v[28:31], v[148:151], v[164:167], v[28:31]
	v_mfma_f32_16x16x32_bf16 v[24:27], v[156:159], v[164:167], v[24:27]
	v_mfma_f32_16x16x32_bf16 v[20:23], v[148:151], v[172:175], v[20:23]
	v_mfma_f32_16x16x32_bf16 v[16:19], v[156:159], v[172:175], v[16:19]
	v_mfma_f32_16x16x32_bf16 v[12:15], v[148:151], v[180:183], v[12:15]
	v_mfma_f32_16x16x32_bf16 v[8:11], v[156:159], v[180:183], v[8:11]
	v_mfma_f32_16x16x32_bf16 v[4:7], v[148:151], v[196:199], v[4:7]
	v_mfma_f32_16x16x32_bf16 v[0:3], v[156:159], v[196:199], v[0:3]
	s_barrier
	s_add_i32 s19, 0, 0x18000
	s_add_i32 s40, 0, 0x1c000
	v_add_u32_e32 v140, s19, v233
	v_add_u32_e32 v156, s40, v233
	ds_read_b128 v[128:131], v140
	ds_read_b128 v[132:135], v140 offset:1024
	ds_read_b128 v[136:139], v140 offset:2048
	ds_read_b128 v[140:143], v140 offset:3072
	ds_read_b128 v[144:147], v156
	ds_read_b128 v[148:151], v156 offset:1024
	ds_read_b128 v[152:155], v156 offset:2048
	ds_read_b128 v[156:159], v156 offset:3072
	s_add_u32 s36, s36, 0x80000
	s_addc_u32 s37, s37, 0
	s_mov_b32 m0, s47
	v_lshl_add_u64 v[218:219], s[36:37], 0, v[200:201]
	ds_read_b128 v[160:163], v235 offset:32768
	ds_read_b128 v[164:167], v235 offset:33792
	ds_read_b128 v[168:171], v235 offset:34816
	ds_read_b128 v[172:175], v235 offset:35840
	ds_read_b128 v[176:179], v235 offset:36864
	ds_read_b128 v[180:183], v235 offset:37888
	ds_read_b128 v[188:191], v235 offset:38912
	ds_read_b128 v[196:199], v235 offset:39936
	global_load_lds_dwordx4 v[218:219], off
	v_lshl_add_u64 v[218:219], s[36:37], 0, v[202:203]
	s_mov_b32 m0, s48
	s_nop 0
	global_load_lds_dwordx4 v[218:219], off
	s_waitcnt vmcnt(8)
	s_waitcnt lgkmcnt(0)
	s_barrier
	s_waitcnt lgkmcnt(0)
	v_mfma_f32_16x16x32_bf16 v[124:127], v[128:131], v[160:163], v[124:127]
	v_mfma_f32_16x16x32_bf16 v[120:123], v[136:139], v[160:163], v[120:123]
	v_mfma_f32_16x16x32_bf16 v[116:119], v[128:131], v[168:171], v[116:119]
	v_mfma_f32_16x16x32_bf16 v[112:115], v[136:139], v[168:171], v[112:115]
	v_mfma_f32_16x16x32_bf16 v[108:111], v[128:131], v[176:179], v[108:111]
	v_mfma_f32_16x16x32_bf16 v[104:107], v[136:139], v[176:179], v[104:107]
	v_mfma_f32_16x16x32_bf16 v[100:103], v[128:131], v[188:191], v[100:103]
	v_mfma_f32_16x16x32_bf16 v[96:99], v[136:139], v[188:191], v[96:99]
	v_mfma_f32_16x16x32_bf16 v[124:127], v[132:135], v[164:167], v[124:127]
	v_mfma_f32_16x16x32_bf16 v[120:123], v[140:143], v[164:167], v[120:123]
	v_mfma_f32_16x16x32_bf16 v[116:119], v[132:135], v[172:175], v[116:119]
	v_mfma_f32_16x16x32_bf16 v[112:115], v[140:143], v[172:175], v[112:115]
	v_mfma_f32_16x16x32_bf16 v[108:111], v[132:135], v[180:183], v[108:111]
	v_mfma_f32_16x16x32_bf16 v[104:107], v[140:143], v[180:183], v[104:107]
	v_mfma_f32_16x16x32_bf16 v[100:103], v[132:135], v[196:199], v[100:103]
	v_mfma_f32_16x16x32_bf16 v[96:99], v[140:143], v[196:199], v[96:99]
	v_mfma_f32_16x16x32_bf16 v[92:95], v[144:147], v[160:163], v[92:95]
	v_mfma_f32_16x16x32_bf16 v[88:91], v[152:155], v[160:163], v[88:91]
	v_mfma_f32_16x16x32_bf16 v[84:87], v[144:147], v[168:171], v[84:87]
	v_mfma_f32_16x16x32_bf16 v[80:83], v[152:155], v[168:171], v[80:83]
	v_mfma_f32_16x16x32_bf16 v[76:79], v[144:147], v[176:179], v[76:79]
	v_mfma_f32_16x16x32_bf16 v[72:75], v[152:155], v[176:179], v[72:75]
	v_mfma_f32_16x16x32_bf16 v[68:71], v[144:147], v[188:191], v[68:71]
	v_mfma_f32_16x16x32_bf16 v[64:67], v[152:155], v[188:191], v[64:67]
	v_mfma_f32_16x16x32_bf16 v[92:95], v[148:151], v[164:167], v[92:95]
	v_mfma_f32_16x16x32_bf16 v[88:91], v[156:159], v[164:167], v[88:91]
	v_mfma_f32_16x16x32_bf16 v[84:87], v[148:151], v[172:175], v[84:87]
	v_mfma_f32_16x16x32_bf16 v[80:83], v[156:159], v[172:175], v[80:83]
	v_mfma_f32_16x16x32_bf16 v[76:79], v[148:151], v[180:183], v[76:79]
	v_mfma_f32_16x16x32_bf16 v[72:75], v[156:159], v[180:183], v[72:75]
	v_mfma_f32_16x16x32_bf16 v[68:71], v[148:151], v[196:199], v[68:71]
	v_mfma_f32_16x16x32_bf16 v[64:67], v[156:159], v[196:199], v[64:67]
	s_barrier
; #define PG8_STAGE(bufoff, gbase, voff) do { _Pragma("unroll") for (int _i = 0; _i < 2; ++_i) \
;         __builtin_amdgcn_global_load_lds((const unsigned*)((const char*)(gbase) + (voff)[_i]), (LAS unsigned*)(lds + (bufoff) + ldsw + _i * 8192), 16, 0, 0); } while (0)
; #define PG8_LDA(dst, b, h) do { _Pragma("unroll") for (int m = 0; m < 4; ++m) _Pragma("unroll") for (int k = 0; k < 2; ++k) dst[m][k] = *(const LAS bf16x8*)(lds + PG8_SA(b, h) + aoff + m * 2048 + k * 1024); } while (0)
; #define PG8_MMA(ai, bj, At, Bt) do { __builtin_amdgcn_s_setprio(1); _Pragma("unroll") for (int m = 0; m < 4; ++m) _Pragma("unroll") for (int n = 0; n < 2; ++n) _Pragma("unroll") for (int k = 0; k < 2; ++k) \
;         acc[ai][bj][m][n] = __builtin_amdgcn_mfma_f32_16x16x32_bf16(Bt[n][k], At[m][k], acc[ai][bj][m][n], 0, 0, 0); __builtin_amdgcn_s_setprio(0); } while (0)
; #define PG8_WAIT_V(n) asm volatile("s_waitcnt vmcnt(" #n ")" ::: "memory")
; #define PG8_WAIT_L(n) asm volatile("s_waitcnt lgkmcnt(" #n ")" ::: "memory")
; #define PG8_BAR __builtin_amdgcn_s_barrier()
; #define PG8_SCHED __builtin_amdgcn_sched_barrier(0)
; template <class Epi, class Sched>
; DI void gemm_phase(LAS unsigned char* lds, const int wv, const int lda, const int ldb, const Sched& S, const Epi& E) {
;     ...
;             PG8_LDA(At, 1, 1); PG8_STAGE(PG8_SB(1, 0), b3, voffB); PG8_STAGE(PG8_SB(1, 1), b3 + hstepB, voffB); PG8_STAGE(PG8_SA(1, 0), a3, voffA);
;             PG8_WAIT_V(8); PG8_WAIT_L(0); PG8_BAR; PG8_MMA(1, 0, At, B0); PG8_MMA(1, 1, At, B1); PG8_BAR; PG8_SCHED;
;         }
;         if (wr == 0) PG8_BAR;
	s_add_i32 s19, s19, s44
	v_lshl_add_u64 v[210:211], v[210:211], 0, s[28:29]
	s_mov_b32 m0, s19
	ds_read_b128 v[160:163], v235 offset:49152
	ds_read_b128 v[164:167], v235 offset:50176
	ds_read_b128 v[168:171], v235 offset:51200
	ds_read_b128 v[172:175], v235 offset:52224
	ds_read_b128 v[176:179], v235 offset:53248
	ds_read_b128 v[180:183], v235 offset:54272
	ds_read_b128 v[188:191], v235 offset:55296
	ds_read_b128 v[196:199], v235 offset:56320
	global_load_lds_dwordx4 v[210:211], off
	s_add_i32 m0, s19, 0x2000
	s_add_u32 s34, s34, 0x80080
	v_lshl_add_u64 v[210:211], v[212:213], 0, s[28:29]
	s_addc_u32 s35, s35, 0
	s_add_i32 s19, s40, s44
	global_load_lds_dwordx4 v[210:211], off
	v_lshl_add_u64 v[210:211], s[34:35], 0, v[184:185]
	s_mov_b32 m0, s19
	s_nop 0
	global_load_lds_dwordx4 v[210:211], off
	v_lshl_add_u64 v[210:211], s[34:35], 0, v[204:205]
	s_add_i32 m0, s19, 0x2000
	s_nop 0
	global_load_lds_dwordx4 v[210:211], off
	v_lshl_add_u64 v[210:211], v[214:215], 0, s[28:29]
	s_mov_b32 m0, s49
	s_nop 0
	global_load_lds_dwordx4 v[210:211], off
	v_lshl_add_u64 v[210:211], v[216:217], 0, s[28:29]
	s_mov_b32 m0, s50
	s_nop 0
	global_load_lds_dwordx4 v[210:211], off
	s_waitcnt vmcnt(8)
	s_waitcnt lgkmcnt(0)
	s_barrier
	s_waitcnt lgkmcnt(0)
	v_mfma_f32_16x16x32_bf16 v[60:63], v[128:131], v[160:163], v[60:63]
	v_mfma_f32_16x16x32_bf16 v[56:59], v[136:139], v[160:163], v[56:59]
	v_mfma_f32_16x16x32_bf16 v[52:55], v[128:131], v[168:171], v[52:55]
	v_mfma_f32_16x16x32_bf16 v[48:51], v[136:139], v[168:171], v[48:51]
	v_mfma_f32_16x16x32_bf16 v[44:47], v[128:131], v[176:179], v[44:47]
	v_mfma_f32_16x16x32_bf16 v[40:43], v[136:139], v[176:179], v[40:43]
	v_mfma_f32_16x16x32_bf16 v[36:39], v[128:131], v[188:191], v[36:39]
	v_mfma_f32_16x16x32_bf16 v[32:35], v[136:139], v[188:191], v[32:35]
	v_mfma_f32_16x16x32_bf16 v[60:63], v[132:135], v[164:167], v[60:63]
	v_mfma_f32_16x16x32_bf16 v[56:59], v[140:143], v[164:167], v[56:59]
	v_mfma_f32_16x16x32_bf16 v[52:55], v[132:135], v[172:175], v[52:55]
	v_mfma_f32_16x16x32_bf16 v[48:51], v[140:143], v[172:175], v[48:51]
	v_mfma_f32_16x16x32_bf16 v[44:47], v[132:135], v[180:183], v[44:47]
	v_mfma_f32_16x16x32_bf16 v[40:43], v[140:143], v[180:183], v[40:43]
	v_mfma_f32_16x16x32_bf16 v[36:39], v[132:135], v[196:199], v[36:39]
	v_mfma_f32_16x16x32_bf16 v[32:35], v[140:143], v[196:199], v[32:35]
	v_mfma_f32_16x16x32_bf16 v[28:31], v[144:147], v[160:163], v[28:31]
	v_mfma_f32_16x16x32_bf16 v[24:27], v[152:155], v[160:163], v[24:27]
	v_mfma_f32_16x16x32_bf16 v[20:23], v[144:147], v[168:171], v[20:23]
	v_mfma_f32_16x16x32_bf16 v[16:19], v[152:155], v[168:171], v[16:19]
	v_mfma_f32_16x16x32_bf16 v[12:15], v[144:147], v[176:179], v[12:15]
	v_mfma_f32_16x16x32_bf16 v[8:11], v[152:155], v[176:179], v[8:11]
	v_mfma_f32_16x16x32_bf16 v[4:7], v[144:147], v[188:191], v[4:7]
	v_mfma_f32_16x16x32_bf16 v[0:3], v[152:155], v[188:191], v[0:3]
	v_mfma_f32_16x16x32_bf16 v[28:31], v[148:151], v[164:167], v[28:31]
	v_mfma_f32_16x16x32_bf16 v[24:27], v[156:159], v[164:167], v[24:27]
	v_mfma_f32_16x16x32_bf16 v[20:23], v[148:151], v[172:175], v[20:23]
	v_mfma_f32_16x16x32_bf16 v[16:19], v[156:159], v[172:175], v[16:19]
	v_mfma_f32_16x16x32_bf16 v[12:15], v[148:151], v[180:183], v[12:15]
	v_mfma_f32_16x16x32_bf16 v[8:11], v[156:159], v[180:183], v[8:11]
	v_mfma_f32_16x16x32_bf16 v[4:7], v[148:151], v[196:199], v[4:7]
	v_mfma_f32_16x16x32_bf16 v[0:3], v[156:159], v[196:199], v[0:3]
	s_barrier
	s_add_u32 s6, s6, 0x100
	s_addc_u32 s7, s7, 0
	s_add_u32 s1, s1, 0x100
	s_addc_u32 s15, s15, 0
	s_cmp_ge_u32 s31, s27
	s_mov_b32 s19, s31
	s_cbranch_scc0 .LBB0_1185
	s_and_b64 vcc, exec, s[12:13]
	s_cbranch_vccz .LBB0_1188
	s_barrier

; DI int lane_id_fresh() { int l; asm volatile("v_mbcnt_lo_u32_b32 %0, -1, 0\n\tv_mbcnt_hi_u32_b32 %0, -1, %0" : "=v"(l)); return l; }
; #define SEAM(k) do { if (IN((k) + 1) && IN(k)) xcd_barrier(bar); } while (0)
; __device__ __forceinline__ void xcd_barrier(const XcdBarrier& b) {
;     asm volatile("s_waitcnt vmcnt(0)" ::: "memory");
;     __syncthreads();
;     if (b.w0 && lane_id_fresh() == 0) {
;         unsigned* bar = b.bar;
;         __builtin_amdgcn_s_waitcnt(0);
;         unsigned nloc = b.st[0], nx = b.st[1];
;         if (nloc == 0u) { xcd_barrier_complete(bar, b.x, nloc, nx); b.st[0] = nloc; b.st[1] = nx; }
; __global__ void __launch_bounds__(512, 2) trunk_fwd(Args args_unused) {
;     ...
;             SEAM(s0 + 7);
.LBB0_1226:
	s_setprio 0
	v_readlane_b32 s0, v254, 37
	s_add_i32 s17, s0, 9
	v_readlane_b32 s0, v252, 10
	v_readlane_b32 s3, v252, 13
	s_cmp_ge_i32 s17, s3
	v_readlane_b32 s1, v252, 11
	v_readlane_b32 s2, v252, 12
	s_cbranch_scc1 .LBB0_1239
	s_waitcnt vmcnt(0)
	v_readlane_b32 s0, v252, 5
	v_readlane_b32 s1, v252, 6
	s_and_b64 vcc, exec, s[0:1]
	s_movk_i32 s20, 0x5ff
	s_waitcnt lgkmcnt(0)
	s_barrier
	s_cbranch_vccnz .LBB0_1278
	v_mbcnt_lo_u32_b32 v0, -1, 0
	v_mbcnt_hi_u32_b32 v0, -1, v0
	s_nop 0
	v_cmp_eq_u32_e32 vcc, 0, v0
	s_and_saveexec_b64 s[2:3], vcc
	s_cbranch_execz .LBB0_1277
	v_readlane_b32 s0, v254, 5
	s_waitcnt vmcnt(0) expcnt(0) lgkmcnt(0)
	s_nop 0
	v_mov_b32_e32 v0, s0
	ds_read_b32 v2, v0
	v_readlane_b32 s0, v254, 6
	s_waitcnt lgkmcnt(0)
	v_cmp_ne_u32_e32 vcc, 0, v2
	v_mov_b32_e32 v0, s0
	ds_read_b32 v0, v0
	s_cbranch_vccnz .LBB0_1245
	v_readlane_b32 s4, v252, 7
	v_readlane_b32 s5, v252, 8
	s_load_dwordx2 s[0:1], s[4:5], 0x4
	s_mov_b32 s9, 1
	s_waitcnt lgkmcnt(0)
	s_mul_i32 s8, s0, s16
	s_mul_i32 s8, s8, s1
	s_branch .LBB0_1232

;     DI void init(const bf16* A_, int lda, const bf16* B_, int ldb, int nM, int nN, int K, int G_, int c_) { T.init(nM, nN); G = G_; c = c_; nt = K / BK; A = (const char*)A_; B = (const char*)B_; ta = (size_t)BM * lda * 2; tb = (size_t)BM * ldb * 2; }
;     DI void init(const bf16* A_, int lda, const bf16* B_, int ldb, int nM, int nN, int G_, int c_) { T.init(nM, nN); G = G_; c = c_; A = (const char*)A_; B = (const char*)B_; ta = (size_t)BM * lda * 2; tb = (size_t)BM * ldb * 2; }
;     DI const char* aptr(const Unit& u) const { return A + (size_t)u.pm * ta + (size_t)kofs(u.seg) * 2; }
;     DI const char* bptr(const Unit& u) const { return B + (size_t)u.pn * tb + (size_t)kofs(u.seg) * 2; }
; #define PG8_STAGE(bufoff, gbase, voff) do { _Pragma("unroll") for (int _i = 0; _i < 2; ++_i) \
;         __builtin_amdgcn_global_load_lds((const unsigned*)((const char*)(gbase) + (voff)[_i]), (LAS unsigned*)(lds + (bufoff) + ldsw + _i * 8192), 16, 0, 0); } while (0)
; #define PG8_WAIT_V(n) asm volatile("s_waitcnt vmcnt(" #n ")" ::: "memory")
; #define PG8_BAR __builtin_amdgcn_s_barrier()
; #define SEAM(k) do { if (IN((k) + 1) && IN(k)) xcd_barrier(bar); } while (0)
; #define FRAME() const CAS Args* ap; const Frame F = make_frame(lds, ap, wv); const CAS Args& A = *ap; (void)A
; template <class Epi, class Sched>
; DI void gemm_phase(LAS unsigned char* lds, const int wv, const int lda, const int ldb, const Sched& S, const Epi& E) {
;     ...
;     const char* cA = S.aptr(cur); const char* cB = S.bptr(cur); int nt = S.ntiles(cur);
;     PG8_STAGE(PG8_SB(0, 0), cB, voffB); PG8_STAGE(PG8_SB(0, 1), cB + hstepB, voffB); PG8_STAGE(PG8_SA(0, 0), cA, voffA); PG8_STAGE(PG8_SA(0, 1), cA + hstepA, voffA);
;     if (wr == 1) PG8_BAR;
;     PG8_WAIT_V(2); PG8_BAR;
;     PG8_STAGE(PG8_SB(1, 0), cB + kstep, voffB); PG8_STAGE(PG8_SA(1, 0), cA + kstep, voffA); PG8_STAGE(PG8_SB(1, 1), cB + hstepB + kstep, voffB);
;     PG8_WAIT_V(6); PG8_BAR;
; __global__ void __launch_bounds__(512, 2) trunk_fwd(Args args_unused) {
;     ...
;         if (PHEN(8) && IN(s0 + 8)) { FRAME();
;             SchedPlain S; S.init((const bf16*)(F.ws + WS_R1), D, (const bf16*)lw(F, l, LW_WOUT), D, M / BM, D / BM, D, F.G, F.bid);
;             EpiResid E{(const bf16*)F.out, (bf16*)F.out, (float*)(F.ws + WS_SSQ)};
;             gemm_phase<EpiResid, SchedPlain>(F.lds, F.wave, D, D, S, E);
;             SEAM(s0 + 8);
.LBB0_1289:
	v_and_b32_e32 v15, 15, v14
	v_bfe_u32 v14, v14, 4, 2
	v_lshlrev_b32_e32 v17, 4, v14
	v_lshl_or_b32 v154, s1, 6, v15
	v_lshl_or_b32 v17, v15, 6, v17
	v_lshlrev_b32_e32 v15, 2, v15
	s_and_b32 s7, s0, 3
	s_lshl_b32 s0, s1, 13
	v_and_b32_e32 v18, 32, v15
	s_add_i32 m0, s27, 0x18000
	v_lshl_add_u64 v[6:7], v[6:7], 0, s[28:29]
	v_bitop3_b32 v19, v17, s0, v18 bitop3:0xde
	s_lshl_b32 s0, s7, 12
	s_waitcnt vmcnt(2)
	s_barrier
	global_load_lds_dwordx4 v[6:7], off
	v_lshl_add_u64 v[4:5], v[4:5], 0, s[28:29]
	s_add_i32 m0, s27, 0x1a000
	s_add_i32 s45, s27, 0x8000
	s_add_i32 s46, s27, 0xa000
	v_bitop3_b32 v155, v17, s0, v18 bitop3:0xde
	global_load_lds_dwordx4 v[4:5], off
	v_lshl_add_u64 v[0:1], v[0:1], 0, s[28:29]
	s_mov_b32 m0, s45
	s_add_u32 s0, s34, 0x80080
	global_load_lds_dwordx4 v[0:1], off
	v_lshl_add_u64 v[0:1], v[2:3], 0, s[28:29]
	s_mov_b32 m0, s46
	s_addc_u32 s1, s35, 0
	global_load_lds_dwordx4 v[0:1], off
	s_add_i32 m0, s27, 0x1c000
	v_lshl_add_u64 v[0:1], s[0:1], 0, v[184:185]
	global_load_lds_dwordx4 v[0:1], off
	v_lshl_add_u64 v[0:1], s[0:1], 0, v[136:137]
	s_add_i32 m0, s27, 0x1e000
	s_movk_i32 s0, 0x80
	global_load_lds_dwordx4 v[0:1], off
	v_lshlrev_b32_e32 v0, 6, v14
	v_bitop3_b32 v157, v0, 64, v15 bitop3:0x36
	v_bitop3_b32 v158, v0, s0, v15 bitop3:0x36
	v_lshlrev_b32_e32 v0, 15, v8
	v_and_b32_e32 v0, 0xffff0000, v0
	v_lshl_add_u32 v0, v9, 12, v0
	v_and_b32_e32 v1, 1, v8
	s_cmpk_lt_u32 s6, 0x100
	v_lshl_or_b32 v0, v1, 6, v0
	s_cselect_b64 s[12:13], -1, 0
	s_ashr_i32 s48, s20, 31
	s_ashr_i32 s49, s17, 31
	s_lshl_b32 s0, s7, 2
	v_lshl_add_u32 v138, v10, 1, v0
	v_lshlrev_b32_e32 v0, 15, v11
	s_add_u32 s0, s10, s0
	v_and_b32_e32 v0, 0xffff0000, v0
	s_waitcnt vmcnt(6)
	s_addc_u32 s1, s11, 0
	v_lshl_add_u32 v0, v12, 12, v0
	v_and_b32_e32 v1, 1, v11
	v_lshlrev_b32_e32 v16, 3, v14
	s_add_u32 s50, s0, 0x49c28000
	v_lshl_or_b32 v0, v1, 6, v0
	v_lshl_or_b32 v156, s7, 5, v16
	s_mov_b32 s47, 0
	v_cmp_eq_u32_e64 s[4:5], 0, v14
	s_addc_u32 s51, s1, 0
	v_mov_b32_e32 v139, v185
	v_lshl_add_u32 v140, v13, 1, v0
	v_mov_b32_e32 v141, v185
	v_add_u32_e32 v159, 0, v19
	s_barrier
	v_mbcnt_lo_u32_b32 v248, -1, 0
	v_mbcnt_hi_u32_b32 v248, -1, v248
	s_lshl_b32 s98, s90, 10
	s_add_i32 s98, s98, 0x22000
	v_lshl_add_u32 v246, v248, 4, s98
	v_and_b32_e32 v249, 15, v248
	v_lshrrev_b32_e32 v242, 4, v248
	v_lshrrev_b32_e32 v243, 2, v249
	v_lshl_add_u32 v242, v243, 4, v242
	v_and_b32_e32 v243, 3, v249
	v_lshl_add_u32 v242, v243, 2, v242
	v_lshl_add_u32 v247, v242, 4, s98
	v_lshrrev_b32_e32 v242, 4, v248
	v_bfe_u32 v243, v248, 2, 2
	v_lshl_add_u32 v243, v242, 2, v243
	v_sub_u32_e32 v243, v243, v249
	v_and_b32_e32 v249, 3, v248
	v_sub_u32_e32 v249, v249, v242
	v_lshlrev_b32_e32 v249, 4, v249
	s_movk_i32 s98, 0x1000
	v_mad_i32_i24 v240, v243, s98, v249
	v_ashrrev_i32_e32 v241, 31, v240
	s_cmp_ge_u32 s90, 4
	s_cbranch_scc0 .Lprio_1292_done
	s_setprio 1

; #define PG8_STAGE(bufoff, gbase, voff) do { _Pragma("unroll") for (int _i = 0; _i < 2; ++_i) \
;         __builtin_amdgcn_global_load_lds((const unsigned*)((const char*)(gbase) + (voff)[_i]), (LAS unsigned*)(lds + (bufoff) + ldsw + _i * 8192), 16, 0, 0); } while (0)
; #define PG8_LDA(dst, b, h) do { _Pragma("unroll") for (int m = 0; m < 4; ++m) _Pragma("unroll") for (int k = 0; k < 2; ++k) dst[m][k] = *(const LAS bf16x8*)(lds + PG8_SA(b, h) + aoff + m * 2048 + k * 1024); } while (0)
; #define PG8_LDB(dst, b, h) do { _Pragma("unroll") for (int n = 0; n < 2; ++n) _Pragma("unroll") for (int k = 0; k < 2; ++k) dst[n][k] = *(const LAS bf16x8*)(lds + PG8_SB(b, h) + boff + n * 2048 + k * 1024); } while (0)
; #define PG8_MMA(ai, bj, At, Bt) do { __builtin_amdgcn_s_setprio(1); _Pragma("unroll") for (int m = 0; m < 4; ++m) _Pragma("unroll") for (int n = 0; n < 2; ++n) _Pragma("unroll") for (int k = 0; k < 2; ++k) \
;         acc[ai][bj][m][n] = __builtin_amdgcn_mfma_f32_16x16x32_bf16(Bt[n][k], At[m][k], acc[ai][bj][m][n], 0, 0, 0); __builtin_amdgcn_s_setprio(0); } while (0)
; #define PG8_WAIT_V(n) asm volatile("s_waitcnt vmcnt(" #n ")" ::: "memory")
; #define PG8_WAIT_L(n) asm volatile("s_waitcnt lgkmcnt(" #n ")" ::: "memory")
; #define PG8_BAR __builtin_amdgcn_s_barrier()
; #define PG8_SCHED __builtin_amdgcn_sched_barrier(0)
; template <class Epi, class Sched>
; DI void gemm_phase(LAS unsigned char* lds, const int wv, const int lda, const int ldb, const Sched& S, const Epi& E) {
;     ...
;             const char* a1 = cA + (size_t)(t + 1) * kstep;
;             const char* a2 = last ? nA : cA + (size_t)(t + 2) * kstep; const char* b2 = last ? nB : cB + (size_t)(t + 2) * kstep;
;             const char* a3 = a2 + kstep; const char* b3 = b2 + kstep;
;             PG8_LDB(B0, 0, 0); PG8_LDB(B1, 0, 1); PG8_SCHED; PG8_LDA(At, 0, 0); PG8_STAGE(PG8_SA(1, 1), a1 + hstepA, voffA);
;             PG8_WAIT_V(8); PG8_WAIT_L(0); PG8_BAR; PG8_MMA(0, 0, At, B0); PG8_MMA(0, 1, At, B1); PG8_BAR; PG8_SCHED;
;             PG8_LDA(At, 0, 1); PG8_STAGE(PG8_SB(0, 0), b2, voffB); PG8_STAGE(PG8_SB(0, 1), b2 + hstepB, voffB); PG8_STAGE(PG8_SA(0, 0), a2, voffA);
;             PG8_WAIT_V(8); PG8_WAIT_L(0); PG8_BAR; PG8_MMA(1, 0, At, B0); PG8_MMA(1, 1, At, B1); PG8_BAR; PG8_SCHED;
.LBB0_1299:
	s_add_u32 s34, s30, 0xfff80080
	s_addc_u32 s35, s31, -1
	s_add_i32 s54, 0, 0x10000
	s_cmp_eq_u32 s53, 28
	s_cselect_b32 s37, s0, s35
	s_cselect_b32 s36, s1, s34
	s_cselect_b32 s35, s11, s52
	s_cselect_b32 s34, s15, s19
	s_add_i32 s56, 0, 0x14000
	v_add_u32_e32 v150, s54, v155
	v_add_u32_e32 v172, s56, v155
	ds_read_b128 v[128:131], v150
	ds_read_b128 v[142:145], v150 offset:1024
	ds_read_b128 v[146:149], v150 offset:2048
	ds_read_b128 v[150:153], v150 offset:3072
	ds_read_b128 v[160:163], v172
	ds_read_b128 v[164:167], v172 offset:1024
	ds_read_b128 v[168:171], v172 offset:2048
	ds_read_b128 v[172:175], v172 offset:3072
	v_lshl_add_u64 v[216:217], s[30:31], 0, v[138:139]
	s_add_i32 m0, s27, 0xc000
	ds_read_b128 v[176:179], v159
	ds_read_b128 v[180:183], v159 offset:1024
	ds_read_b128 v[188:191], v159 offset:2048
	ds_read_b128 v[196:199], v159 offset:3072
	ds_read_b128 v[200:203], v159 offset:4096
	ds_read_b128 v[204:207], v159 offset:5120
	ds_read_b128 v[208:211], v159 offset:6144
	ds_read_b128 v[212:215], v159 offset:7168
	global_load_lds_dwordx4 v[216:217], off
	v_lshl_add_u64 v[216:217], s[30:31], 0, v[140:141]
	s_add_i32 m0, s27, 0xe000
	s_nop 0
	global_load_lds_dwordx4 v[216:217], off
	s_waitcnt vmcnt(8)
	s_waitcnt lgkmcnt(0)
	s_barrier
	s_waitcnt lgkmcnt(0)
	v_mfma_f32_16x16x32_bf16 v[124:127], v[128:131], v[176:179], v[124:127]
	v_mfma_f32_16x16x32_bf16 v[120:123], v[146:149], v[176:179], v[120:123]
	v_mfma_f32_16x16x32_bf16 v[108:111], v[128:131], v[188:191], v[108:111]
	v_mfma_f32_16x16x32_bf16 v[104:107], v[146:149], v[188:191], v[104:107]
	v_mfma_f32_16x16x32_bf16 v[96:99], v[128:131], v[200:203], v[96:99]
	v_mfma_f32_16x16x32_bf16 v[88:91], v[146:149], v[200:203], v[88:91]
	v_mfma_f32_16x16x32_bf16 v[80:83], v[128:131], v[208:211], v[80:83]
	v_mfma_f32_16x16x32_bf16 v[72:75], v[146:149], v[208:211], v[72:75]
	v_mfma_f32_16x16x32_bf16 v[124:127], v[142:145], v[180:183], v[124:127]
	v_mfma_f32_16x16x32_bf16 v[120:123], v[150:153], v[180:183], v[120:123]
	v_mfma_f32_16x16x32_bf16 v[108:111], v[142:145], v[196:199], v[108:111]
	v_mfma_f32_16x16x32_bf16 v[104:107], v[150:153], v[196:199], v[104:107]
	v_mfma_f32_16x16x32_bf16 v[96:99], v[142:145], v[204:207], v[96:99]
	v_mfma_f32_16x16x32_bf16 v[88:91], v[150:153], v[204:207], v[88:91]
	v_mfma_f32_16x16x32_bf16 v[80:83], v[142:145], v[212:215], v[80:83]
	v_mfma_f32_16x16x32_bf16 v[72:75], v[150:153], v[212:215], v[72:75]
	v_mfma_f32_16x16x32_bf16 v[116:119], v[160:163], v[176:179], v[116:119]
	v_mfma_f32_16x16x32_bf16 v[112:115], v[168:171], v[176:179], v[112:115]
	v_mfma_f32_16x16x32_bf16 v[100:103], v[160:163], v[188:191], v[100:103]
	v_mfma_f32_16x16x32_bf16 v[92:95], v[168:171], v[188:191], v[92:95]
	v_mfma_f32_16x16x32_bf16 v[84:87], v[160:163], v[200:203], v[84:87]
	v_mfma_f32_16x16x32_bf16 v[76:79], v[168:171], v[200:203], v[76:79]
	v_mfma_f32_16x16x32_bf16 v[68:71], v[160:163], v[208:211], v[68:71]
	v_mfma_f32_16x16x32_bf16 v[64:67], v[168:171], v[208:211], v[64:67]
	v_mfma_f32_16x16x32_bf16 v[116:119], v[164:167], v[180:183], v[116:119]
	v_mfma_f32_16x16x32_bf16 v[112:115], v[172:175], v[180:183], v[112:115]
	v_mfma_f32_16x16x32_bf16 v[100:103], v[164:167], v[196:199], v[100:103]
	v_mfma_f32_16x16x32_bf16 v[92:95], v[172:175], v[196:199], v[92:95]
	v_mfma_f32_16x16x32_bf16 v[84:87], v[164:167], v[204:207], v[84:87]
	v_mfma_f32_16x16x32_bf16 v[76:79], v[172:175], v[204:207], v[76:79]
	v_mfma_f32_16x16x32_bf16 v[68:71], v[164:167], v[212:215], v[68:71]
	v_mfma_f32_16x16x32_bf16 v[64:67], v[172:175], v[212:215], v[64:67]
	s_barrier
	s_add_i32 s54, s54, s41
	v_lshl_add_u64 v[216:217], s[34:35], 0, v[184:185]
	s_mov_b32 m0, s54
	ds_read_b128 v[176:179], v159 offset:16384
	ds_read_b128 v[180:183], v159 offset:17408
	ds_read_b128 v[188:191], v159 offset:18432
	ds_read_b128 v[196:199], v159 offset:19456
	ds_read_b128 v[200:203], v159 offset:20480
	ds_read_b128 v[204:207], v159 offset:21504
	ds_read_b128 v[208:211], v159 offset:22528
	ds_read_b128 v[212:215], v159 offset:23552
	global_load_lds_dwordx4 v[216:217], off
	s_add_i32 m0, s54, 0x2000
	s_add_u32 s54, s34, 0x80000
	v_lshl_add_u64 v[218:219], s[34:35], 0, v[136:137]
	s_addc_u32 s55, s35, 0
	s_add_i32 s56, s56, s41
	global_load_lds_dwordx4 v[218:219], off
	v_lshl_add_u64 v[220:221], s[54:55], 0, v[184:185]
	s_mov_b32 m0, s56
	v_lshl_add_u64 v[222:223], s[36:37], 0, v[134:135]
	global_load_lds_dwordx4 v[220:221], off
	v_lshl_add_u64 v[220:221], s[54:55], 0, v[136:137]
	s_add_i32 m0, s56, 0x2000
	s_nop 0
	global_load_lds_dwordx4 v[220:221], off
	v_lshl_add_u64 v[220:221], s[36:37], 0, v[132:133]
	s_mov_b32 m0, s27
	s_nop 0
	global_load_lds_dwordx4 v[220:221], off
	s_mov_b32 m0, s42
	s_nop 0
	global_load_lds_dwordx4 v[222:223], off
	s_waitcnt vmcnt(8)
	s_waitcnt lgkmcnt(0)
	s_barrier
; #define PG8_STAGE(bufoff, gbase, voff) do { _Pragma("unroll") for (int _i = 0; _i < 2; ++_i) \
;         __builtin_amdgcn_global_load_lds((const unsigned*)((const char*)(gbase) + (voff)[_i]), (LAS unsigned*)(lds + (bufoff) + ldsw + _i * 8192), 16, 0, 0); } while (0)
; #define PG8_LDA(dst, b, h) do { _Pragma("unroll") for (int m = 0; m < 4; ++m) _Pragma("unroll") for (int k = 0; k < 2; ++k) dst[m][k] = *(const LAS bf16x8*)(lds + PG8_SA(b, h) + aoff + m * 2048 + k * 1024); } while (0)
; #define PG8_LDB(dst, b, h) do { _Pragma("unroll") for (int n = 0; n < 2; ++n) _Pragma("unroll") for (int k = 0; k < 2; ++k) dst[n][k] = *(const LAS bf16x8*)(lds + PG8_SB(b, h) + boff + n * 2048 + k * 1024); } while (0)
; #define PG8_MMA(ai, bj, At, Bt) do { __builtin_amdgcn_s_setprio(1); _Pragma("unroll") for (int m = 0; m < 4; ++m) _Pragma("unroll") for (int n = 0; n < 2; ++n) _Pragma("unroll") for (int k = 0; k < 2; ++k) \
;         acc[ai][bj][m][n] = __builtin_amdgcn_mfma_f32_16x16x32_bf16(Bt[n][k], At[m][k], acc[ai][bj][m][n], 0, 0, 0); __builtin_amdgcn_s_setprio(0); } while (0)
; #define PG8_WAIT_V(n) asm volatile("s_waitcnt vmcnt(" #n ")" ::: "memory")
; #define PG8_WAIT_L(n) asm volatile("s_waitcnt lgkmcnt(" #n ")" ::: "memory")
; #define PG8_BAR __builtin_amdgcn_s_barrier()
; #define PG8_SCHED __builtin_amdgcn_sched_barrier(0)
; template <class Epi, class Sched>
; DI void gemm_phase(LAS unsigned char* lds, const int wv, const int lda, const int ldb, const Sched& S, const Epi& E) {
;     ...
;             PG8_WAIT_V(8); PG8_WAIT_L(0); PG8_BAR; PG8_MMA(1, 0, At, B0); PG8_MMA(1, 1, At, B1); PG8_BAR; PG8_SCHED;
;             PG8_LDB(B0, 1, 0); PG8_LDB(B1, 1, 1); PG8_SCHED; PG8_LDA(At, 1, 0); PG8_STAGE(PG8_SA(0, 1), a2 + hstepA, voffA);
;             PG8_WAIT_V(8); PG8_WAIT_L(0); PG8_BAR; PG8_MMA(0, 0, At, B0); PG8_MMA(0, 1, At, B1); PG8_BAR; PG8_SCHED;
	s_waitcnt lgkmcnt(0)
	v_mfma_f32_16x16x32_bf16 v[60:63], v[128:131], v[176:179], v[60:63]
	v_mfma_f32_16x16x32_bf16 v[56:59], v[146:149], v[176:179], v[56:59]
	v_mfma_f32_16x16x32_bf16 v[48:51], v[128:131], v[188:191], v[48:51]
	v_mfma_f32_16x16x32_bf16 v[40:43], v[146:149], v[188:191], v[40:43]
	v_mfma_f32_16x16x32_bf16 v[32:35], v[128:131], v[200:203], v[32:35]
	v_mfma_f32_16x16x32_bf16 v[24:27], v[146:149], v[200:203], v[24:27]
	v_mfma_f32_16x16x32_bf16 v[16:19], v[128:131], v[208:211], v[16:19]
	v_mfma_f32_16x16x32_bf16 v[8:11], v[146:149], v[208:211], v[8:11]
	v_mfma_f32_16x16x32_bf16 v[60:63], v[142:145], v[180:183], v[60:63]
	v_mfma_f32_16x16x32_bf16 v[56:59], v[150:153], v[180:183], v[56:59]
	v_mfma_f32_16x16x32_bf16 v[48:51], v[142:145], v[196:199], v[48:51]
	v_mfma_f32_16x16x32_bf16 v[40:43], v[150:153], v[196:199], v[40:43]
	v_mfma_f32_16x16x32_bf16 v[32:35], v[142:145], v[204:207], v[32:35]
	v_mfma_f32_16x16x32_bf16 v[24:27], v[150:153], v[204:207], v[24:27]
	v_mfma_f32_16x16x32_bf16 v[16:19], v[142:145], v[212:215], v[16:19]
	v_mfma_f32_16x16x32_bf16 v[8:11], v[150:153], v[212:215], v[8:11]
	v_mfma_f32_16x16x32_bf16 v[52:55], v[160:163], v[176:179], v[52:55]
	v_mfma_f32_16x16x32_bf16 v[44:47], v[168:171], v[176:179], v[44:47]
	v_mfma_f32_16x16x32_bf16 v[36:39], v[160:163], v[188:191], v[36:39]
	v_mfma_f32_16x16x32_bf16 v[28:31], v[168:171], v[188:191], v[28:31]
	v_mfma_f32_16x16x32_bf16 v[20:23], v[160:163], v[200:203], v[20:23]
	v_mfma_f32_16x16x32_bf16 v[12:15], v[168:171], v[200:203], v[12:15]
	v_mfma_f32_16x16x32_bf16 v[4:7], v[160:163], v[208:211], v[4:7]
	v_mfma_f32_16x16x32_bf16 v[0:3], v[168:171], v[208:211], v[0:3]
	v_mfma_f32_16x16x32_bf16 v[52:55], v[164:167], v[180:183], v[52:55]
	v_mfma_f32_16x16x32_bf16 v[44:47], v[172:175], v[180:183], v[44:47]
	v_mfma_f32_16x16x32_bf16 v[36:39], v[164:167], v[196:199], v[36:39]
	v_mfma_f32_16x16x32_bf16 v[28:31], v[172:175], v[196:199], v[28:31]
	v_mfma_f32_16x16x32_bf16 v[20:23], v[164:167], v[204:207], v[20:23]
	v_mfma_f32_16x16x32_bf16 v[12:15], v[172:175], v[204:207], v[12:15]
	v_mfma_f32_16x16x32_bf16 v[4:7], v[164:167], v[212:215], v[4:7]
	v_mfma_f32_16x16x32_bf16 v[0:3], v[172:175], v[212:215], v[0:3]
	s_barrier
	s_add_i32 s54, 0, 0x18000
	s_add_i32 s55, 0, 0x1c000
	v_add_u32_e32 v150, s54, v155
	v_add_u32_e32 v172, s55, v155
	ds_read_b128 v[128:131], v150
	ds_read_b128 v[142:145], v150 offset:1024
	ds_read_b128 v[146:149], v150 offset:2048
	ds_read_b128 v[150:153], v150 offset:3072
	ds_read_b128 v[160:163], v172
	ds_read_b128 v[164:167], v172 offset:1024
	ds_read_b128 v[168:171], v172 offset:2048
	ds_read_b128 v[172:175], v172 offset:3072
	s_add_u32 s36, s36, 0x80000
	s_addc_u32 s37, s37, 0
	s_mov_b32 m0, s43
	v_lshl_add_u64 v[234:235], s[36:37], 0, v[132:133]
	ds_read_b128 v[176:179], v159 offset:32768
	ds_read_b128 v[180:183], v159 offset:33792
	ds_read_b128 v[188:191], v159 offset:34816
	ds_read_b128 v[196:199], v159 offset:35840
	ds_read_b128 v[200:203], v159 offset:36864
	ds_read_b128 v[204:207], v159 offset:37888
	ds_read_b128 v[208:211], v159 offset:38912
	ds_read_b128 v[212:215], v159 offset:39936
	global_load_lds_dwordx4 v[234:235], off
	v_lshl_add_u64 v[234:235], s[36:37], 0, v[134:135]
	s_mov_b32 m0, s44
	s_nop 0
	global_load_lds_dwordx4 v[234:235], off
	s_waitcnt vmcnt(8)
	s_waitcnt lgkmcnt(0)
	s_barrier
	s_waitcnt lgkmcnt(0)
	v_mfma_f32_16x16x32_bf16 v[124:127], v[128:131], v[176:179], v[124:127]
	v_mfma_f32_16x16x32_bf16 v[120:123], v[146:149], v[176:179], v[120:123]
	v_mfma_f32_16x16x32_bf16 v[108:111], v[128:131], v[188:191], v[108:111]
	v_mfma_f32_16x16x32_bf16 v[104:107], v[146:149], v[188:191], v[104:107]
	v_mfma_f32_16x16x32_bf16 v[96:99], v[128:131], v[200:203], v[96:99]
	v_mfma_f32_16x16x32_bf16 v[88:91], v[146:149], v[200:203], v[88:91]
	v_mfma_f32_16x16x32_bf16 v[80:83], v[128:131], v[208:211], v[80:83]
	v_mfma_f32_16x16x32_bf16 v[72:75], v[146:149], v[208:211], v[72:75]
	v_mfma_f32_16x16x32_bf16 v[124:127], v[142:145], v[180:183], v[124:127]
	v_mfma_f32_16x16x32_bf16 v[120:123], v[150:153], v[180:183], v[120:123]
	v_mfma_f32_16x16x32_bf16 v[108:111], v[142:145], v[196:199], v[108:111]
	v_mfma_f32_16x16x32_bf16 v[104:107], v[150:153], v[196:199], v[104:107]
	v_mfma_f32_16x16x32_bf16 v[96:99], v[142:145], v[204:207], v[96:99]
	v_mfma_f32_16x16x32_bf16 v[88:91], v[150:153], v[204:207], v[88:91]
	v_mfma_f32_16x16x32_bf16 v[80:83], v[142:145], v[212:215], v[80:83]
	v_mfma_f32_16x16x32_bf16 v[72:75], v[150:153], v[212:215], v[72:75]
	v_mfma_f32_16x16x32_bf16 v[116:119], v[160:163], v[176:179], v[116:119]
	v_mfma_f32_16x16x32_bf16 v[112:115], v[168:171], v[176:179], v[112:115]
	v_mfma_f32_16x16x32_bf16 v[100:103], v[160:163], v[188:191], v[100:103]
	v_mfma_f32_16x16x32_bf16 v[92:95], v[168:171], v[188:191], v[92:95]
	v_mfma_f32_16x16x32_bf16 v[84:87], v[160:163], v[200:203], v[84:87]
	v_mfma_f32_16x16x32_bf16 v[76:79], v[168:171], v[200:203], v[76:79]
	v_mfma_f32_16x16x32_bf16 v[68:71], v[160:163], v[208:211], v[68:71]
	v_mfma_f32_16x16x32_bf16 v[64:67], v[168:171], v[208:211], v[64:67]
	v_mfma_f32_16x16x32_bf16 v[116:119], v[164:167], v[180:183], v[116:119]
	v_mfma_f32_16x16x32_bf16 v[112:115], v[172:175], v[180:183], v[112:115]
	v_mfma_f32_16x16x32_bf16 v[100:103], v[164:167], v[196:199], v[100:103]
	v_mfma_f32_16x16x32_bf16 v[92:95], v[172:175], v[196:199], v[92:95]
	v_mfma_f32_16x16x32_bf16 v[84:87], v[164:167], v[204:207], v[84:87]
	v_mfma_f32_16x16x32_bf16 v[76:79], v[172:175], v[204:207], v[76:79]
	v_mfma_f32_16x16x32_bf16 v[68:71], v[164:167], v[212:215], v[68:71]
	v_mfma_f32_16x16x32_bf16 v[64:67], v[172:175], v[212:215], v[64:67]
	s_barrier
; #define PG8_STAGE(bufoff, gbase, voff) do { _Pragma("unroll") for (int _i = 0; _i < 2; ++_i) \
;         __builtin_amdgcn_global_load_lds((const unsigned*)((const char*)(gbase) + (voff)[_i]), (LAS unsigned*)(lds + (bufoff) + ldsw + _i * 8192), 16, 0, 0); } while (0)
; #define PG8_LDA(dst, b, h) do { _Pragma("unroll") for (int m = 0; m < 4; ++m) _Pragma("unroll") for (int k = 0; k < 2; ++k) dst[m][k] = *(const LAS bf16x8*)(lds + PG8_SA(b, h) + aoff + m * 2048 + k * 1024); } while (0)
; #define PG8_MMA(ai, bj, At, Bt) do { __builtin_amdgcn_s_setprio(1); _Pragma("unroll") for (int m = 0; m < 4; ++m) _Pragma("unroll") for (int n = 0; n < 2; ++n) _Pragma("unroll") for (int k = 0; k < 2; ++k) \
;         acc[ai][bj][m][n] = __builtin_amdgcn_mfma_f32_16x16x32_bf16(Bt[n][k], At[m][k], acc[ai][bj][m][n], 0, 0, 0); __builtin_amdgcn_s_setprio(0); } while (0)
; #define PG8_WAIT_V(n) asm volatile("s_waitcnt vmcnt(" #n ")" ::: "memory")
; #define PG8_WAIT_L(n) asm volatile("s_waitcnt lgkmcnt(" #n ")" ::: "memory")
; #define PG8_BAR __builtin_amdgcn_s_barrier()
; #define PG8_SCHED __builtin_amdgcn_sched_barrier(0)
; template <class Epi, class Sched>
; DI void gemm_phase(LAS unsigned char* lds, const int wv, const int lda, const int ldb, const Sched& S, const Epi& E) {
;     ...
;             PG8_LDA(At, 1, 1); PG8_STAGE(PG8_SB(1, 0), b3, voffB); PG8_STAGE(PG8_SB(1, 1), b3 + hstepB, voffB); PG8_STAGE(PG8_SA(1, 0), a3, voffA);
;             PG8_WAIT_V(8); PG8_WAIT_L(0); PG8_BAR; PG8_MMA(1, 0, At, B0); PG8_MMA(1, 1, At, B1); PG8_BAR; PG8_SCHED;
;         }
;         if (wr == 0) PG8_BAR;
	s_add_i32 s36, s54, s41
	v_lshl_add_u64 v[216:217], v[216:217], 0, s[28:29]
	s_mov_b32 m0, s36
	ds_read_b128 v[176:179], v159 offset:49152
	ds_read_b128 v[180:183], v159 offset:50176
	ds_read_b128 v[188:191], v159 offset:51200
	ds_read_b128 v[196:199], v159 offset:52224
	ds_read_b128 v[200:203], v159 offset:53248
	ds_read_b128 v[204:207], v159 offset:54272
	ds_read_b128 v[208:211], v159 offset:55296
	ds_read_b128 v[212:215], v159 offset:56320
	global_load_lds_dwordx4 v[216:217], off
	s_add_i32 m0, s36, 0x2000
	s_add_u32 s34, s34, 0x80080
	v_lshl_add_u64 v[216:217], v[218:219], 0, s[28:29]
	s_addc_u32 s35, s35, 0
	s_add_i32 s36, s55, s41
	global_load_lds_dwordx4 v[216:217], off
	v_lshl_add_u64 v[216:217], s[34:35], 0, v[184:185]
	s_mov_b32 m0, s36
	s_nop 0
	global_load_lds_dwordx4 v[216:217], off
	v_lshl_add_u64 v[216:217], s[34:35], 0, v[136:137]
	s_add_i32 m0, s36, 0x2000
	s_nop 0
	global_load_lds_dwordx4 v[216:217], off
	v_lshl_add_u64 v[216:217], v[220:221], 0, s[28:29]
	s_mov_b32 m0, s45
	s_nop 0
	global_load_lds_dwordx4 v[216:217], off
	v_lshl_add_u64 v[216:217], v[222:223], 0, s[28:29]
	s_mov_b32 m0, s46
	s_nop 0
	global_load_lds_dwordx4 v[216:217], off
	s_waitcnt vmcnt(8)
	s_waitcnt lgkmcnt(0)
	s_barrier
	s_waitcnt lgkmcnt(0)
	v_mfma_f32_16x16x32_bf16 v[60:63], v[128:131], v[176:179], v[60:63]
	v_mfma_f32_16x16x32_bf16 v[56:59], v[146:149], v[176:179], v[56:59]
	v_mfma_f32_16x16x32_bf16 v[48:51], v[128:131], v[188:191], v[48:51]
	v_mfma_f32_16x16x32_bf16 v[40:43], v[146:149], v[188:191], v[40:43]
	v_mfma_f32_16x16x32_bf16 v[32:35], v[128:131], v[200:203], v[32:35]
	v_mfma_f32_16x16x32_bf16 v[24:27], v[146:149], v[200:203], v[24:27]
	v_mfma_f32_16x16x32_bf16 v[16:19], v[128:131], v[208:211], v[16:19]
	v_mfma_f32_16x16x32_bf16 v[8:11], v[146:149], v[208:211], v[8:11]
	v_mfma_f32_16x16x32_bf16 v[60:63], v[142:145], v[180:183], v[60:63]
	v_mfma_f32_16x16x32_bf16 v[56:59], v[150:153], v[180:183], v[56:59]
	v_mfma_f32_16x16x32_bf16 v[48:51], v[142:145], v[196:199], v[48:51]
	v_mfma_f32_16x16x32_bf16 v[40:43], v[150:153], v[196:199], v[40:43]
	v_mfma_f32_16x16x32_bf16 v[32:35], v[142:145], v[204:207], v[32:35]
	v_mfma_f32_16x16x32_bf16 v[24:27], v[150:153], v[204:207], v[24:27]
	v_mfma_f32_16x16x32_bf16 v[16:19], v[142:145], v[212:215], v[16:19]
	v_mfma_f32_16x16x32_bf16 v[8:11], v[150:153], v[212:215], v[8:11]
	v_mfma_f32_16x16x32_bf16 v[52:55], v[160:163], v[176:179], v[52:55]
	v_mfma_f32_16x16x32_bf16 v[44:47], v[168:171], v[176:179], v[44:47]
	v_mfma_f32_16x16x32_bf16 v[36:39], v[160:163], v[188:191], v[36:39]
	v_mfma_f32_16x16x32_bf16 v[28:31], v[168:171], v[188:191], v[28:31]
	v_mfma_f32_16x16x32_bf16 v[20:23], v[160:163], v[200:203], v[20:23]
	v_mfma_f32_16x16x32_bf16 v[12:15], v[168:171], v[200:203], v[12:15]
	v_mfma_f32_16x16x32_bf16 v[4:7], v[160:163], v[208:211], v[4:7]
	v_mfma_f32_16x16x32_bf16 v[0:3], v[168:171], v[208:211], v[0:3]
	v_mfma_f32_16x16x32_bf16 v[52:55], v[164:167], v[180:183], v[52:55]
	v_mfma_f32_16x16x32_bf16 v[44:47], v[172:175], v[180:183], v[44:47]
	v_mfma_f32_16x16x32_bf16 v[36:39], v[164:167], v[196:199], v[36:39]
	v_mfma_f32_16x16x32_bf16 v[28:31], v[172:175], v[196:199], v[28:31]
	v_mfma_f32_16x16x32_bf16 v[20:23], v[164:167], v[204:207], v[20:23]
	v_mfma_f32_16x16x32_bf16 v[12:15], v[172:175], v[204:207], v[12:15]
	v_mfma_f32_16x16x32_bf16 v[4:7], v[164:167], v[212:215], v[4:7]
	v_mfma_f32_16x16x32_bf16 v[0:3], v[172:175], v[212:215], v[0:3]
	s_barrier
	s_add_i32 s53, s53, 2
	s_add_u32 s30, s30, 0x100
	s_addc_u32 s31, s31, 0
	s_add_u32 s19, s19, 0x100
	s_addc_u32 s52, s52, 0
	s_cmp_gt_u32 s53, 29
	s_cbranch_scc0 .LBB0_1299
	s_and_b64 vcc, exec, s[12:13]
	s_cbranch_vccz .LBB0_1302
	s_barrier

; DI int lane_id_fresh() { int l; asm volatile("v_mbcnt_lo_u32_b32 %0, -1, 0\n\tv_mbcnt_hi_u32_b32 %0, -1, %0" : "=v"(l)); return l; }
; #define SEAM(k) do { if (IN((k) + 1) && IN(k)) xcd_barrier(bar); } while (0)
; __device__ __forceinline__ void xcd_barrier(const XcdBarrier& b) {
;     asm volatile("s_waitcnt vmcnt(0)" ::: "memory");
;     __syncthreads();
;     if (b.w0 && lane_id_fresh() == 0) {
;         unsigned* bar = b.bar;
;         __builtin_amdgcn_s_waitcnt(0);
;         unsigned nloc = b.st[0], nx = b.st[1];
;         if (nloc == 0u) { xcd_barrier_complete(bar, b.x, nloc, nx); b.st[0] = nloc; b.st[1] = nx; }
; __global__ void __launch_bounds__(512, 2) trunk_fwd(Args args_unused) {
;     ...
;             SEAM(s0 + 8);
.LBB0_1322:
	s_setprio 0
	v_readlane_b32 s0, v254, 37
	v_readlane_b32 s4, v252, 10
	s_add_i32 s0, s0, 10
	v_readlane_b32 s7, v252, 13
	v_readlane_b32 s6, v252, 12
	s_cmp_ge_i32 s0, s7
	s_movk_i32 s20, 0x5ff
	v_readlane_b32 s5, v252, 11
	s_cbranch_scc1 .LBB0_1374
	s_waitcnt vmcnt(0)
	v_readlane_b32 s0, v252, 5
	v_readlane_b32 s1, v252, 6
	s_and_b64 vcc, exec, s[0:1]
	s_waitcnt lgkmcnt(0)
	s_barrier
	s_cbranch_vccnz .LBB0_1373
	v_mbcnt_lo_u32_b32 v0, -1, 0
	v_mbcnt_hi_u32_b32 v0, -1, v0
	s_nop 0
	v_cmp_eq_u32_e32 vcc, 0, v0
	s_and_saveexec_b64 s[2:3], vcc
	s_cbranch_execz .LBB0_1372
	v_readlane_b32 s0, v254, 5
	s_waitcnt vmcnt(0) expcnt(0) lgkmcnt(0)
	s_nop 0
	v_mov_b32_e32 v0, s0
	ds_read_b32 v2, v0
	v_readlane_b32 s0, v254, 6
	s_waitcnt lgkmcnt(0)
	v_cmp_ne_u32_e32 vcc, 0, v2
	v_mov_b32_e32 v0, s0
	ds_read_b32 v0, v0
	s_cbranch_vccnz .LBB0_1340
	v_readlane_b32 s4, v252, 7
	v_readlane_b32 s5, v252, 8
	s_load_dwordx2 s[0:1], s[4:5], 0x4
	s_mov_b32 s9, 1
	s_waitcnt lgkmcnt(0)
	s_mul_i32 s8, s0, s16
	s_mul_i32 s8, s8, s1
	s_branch .LBB0_1328

; #define LAS __attribute__((address_space(3)))
;     DI void init(const bf16* A_, int lda, const bf16* B_, int ldb, int nM, int nN, int K, int G_, int c_) { T.init(nM, nN); G = G_; c = c_; nt = K / BK; A = (const char*)A_; B = (const char*)B_; ta = (size_t)BM * lda * 2; tb = (size_t)BM * ldb * 2; }
;     DI void init(const bf16* A_, int lda, const bf16* B_, int ldb, int nM, int nN, int G_, int c_) { T.init(nM, nN); G = G_; c = c_; A = (const char*)A_; B = (const char*)B_; ta = (size_t)BM * lda * 2; tb = (size_t)BM * ldb * 2; }
;     DI const char* aptr(const Unit& u) const { return A + (size_t)u.pm * ta + (size_t)kofs(u.seg) * 2; }
;     DI const char* bptr(const Unit& u) const { return B + (size_t)u.pn * tb + (size_t)kofs(u.seg) * 2; }
; #define PG8_STAGE(bufoff, gbase, voff) do { _Pragma("unroll") for (int _i = 0; _i < 2; ++_i) \
;         __builtin_amdgcn_global_load_lds((const unsigned*)((const char*)(gbase) + (voff)[_i]), (LAS unsigned*)(lds + (bufoff) + ldsw + _i * 8192), 16, 0, 0); } while (0)
; #define PG8_WAIT_V(n) asm volatile("s_waitcnt vmcnt(" #n ")" ::: "memory")
; #define PG8_BAR __builtin_amdgcn_s_barrier()
; #define SEAM(k) do { if (IN((k) + 1) && IN(k)) xcd_barrier(bar); } while (0)
; template <class Epi, class Sched>
; DI void gemm_phase(LAS unsigned char* lds, const int wv, const int lda, const int ldb, const Sched& S, const Epi& E) {
;     ...
;     const char* cA = S.aptr(cur); const char* cB = S.bptr(cur); int nt = S.ntiles(cur);
;     PG8_STAGE(PG8_SB(0, 0), cB, voffB); PG8_STAGE(PG8_SB(0, 1), cB + hstepB, voffB); PG8_STAGE(PG8_SA(0, 0), cA, voffA); PG8_STAGE(PG8_SA(0, 1), cA + hstepA, voffA);
;     if (wr == 1) PG8_BAR;
;     PG8_WAIT_V(2); PG8_BAR;
;     PG8_STAGE(PG8_SB(1, 0), cB + kstep, voffB); PG8_STAGE(PG8_SA(1, 0), cA + kstep, voffA); PG8_STAGE(PG8_SB(1, 1), cB + hstepB + kstep, voffB);
;     PG8_WAIT_V(6); PG8_BAR;
; __global__ void __launch_bounds__(512, 2) trunk_fwd(Args args_unused) {
;     ...
;         if (PHEN(10) && IN(s0 + 10)) { FRAME();
;             const LAS float* rs = rstd_table(F);
;             SchedPlain S; S.init((const bf16*)F.out, XP, (const bf16*)lw(F, l, LW_W1), D, M / BM, DFF / BM, D, F.G, F.bid);
;             EpiRelu2 E{(bf16*)(F.ws + WS_R2), rs};
;             gemm_phase<EpiRelu2, SchedPlain>(F.lds, F.wave, XP, D, S, E);
;             SEAM(s0 + 10);
.LBB0_1387:
	s_sext_i32_i16 s47, s4
	s_lshl_b32 s4, s17, 13
	s_and_b32 s4, s4, 0xe000
	s_sub_i32 s42, 0, s4
	v_lshrrev_b32_e32 v16, 1, v14
	s_add_i32 s42, s42, 0x20000
	v_and_b32_e32 v16, 24, v16
	s_add_u32 s6, s10, 0x23c28000
	v_and_b32_e32 v15, 15, v14
	v_lshlrev_b32_e32 v17, 1, v16
	v_lshlrev_b32_e32 v14, 2, v14
	s_addc_u32 s7, s11, 0
	v_lshl_or_b32 v144, s0, 6, v15
	v_lshl_or_b32 v15, v15, 6, v17
	s_lshl_b32 s0, s0, 13
	v_and_b32_e32 v14, 32, v14
	v_bitop3_b32 v17, v15, s0, v14 bitop3:0xde
	s_lshl_b32 s0, s1, 5
	s_and_b32 s4, s0, 0x60
	s_add_i32 m0, s25, 0x18000
	v_lshl_add_u64 v[6:7], v[6:7], 0, s[28:29]
	s_lshl_b32 s0, s4, 7
	s_waitcnt vmcnt(2)
	s_barrier
	global_load_lds_dwordx4 v[6:7], off
	v_lshl_add_u64 v[4:5], v[4:5], 0, s[28:29]
	s_add_i32 m0, s25, 0x1a000
	s_add_i32 s43, s25, 0x8000
	s_add_i32 s44, s25, 0xa000
	v_bitop3_b32 v145, v15, s0, v14 bitop3:0xde
	global_load_lds_dwordx4 v[4:5], off
	v_lshl_add_u64 v[0:1], v[0:1], 0, s[28:29]
	s_mov_b32 m0, s43
	s_add_u32 s0, s30, 0x80080
	global_load_lds_dwordx4 v[0:1], off
	v_lshl_add_u64 v[0:1], v[2:3], 0, s[28:29]
	s_mov_b32 m0, s44
	s_addc_u32 s1, s31, 0
	global_load_lds_dwordx4 v[0:1], off
	s_add_i32 m0, s25, 0x1c000
	v_lshl_add_u64 v[0:1], s[0:1], 0, v[184:185]
	global_load_lds_dwordx4 v[0:1], off
	v_lshl_add_u64 v[0:1], s[0:1], 0, v[132:133]
	s_add_i32 m0, s25, 0x1e000
	s_cmpk_lt_u32 s5, 0x100
	global_load_lds_dwordx4 v[0:1], off
	v_lshlrev_b32_e32 v0, 15, v8
	v_and_b32_e32 v0, 0xffff0000, v0
	v_lshl_add_u32 v0, v9, 12, v0
	v_and_b32_e32 v1, 1, v8
	v_lshl_or_b32 v0, v1, 6, v0
	v_lshl_add_u32 v134, v10, 1, v0
	v_lshlrev_b32_e32 v0, 15, v11
	v_and_b32_e32 v0, 0xffff0000, v0
	s_waitcnt vmcnt(6)
	v_lshl_add_u32 v0, v12, 12, v0
	v_and_b32_e32 v1, 1, v11
	v_lshl_or_b32 v0, v1, 6, v0
	s_cselect_b64 s[10:11], -1, 0
	s_ashr_i32 s45, s20, 31
	v_or_b32_e32 v146, s4, v16
	v_mov_b32_e32 v135, v185
	v_lshl_add_u32 v136, v13, 1, v0
	v_mov_b32_e32 v137, v185
	s_mov_b32 s46, 0
	v_add_u32_e32 v147, 0, v17
	s_barrier
	s_cmp_ge_u32 s90, 4
	s_cbranch_scc0 .Lprio_1390_done
	s_setprio 1

; #define PG8_STAGE(bufoff, gbase, voff) do { _Pragma("unroll") for (int _i = 0; _i < 2; ++_i) \
;         __builtin_amdgcn_global_load_lds((const unsigned*)((const char*)(gbase) + (voff)[_i]), (LAS unsigned*)(lds + (bufoff) + ldsw + _i * 8192), 16, 0, 0); } while (0)
; #define PG8_LDA(dst, b, h) do { _Pragma("unroll") for (int m = 0; m < 4; ++m) _Pragma("unroll") for (int k = 0; k < 2; ++k) dst[m][k] = *(const LAS bf16x8*)(lds + PG8_SA(b, h) + aoff + m * 2048 + k * 1024); } while (0)
; #define PG8_LDB(dst, b, h) do { _Pragma("unroll") for (int n = 0; n < 2; ++n) _Pragma("unroll") for (int k = 0; k < 2; ++k) dst[n][k] = *(const LAS bf16x8*)(lds + PG8_SB(b, h) + boff + n * 2048 + k * 1024); } while (0)
; #define PG8_MMA(ai, bj, At, Bt) do { __builtin_amdgcn_s_setprio(1); _Pragma("unroll") for (int m = 0; m < 4; ++m) _Pragma("unroll") for (int n = 0; n < 2; ++n) _Pragma("unroll") for (int k = 0; k < 2; ++k) \
;         acc[ai][bj][m][n] = __builtin_amdgcn_mfma_f32_16x16x32_bf16(Bt[n][k], At[m][k], acc[ai][bj][m][n], 0, 0, 0); __builtin_amdgcn_s_setprio(0); } while (0)
; #define PG8_WAIT_V(n) asm volatile("s_waitcnt vmcnt(" #n ")" ::: "memory")
; #define PG8_WAIT_L(n) asm volatile("s_waitcnt lgkmcnt(" #n ")" ::: "memory")
; #define PG8_BAR __builtin_amdgcn_s_barrier()
; #define PG8_SCHED __builtin_amdgcn_sched_barrier(0)
; template <class Epi, class Sched>
; DI void gemm_phase(LAS unsigned char* lds, const int wv, const int lda, const int ldb, const Sched& S, const Epi& E) {
;     ...
;             const char* a1 = cA + (size_t)(t + 1) * kstep;
;             const char* a2 = last ? nA : cA + (size_t)(t + 2) * kstep; const char* b2 = last ? nB : cB + (size_t)(t + 2) * kstep;
;             const char* a3 = a2 + kstep; const char* b3 = b2 + kstep;
;             PG8_LDB(B0, 0, 0); PG8_LDB(B1, 0, 1); PG8_SCHED; PG8_LDA(At, 0, 0); PG8_STAGE(PG8_SA(1, 1), a1 + hstepA, voffA);
;             PG8_WAIT_V(8); PG8_WAIT_L(0); PG8_BAR; PG8_MMA(0, 0, At, B0); PG8_MMA(0, 1, At, B1); PG8_BAR; PG8_SCHED;
;             PG8_LDA(At, 0, 1); PG8_STAGE(PG8_SB(0, 0), b2, voffB); PG8_STAGE(PG8_SB(0, 1), b2 + hstepB, voffB); PG8_STAGE(PG8_SA(0, 0), a2, voffA);
;             PG8_WAIT_V(8); PG8_WAIT_L(0); PG8_BAR; PG8_MMA(1, 0, At, B0); PG8_MMA(1, 1, At, B1); PG8_BAR; PG8_SCHED;
.LBB0_1397:
	s_add_u32 s30, s26, 0xfff80080
	s_addc_u32 s31, s27, -1
	s_add_i32 s51, 0, 0x10000
	s_cmp_eq_u32 s50, 28
	s_cselect_b32 s35, s0, s31
	s_cselect_b32 s34, s1, s30
	v_add_u32_e32 v142, s51, v145
	s_cselect_b32 s31, s13, s49
	s_cselect_b32 s30, s15, s48
	s_add_i32 s54, 0, 0x14000
	ds_read_b128 v[138:141], v142
	ds_read_b128 v[148:151], v142 offset:1024
	ds_read_b128 v[152:155], v142 offset:2048
	ds_read_b128 v[156:159], v142 offset:3072
	v_add_u32_e32 v142, s54, v145
	ds_read_b128 v[160:163], v142
	ds_read_b128 v[164:167], v142 offset:1024
	ds_read_b128 v[168:171], v142 offset:2048
	ds_read_b128 v[172:175], v142 offset:3072
	v_lshl_add_u64 v[142:143], s[26:27], 0, v[134:135]
	s_add_i32 m0, s25, 0xc000
	ds_read_b128 v[176:179], v147
	ds_read_b128 v[180:183], v147 offset:1024
	ds_read_b128 v[188:191], v147 offset:2048
	ds_read_b128 v[196:199], v147 offset:3072
	ds_read_b128 v[200:203], v147 offset:4096
	ds_read_b128 v[204:207], v147 offset:5120
	ds_read_b128 v[208:211], v147 offset:6144
	ds_read_b128 v[212:215], v147 offset:7168
	global_load_lds_dwordx4 v[142:143], off
	v_lshl_add_u64 v[142:143], s[26:27], 0, v[136:137]
	s_add_i32 m0, s25, 0xe000
	s_nop 0
	global_load_lds_dwordx4 v[142:143], off
	s_waitcnt vmcnt(8)
	s_waitcnt lgkmcnt(0)
	s_barrier
	s_waitcnt lgkmcnt(0)
	v_mfma_f32_16x16x32_bf16 v[124:127], v[138:141], v[176:179], v[124:127]
	v_mfma_f32_16x16x32_bf16 v[120:123], v[152:155], v[176:179], v[120:123]
	v_mfma_f32_16x16x32_bf16 v[108:111], v[138:141], v[188:191], v[108:111]
	v_mfma_f32_16x16x32_bf16 v[104:107], v[152:155], v[188:191], v[104:107]
	v_mfma_f32_16x16x32_bf16 v[92:95], v[138:141], v[200:203], v[92:95]
	v_mfma_f32_16x16x32_bf16 v[88:91], v[152:155], v[200:203], v[88:91]
	v_mfma_f32_16x16x32_bf16 v[76:79], v[138:141], v[208:211], v[76:79]
	v_mfma_f32_16x16x32_bf16 v[72:75], v[152:155], v[208:211], v[72:75]
	v_mfma_f32_16x16x32_bf16 v[124:127], v[148:151], v[180:183], v[124:127]
	v_mfma_f32_16x16x32_bf16 v[120:123], v[156:159], v[180:183], v[120:123]
	v_mfma_f32_16x16x32_bf16 v[108:111], v[148:151], v[196:199], v[108:111]
	v_mfma_f32_16x16x32_bf16 v[104:107], v[156:159], v[196:199], v[104:107]
	v_mfma_f32_16x16x32_bf16 v[92:95], v[148:151], v[204:207], v[92:95]
	v_mfma_f32_16x16x32_bf16 v[88:91], v[156:159], v[204:207], v[88:91]
	v_mfma_f32_16x16x32_bf16 v[76:79], v[148:151], v[212:215], v[76:79]
	v_mfma_f32_16x16x32_bf16 v[72:75], v[156:159], v[212:215], v[72:75]
	v_mfma_f32_16x16x32_bf16 v[116:119], v[160:163], v[176:179], v[116:119]
	v_mfma_f32_16x16x32_bf16 v[112:115], v[168:171], v[176:179], v[112:115]
	v_mfma_f32_16x16x32_bf16 v[100:103], v[160:163], v[188:191], v[100:103]
	v_mfma_f32_16x16x32_bf16 v[96:99], v[168:171], v[188:191], v[96:99]
	v_mfma_f32_16x16x32_bf16 v[84:87], v[160:163], v[200:203], v[84:87]
	v_mfma_f32_16x16x32_bf16 v[80:83], v[168:171], v[200:203], v[80:83]
	v_mfma_f32_16x16x32_bf16 v[68:71], v[160:163], v[208:211], v[68:71]
	v_mfma_f32_16x16x32_bf16 v[64:67], v[168:171], v[208:211], v[64:67]
	v_mfma_f32_16x16x32_bf16 v[116:119], v[164:167], v[180:183], v[116:119]
	v_mfma_f32_16x16x32_bf16 v[112:115], v[172:175], v[180:183], v[112:115]
	v_mfma_f32_16x16x32_bf16 v[100:103], v[164:167], v[196:199], v[100:103]
	v_mfma_f32_16x16x32_bf16 v[96:99], v[172:175], v[196:199], v[96:99]
	v_mfma_f32_16x16x32_bf16 v[84:87], v[164:167], v[204:207], v[84:87]
	v_mfma_f32_16x16x32_bf16 v[80:83], v[172:175], v[204:207], v[80:83]
	v_mfma_f32_16x16x32_bf16 v[68:71], v[164:167], v[212:215], v[68:71]
	v_mfma_f32_16x16x32_bf16 v[64:67], v[172:175], v[212:215], v[64:67]
	s_barrier
	s_add_i32 s51, s51, s38
	v_lshl_add_u64 v[142:143], s[30:31], 0, v[184:185]
	s_mov_b32 m0, s51
	ds_read_b128 v[176:179], v147 offset:16384
	ds_read_b128 v[180:183], v147 offset:17408
	ds_read_b128 v[188:191], v147 offset:18432
	ds_read_b128 v[196:199], v147 offset:19456
	ds_read_b128 v[200:203], v147 offset:20480
	ds_read_b128 v[204:207], v147 offset:21504
	ds_read_b128 v[208:211], v147 offset:22528
	ds_read_b128 v[212:215], v147 offset:23552
	global_load_lds_dwordx4 v[142:143], off
	s_add_i32 m0, s51, 0x2000
	s_add_u32 s52, s30, 0x80000
	v_lshl_add_u64 v[216:217], s[30:31], 0, v[132:133]
	s_addc_u32 s53, s31, 0
	s_add_i32 s51, s54, s38
	global_load_lds_dwordx4 v[216:217], off
	v_lshl_add_u64 v[218:219], s[52:53], 0, v[184:185]
	s_mov_b32 m0, s51
	v_lshl_add_u64 v[220:221], s[34:35], 0, v[130:131]
	global_load_lds_dwordx4 v[218:219], off
	v_lshl_add_u64 v[218:219], s[52:53], 0, v[132:133]
	s_add_i32 m0, s51, 0x2000
	s_nop 0
	global_load_lds_dwordx4 v[218:219], off
	v_lshl_add_u64 v[218:219], s[34:35], 0, v[128:129]
	s_mov_b32 m0, s25
	s_nop 0
	global_load_lds_dwordx4 v[218:219], off
	s_mov_b32 m0, s39
	s_nop 0
	global_load_lds_dwordx4 v[220:221], off
	s_waitcnt vmcnt(8)
	s_waitcnt lgkmcnt(0)
	s_barrier
; #define PG8_STAGE(bufoff, gbase, voff) do { _Pragma("unroll") for (int _i = 0; _i < 2; ++_i) \
;         __builtin_amdgcn_global_load_lds((const unsigned*)((const char*)(gbase) + (voff)[_i]), (LAS unsigned*)(lds + (bufoff) + ldsw + _i * 8192), 16, 0, 0); } while (0)
; #define PG8_LDA(dst, b, h) do { _Pragma("unroll") for (int m = 0; m < 4; ++m) _Pragma("unroll") for (int k = 0; k < 2; ++k) dst[m][k] = *(const LAS bf16x8*)(lds + PG8_SA(b, h) + aoff + m * 2048 + k * 1024); } while (0)
; #define PG8_LDB(dst, b, h) do { _Pragma("unroll") for (int n = 0; n < 2; ++n) _Pragma("unroll") for (int k = 0; k < 2; ++k) dst[n][k] = *(const LAS bf16x8*)(lds + PG8_SB(b, h) + boff + n * 2048 + k * 1024); } while (0)
; #define PG8_MMA(ai, bj, At, Bt) do { __builtin_amdgcn_s_setprio(1); _Pragma("unroll") for (int m = 0; m < 4; ++m) _Pragma("unroll") for (int n = 0; n < 2; ++n) _Pragma("unroll") for (int k = 0; k < 2; ++k) \
;         acc[ai][bj][m][n] = __builtin_amdgcn_mfma_f32_16x16x32_bf16(Bt[n][k], At[m][k], acc[ai][bj][m][n], 0, 0, 0); __builtin_amdgcn_s_setprio(0); } while (0)
; #define PG8_WAIT_V(n) asm volatile("s_waitcnt vmcnt(" #n ")" ::: "memory")
; #define PG8_WAIT_L(n) asm volatile("s_waitcnt lgkmcnt(" #n ")" ::: "memory")
; #define PG8_BAR __builtin_amdgcn_s_barrier()
; #define PG8_SCHED __builtin_amdgcn_sched_barrier(0)
; template <class Epi, class Sched>
; DI void gemm_phase(LAS unsigned char* lds, const int wv, const int lda, const int ldb, const Sched& S, const Epi& E) {
;     ...
;             PG8_WAIT_V(8); PG8_WAIT_L(0); PG8_BAR; PG8_MMA(1, 0, At, B0); PG8_MMA(1, 1, At, B1); PG8_BAR; PG8_SCHED;
;             PG8_LDB(B0, 1, 0); PG8_LDB(B1, 1, 1); PG8_SCHED; PG8_LDA(At, 1, 0); PG8_STAGE(PG8_SA(0, 1), a2 + hstepA, voffA);
;             PG8_WAIT_V(8); PG8_WAIT_L(0); PG8_BAR; PG8_MMA(0, 0, At, B0); PG8_MMA(0, 1, At, B1); PG8_BAR; PG8_SCHED;
	s_waitcnt lgkmcnt(0)
	v_mfma_f32_16x16x32_bf16 v[60:63], v[138:141], v[176:179], v[60:63]
	v_mfma_f32_16x16x32_bf16 v[56:59], v[152:155], v[176:179], v[56:59]
	v_mfma_f32_16x16x32_bf16 v[44:47], v[138:141], v[188:191], v[44:47]
	v_mfma_f32_16x16x32_bf16 v[40:43], v[152:155], v[188:191], v[40:43]
	v_mfma_f32_16x16x32_bf16 v[28:31], v[138:141], v[200:203], v[28:31]
	v_mfma_f32_16x16x32_bf16 v[24:27], v[152:155], v[200:203], v[24:27]
	v_mfma_f32_16x16x32_bf16 v[12:15], v[138:141], v[208:211], v[12:15]
	v_mfma_f32_16x16x32_bf16 v[8:11], v[152:155], v[208:211], v[8:11]
	v_mfma_f32_16x16x32_bf16 v[60:63], v[148:151], v[180:183], v[60:63]
	v_mfma_f32_16x16x32_bf16 v[56:59], v[156:159], v[180:183], v[56:59]
	v_mfma_f32_16x16x32_bf16 v[44:47], v[148:151], v[196:199], v[44:47]
	v_mfma_f32_16x16x32_bf16 v[40:43], v[156:159], v[196:199], v[40:43]
	v_mfma_f32_16x16x32_bf16 v[28:31], v[148:151], v[204:207], v[28:31]
	v_mfma_f32_16x16x32_bf16 v[24:27], v[156:159], v[204:207], v[24:27]
	v_mfma_f32_16x16x32_bf16 v[12:15], v[148:151], v[212:215], v[12:15]
	v_mfma_f32_16x16x32_bf16 v[8:11], v[156:159], v[212:215], v[8:11]
	v_mfma_f32_16x16x32_bf16 v[52:55], v[160:163], v[176:179], v[52:55]
	v_mfma_f32_16x16x32_bf16 v[48:51], v[168:171], v[176:179], v[48:51]
	v_mfma_f32_16x16x32_bf16 v[36:39], v[160:163], v[188:191], v[36:39]
	v_mfma_f32_16x16x32_bf16 v[32:35], v[168:171], v[188:191], v[32:35]
	v_mfma_f32_16x16x32_bf16 v[20:23], v[160:163], v[200:203], v[20:23]
	v_mfma_f32_16x16x32_bf16 v[16:19], v[168:171], v[200:203], v[16:19]
	v_mfma_f32_16x16x32_bf16 v[4:7], v[160:163], v[208:211], v[4:7]
	v_mfma_f32_16x16x32_bf16 v[0:3], v[168:171], v[208:211], v[0:3]
	v_mfma_f32_16x16x32_bf16 v[52:55], v[164:167], v[180:183], v[52:55]
	v_mfma_f32_16x16x32_bf16 v[48:51], v[172:175], v[180:183], v[48:51]
	v_mfma_f32_16x16x32_bf16 v[36:39], v[164:167], v[196:199], v[36:39]
	v_mfma_f32_16x16x32_bf16 v[32:35], v[172:175], v[196:199], v[32:35]
	v_mfma_f32_16x16x32_bf16 v[20:23], v[164:167], v[204:207], v[20:23]
	v_mfma_f32_16x16x32_bf16 v[16:19], v[172:175], v[204:207], v[16:19]
	v_mfma_f32_16x16x32_bf16 v[4:7], v[164:167], v[212:215], v[4:7]
	v_mfma_f32_16x16x32_bf16 v[0:3], v[172:175], v[212:215], v[0:3]
	s_barrier
	s_add_i32 s51, 0, 0x18000
	s_add_i32 s52, 0, 0x1c000
	v_add_u32_e32 v156, s51, v145
	v_add_u32_e32 v172, s52, v145
	ds_read_b128 v[138:141], v156
	ds_read_b128 v[148:151], v156 offset:1024
	ds_read_b128 v[152:155], v156 offset:2048
	ds_read_b128 v[156:159], v156 offset:3072
	ds_read_b128 v[160:163], v172
	ds_read_b128 v[164:167], v172 offset:1024
	ds_read_b128 v[168:171], v172 offset:2048
	ds_read_b128 v[172:175], v172 offset:3072
	s_add_u32 s34, s34, 0x80000
	s_addc_u32 s35, s35, 0
	s_mov_b32 m0, s40
	v_lshl_add_u64 v[222:223], s[34:35], 0, v[128:129]
	ds_read_b128 v[176:179], v147 offset:32768
	ds_read_b128 v[180:183], v147 offset:33792
	ds_read_b128 v[188:191], v147 offset:34816
	ds_read_b128 v[196:199], v147 offset:35840
	ds_read_b128 v[200:203], v147 offset:36864
	ds_read_b128 v[204:207], v147 offset:37888
	ds_read_b128 v[208:211], v147 offset:38912
	ds_read_b128 v[212:215], v147 offset:39936
	global_load_lds_dwordx4 v[222:223], off
	v_lshl_add_u64 v[222:223], s[34:35], 0, v[130:131]
	s_mov_b32 m0, s41
	s_nop 0
	global_load_lds_dwordx4 v[222:223], off
	s_waitcnt vmcnt(8)
	s_waitcnt lgkmcnt(0)
	s_barrier
	s_waitcnt lgkmcnt(0)
	v_mfma_f32_16x16x32_bf16 v[124:127], v[138:141], v[176:179], v[124:127]
	v_mfma_f32_16x16x32_bf16 v[120:123], v[152:155], v[176:179], v[120:123]
	v_mfma_f32_16x16x32_bf16 v[108:111], v[138:141], v[188:191], v[108:111]
	v_mfma_f32_16x16x32_bf16 v[104:107], v[152:155], v[188:191], v[104:107]
	v_mfma_f32_16x16x32_bf16 v[92:95], v[138:141], v[200:203], v[92:95]
	v_mfma_f32_16x16x32_bf16 v[88:91], v[152:155], v[200:203], v[88:91]
	v_mfma_f32_16x16x32_bf16 v[76:79], v[138:141], v[208:211], v[76:79]
	v_mfma_f32_16x16x32_bf16 v[72:75], v[152:155], v[208:211], v[72:75]
	v_mfma_f32_16x16x32_bf16 v[124:127], v[148:151], v[180:183], v[124:127]
	v_mfma_f32_16x16x32_bf16 v[120:123], v[156:159], v[180:183], v[120:123]
	v_mfma_f32_16x16x32_bf16 v[108:111], v[148:151], v[196:199], v[108:111]
	v_mfma_f32_16x16x32_bf16 v[104:107], v[156:159], v[196:199], v[104:107]
	v_mfma_f32_16x16x32_bf16 v[92:95], v[148:151], v[204:207], v[92:95]
	v_mfma_f32_16x16x32_bf16 v[88:91], v[156:159], v[204:207], v[88:91]
	v_mfma_f32_16x16x32_bf16 v[76:79], v[148:151], v[212:215], v[76:79]
	v_mfma_f32_16x16x32_bf16 v[72:75], v[156:159], v[212:215], v[72:75]
	v_mfma_f32_16x16x32_bf16 v[116:119], v[160:163], v[176:179], v[116:119]
	v_mfma_f32_16x16x32_bf16 v[112:115], v[168:171], v[176:179], v[112:115]
	v_mfma_f32_16x16x32_bf16 v[100:103], v[160:163], v[188:191], v[100:103]
	v_mfma_f32_16x16x32_bf16 v[96:99], v[168:171], v[188:191], v[96:99]
	v_mfma_f32_16x16x32_bf16 v[84:87], v[160:163], v[200:203], v[84:87]
	v_mfma_f32_16x16x32_bf16 v[80:83], v[168:171], v[200:203], v[80:83]
	v_mfma_f32_16x16x32_bf16 v[68:71], v[160:163], v[208:211], v[68:71]
	v_mfma_f32_16x16x32_bf16 v[64:67], v[168:171], v[208:211], v[64:67]
	v_mfma_f32_16x16x32_bf16 v[116:119], v[164:167], v[180:183], v[116:119]
	v_mfma_f32_16x16x32_bf16 v[112:115], v[172:175], v[180:183], v[112:115]
	v_mfma_f32_16x16x32_bf16 v[100:103], v[164:167], v[196:199], v[100:103]
	v_mfma_f32_16x16x32_bf16 v[96:99], v[172:175], v[196:199], v[96:99]
	v_mfma_f32_16x16x32_bf16 v[84:87], v[164:167], v[204:207], v[84:87]
	v_mfma_f32_16x16x32_bf16 v[80:83], v[172:175], v[204:207], v[80:83]
	v_mfma_f32_16x16x32_bf16 v[68:71], v[164:167], v[212:215], v[68:71]
	v_mfma_f32_16x16x32_bf16 v[64:67], v[172:175], v[212:215], v[64:67]
	s_barrier
; #define PG8_STAGE(bufoff, gbase, voff) do { _Pragma("unroll") for (int _i = 0; _i < 2; ++_i) \
;         __builtin_amdgcn_global_load_lds((const unsigned*)((const char*)(gbase) + (voff)[_i]), (LAS unsigned*)(lds + (bufoff) + ldsw + _i * 8192), 16, 0, 0); } while (0)
; #define PG8_LDA(dst, b, h) do { _Pragma("unroll") for (int m = 0; m < 4; ++m) _Pragma("unroll") for (int k = 0; k < 2; ++k) dst[m][k] = *(const LAS bf16x8*)(lds + PG8_SA(b, h) + aoff + m * 2048 + k * 1024); } while (0)
; #define PG8_MMA(ai, bj, At, Bt) do { __builtin_amdgcn_s_setprio(1); _Pragma("unroll") for (int m = 0; m < 4; ++m) _Pragma("unroll") for (int n = 0; n < 2; ++n) _Pragma("unroll") for (int k = 0; k < 2; ++k) \
;         acc[ai][bj][m][n] = __builtin_amdgcn_mfma_f32_16x16x32_bf16(Bt[n][k], At[m][k], acc[ai][bj][m][n], 0, 0, 0); __builtin_amdgcn_s_setprio(0); } while (0)
; #define PG8_WAIT_V(n) asm volatile("s_waitcnt vmcnt(" #n ")" ::: "memory")
; #define PG8_WAIT_L(n) asm volatile("s_waitcnt lgkmcnt(" #n ")" ::: "memory")
; #define PG8_BAR __builtin_amdgcn_s_barrier()
; #define PG8_SCHED __builtin_amdgcn_sched_barrier(0)
; template <class Epi, class Sched>
; DI void gemm_phase(LAS unsigned char* lds, const int wv, const int lda, const int ldb, const Sched& S, const Epi& E) {
;     ...
;             PG8_LDA(At, 1, 1); PG8_STAGE(PG8_SB(1, 0), b3, voffB); PG8_STAGE(PG8_SB(1, 1), b3 + hstepB, voffB); PG8_STAGE(PG8_SA(1, 0), a3, voffA);
;             PG8_WAIT_V(8); PG8_WAIT_L(0); PG8_BAR; PG8_MMA(1, 0, At, B0); PG8_MMA(1, 1, At, B1); PG8_BAR; PG8_SCHED;
;         }
;         if (wr == 0) PG8_BAR;
	s_add_i32 s34, s51, s38
	v_lshl_add_u64 v[142:143], v[142:143], 0, s[28:29]
	s_mov_b32 m0, s34
	ds_read_b128 v[176:179], v147 offset:49152
	ds_read_b128 v[180:183], v147 offset:50176
	ds_read_b128 v[188:191], v147 offset:51200
	ds_read_b128 v[196:199], v147 offset:52224
	ds_read_b128 v[200:203], v147 offset:53248
	ds_read_b128 v[204:207], v147 offset:54272
	ds_read_b128 v[208:211], v147 offset:55296
	ds_read_b128 v[212:215], v147 offset:56320
	global_load_lds_dwordx4 v[142:143], off
	s_add_i32 m0, s34, 0x2000
	s_add_u32 s30, s30, 0x80080
	v_lshl_add_u64 v[142:143], v[216:217], 0, s[28:29]
	s_addc_u32 s31, s31, 0
	s_add_i32 s34, s52, s38
	global_load_lds_dwordx4 v[142:143], off
	v_lshl_add_u64 v[142:143], s[30:31], 0, v[184:185]
	s_mov_b32 m0, s34
	s_nop 0
	global_load_lds_dwordx4 v[142:143], off
	v_lshl_add_u64 v[142:143], s[30:31], 0, v[132:133]
	s_add_i32 m0, s34, 0x2000
	s_nop 0
	global_load_lds_dwordx4 v[142:143], off
	v_lshl_add_u64 v[142:143], v[218:219], 0, s[28:29]
	s_mov_b32 m0, s43
	s_nop 0
	global_load_lds_dwordx4 v[142:143], off
	v_lshl_add_u64 v[142:143], v[220:221], 0, s[28:29]
	s_mov_b32 m0, s44
	s_nop 0
	global_load_lds_dwordx4 v[142:143], off
	s_waitcnt vmcnt(8)
	s_waitcnt lgkmcnt(0)
	s_barrier
	s_waitcnt lgkmcnt(0)
	v_mfma_f32_16x16x32_bf16 v[60:63], v[138:141], v[176:179], v[60:63]
	v_mfma_f32_16x16x32_bf16 v[56:59], v[152:155], v[176:179], v[56:59]
	v_mfma_f32_16x16x32_bf16 v[44:47], v[138:141], v[188:191], v[44:47]
	v_mfma_f32_16x16x32_bf16 v[40:43], v[152:155], v[188:191], v[40:43]
	v_mfma_f32_16x16x32_bf16 v[28:31], v[138:141], v[200:203], v[28:31]
	v_mfma_f32_16x16x32_bf16 v[24:27], v[152:155], v[200:203], v[24:27]
	v_mfma_f32_16x16x32_bf16 v[12:15], v[138:141], v[208:211], v[12:15]
	v_mfma_f32_16x16x32_bf16 v[8:11], v[152:155], v[208:211], v[8:11]
	v_mfma_f32_16x16x32_bf16 v[60:63], v[148:151], v[180:183], v[60:63]
	v_mfma_f32_16x16x32_bf16 v[56:59], v[156:159], v[180:183], v[56:59]
	v_mfma_f32_16x16x32_bf16 v[44:47], v[148:151], v[196:199], v[44:47]
	v_mfma_f32_16x16x32_bf16 v[40:43], v[156:159], v[196:199], v[40:43]
	v_mfma_f32_16x16x32_bf16 v[28:31], v[148:151], v[204:207], v[28:31]
	v_mfma_f32_16x16x32_bf16 v[24:27], v[156:159], v[204:207], v[24:27]
	v_mfma_f32_16x16x32_bf16 v[12:15], v[148:151], v[212:215], v[12:15]
	v_mfma_f32_16x16x32_bf16 v[8:11], v[156:159], v[212:215], v[8:11]
	v_mfma_f32_16x16x32_bf16 v[52:55], v[160:163], v[176:179], v[52:55]
	v_mfma_f32_16x16x32_bf16 v[48:51], v[168:171], v[176:179], v[48:51]
	v_mfma_f32_16x16x32_bf16 v[36:39], v[160:163], v[188:191], v[36:39]
	v_mfma_f32_16x16x32_bf16 v[32:35], v[168:171], v[188:191], v[32:35]
	v_mfma_f32_16x16x32_bf16 v[20:23], v[160:163], v[200:203], v[20:23]
	v_mfma_f32_16x16x32_bf16 v[16:19], v[168:171], v[200:203], v[16:19]
	v_mfma_f32_16x16x32_bf16 v[4:7], v[160:163], v[208:211], v[4:7]
	v_mfma_f32_16x16x32_bf16 v[0:3], v[168:171], v[208:211], v[0:3]
	v_mfma_f32_16x16x32_bf16 v[52:55], v[164:167], v[180:183], v[52:55]
	v_mfma_f32_16x16x32_bf16 v[48:51], v[172:175], v[180:183], v[48:51]
	v_mfma_f32_16x16x32_bf16 v[36:39], v[164:167], v[196:199], v[36:39]
	v_mfma_f32_16x16x32_bf16 v[32:35], v[172:175], v[196:199], v[32:35]
	v_mfma_f32_16x16x32_bf16 v[20:23], v[164:167], v[204:207], v[20:23]
	v_mfma_f32_16x16x32_bf16 v[16:19], v[172:175], v[204:207], v[16:19]
	v_mfma_f32_16x16x32_bf16 v[4:7], v[164:167], v[212:215], v[4:7]
	v_mfma_f32_16x16x32_bf16 v[0:3], v[172:175], v[212:215], v[0:3]
	s_barrier
	s_add_i32 s50, s50, 2
	s_add_u32 s26, s26, 0x100
	s_addc_u32 s27, s27, 0
	s_add_u32 s48, s48, 0x100
	s_addc_u32 s49, s49, 0
	s_cmp_gt_u32 s50, 29
	s_cbranch_scc0 .LBB0_1397
	s_and_b64 vcc, exec, s[10:11]
	s_cbranch_vccz .LBB0_1400
	s_barrier

; DI int lane_id_fresh() { int l; asm volatile("v_mbcnt_lo_u32_b32 %0, -1, 0\n\tv_mbcnt_hi_u32_b32 %0, -1, %0" : "=v"(l)); return l; }
; #define SEAM(k) do { if (IN((k) + 1) && IN(k)) xcd_barrier(bar); } while (0)
; __device__ __forceinline__ void xcd_barrier(const XcdBarrier& b) {
;     asm volatile("s_waitcnt vmcnt(0)" ::: "memory");
;     __syncthreads();
;     if (b.w0 && lane_id_fresh() == 0) {
;         unsigned* bar = b.bar;
;         __builtin_amdgcn_s_waitcnt(0);
;         unsigned nloc = b.st[0], nx = b.st[1];
;         if (nloc == 0u) { xcd_barrier_complete(bar, b.x, nloc, nx); b.st[0] = nloc; b.st[1] = nx; }
; __global__ void __launch_bounds__(512, 2) trunk_fwd(Args args_unused) {
;     ...
;             SEAM(s0 + 10);
.LBB0_1404:
	s_setprio 0
	v_readlane_b32 s0, v254, 37
	s_add_i32 s17, s0, 12
	v_readlane_b32 s0, v252, 10
	v_readlane_b32 s3, v252, 13
	s_cmp_ge_i32 s17, s3
	v_readlane_b32 s1, v252, 11
	v_readlane_b32 s2, v252, 12
	s_cbranch_scc1 .LBB0_1417
	s_waitcnt vmcnt(0)
	v_readlane_b32 s0, v252, 5
	v_readlane_b32 s1, v252, 6
	s_and_b64 vcc, exec, s[0:1]
	s_movk_i32 s20, 0x5ff
	s_waitcnt vmcnt(0)
	s_barrier
	s_cbranch_vccnz .LBB0_1456
	v_mbcnt_lo_u32_b32 v0, -1, 0
	v_mbcnt_hi_u32_b32 v0, -1, v0
	s_nop 0
	v_cmp_eq_u32_e32 vcc, 0, v0
	s_and_saveexec_b64 s[2:3], vcc
	s_cbranch_execz .LBB0_1455
	v_readlane_b32 s0, v254, 5
	s_waitcnt vmcnt(0) expcnt(0) lgkmcnt(0)
	s_nop 0
	v_mov_b32_e32 v0, s0
	ds_read_b32 v2, v0
	v_readlane_b32 s0, v254, 6
	s_waitcnt lgkmcnt(0)
	v_cmp_ne_u32_e32 vcc, 0, v2
	v_mov_b32_e32 v0, s0
	ds_read_b32 v0, v0
	s_cbranch_vccnz .LBB0_1423
	v_readlane_b32 s4, v252, 7
	v_readlane_b32 s5, v252, 8
	s_load_dwordx2 s[0:1], s[4:5], 0x4
	s_mov_b32 s9, 1
	s_waitcnt lgkmcnt(0)
	s_mul_i32 s8, s0, s16
	s_mul_i32 s8, s8, s1
	s_branch .LBB0_1410

;     DI void init(const bf16* A_, int lda, const bf16* B_, int ldb, int nM, int nN, int K, int G_, int c_) { T.init(nM, nN); G = G_; c = c_; nt = K / BK; A = (const char*)A_; B = (const char*)B_; ta = (size_t)BM * lda * 2; tb = (size_t)BM * ldb * 2; }
;     DI void init(const bf16* A_, int lda, const bf16* B_, int ldb, int nM, int nN, int G_, int c_) { T.init(nM, nN); G = G_; c = c_; A = (const char*)A_; B = (const char*)B_; ta = (size_t)BM * lda * 2; tb = (size_t)BM * ldb * 2; }
;     DI const char* aptr(const Unit& u) const { return A + (size_t)u.pm * ta + (size_t)kofs(u.seg) * 2; }
;     DI const char* bptr(const Unit& u) const { return B + (size_t)u.pn * tb + (size_t)kofs(u.seg) * 2; }
; #define PG8_STAGE(bufoff, gbase, voff) do { _Pragma("unroll") for (int _i = 0; _i < 2; ++_i) \
;         __builtin_amdgcn_global_load_lds((const unsigned*)((const char*)(gbase) + (voff)[_i]), (LAS unsigned*)(lds + (bufoff) + ldsw + _i * 8192), 16, 0, 0); } while (0)
; #define PG8_WAIT_V(n) asm volatile("s_waitcnt vmcnt(" #n ")" ::: "memory")
; #define PG8_BAR __builtin_amdgcn_s_barrier()
; #define SEAM(k) do { if (IN((k) + 1) && IN(k)) xcd_barrier(bar); } while (0)
; template <class Epi, class Sched>
; DI void gemm_phase(LAS unsigned char* lds, const int wv, const int lda, const int ldb, const Sched& S, const Epi& E) {
;     ...
;     const char* cA = S.aptr(cur); const char* cB = S.bptr(cur); int nt = S.ntiles(cur);
;     PG8_STAGE(PG8_SB(0, 0), cB, voffB); PG8_STAGE(PG8_SB(0, 1), cB + hstepB, voffB); PG8_STAGE(PG8_SA(0, 0), cA, voffA); PG8_STAGE(PG8_SA(0, 1), cA + hstepA, voffA);
;     if (wr == 1) PG8_BAR;
;     PG8_WAIT_V(2); PG8_BAR;
;     PG8_STAGE(PG8_SB(1, 0), cB + kstep, voffB); PG8_STAGE(PG8_SA(1, 0), cA + kstep, voffA); PG8_STAGE(PG8_SB(1, 1), cB + hstepB + kstep, voffB);
;     PG8_WAIT_V(6); PG8_BAR;
; __global__ void __launch_bounds__(512, 2) trunk_fwd(Args args_unused) {
;     ...
;         if (PHEN(11) && IN(s0 + 11)) { FRAME();
;             SchedPlain S; S.init((const bf16*)(F.ws + WS_R2), DFF, (const bf16*)lw(F, l, LW_W2), DFF, M / BM, D / BM, DFF, F.G, F.bid);
;             EpiResid E{(const bf16*)F.out, (l == DEPTH - 1) ? (bf16*)(F.ws + WS_R1) : (bf16*)F.out, (float*)(F.ws + WS_SSQ)};
;             gemm_phase<EpiResid, SchedPlain>(F.lds, F.wave, DFF, DFF, S, E);
;             SEAM(s0 + 11);
.LBB0_1467:
	s_add_u32 s4, s10, 0x1fc28000
	v_and_b32_e32 v15, 15, v14
	v_bfe_u32 v14, v14, 4, 2
	s_addc_u32 s5, s11, 0
	v_lshlrev_b32_e32 v17, 4, v14
	s_cmp_eq_u32 s71, 3
	v_lshl_or_b32 v154, s1, 6, v15
	v_lshl_or_b32 v17, v15, 6, v17
	v_lshlrev_b32_e32 v15, 2, v15
	s_cselect_b32 s13, s5, s9
	s_cselect_b32 s12, s4, s8
	s_and_b32 s7, s0, 3
	s_lshl_b32 s0, s1, 13
	v_and_b32_e32 v18, 32, v15
	s_add_i32 m0, s31, 0x18000
	v_lshl_add_u64 v[6:7], v[6:7], 0, s[28:29]
	v_bitop3_b32 v19, v17, s0, v18 bitop3:0xde
	s_lshl_b32 s0, s7, 12
	s_waitcnt vmcnt(2)
	s_barrier
	global_load_lds_dwordx4 v[6:7], off
	v_lshl_add_u64 v[4:5], v[4:5], 0, s[28:29]
	s_add_i32 m0, s31, 0x1a000
	s_add_i32 s47, s31, 0x8000
	s_add_i32 s48, s31, 0xa000
	v_bitop3_b32 v155, v17, s0, v18 bitop3:0xde
	global_load_lds_dwordx4 v[4:5], off
	v_lshl_add_u64 v[0:1], v[0:1], 0, s[28:29]
	s_mov_b32 m0, s47
	s_add_u32 s0, s36, 0x200080
	global_load_lds_dwordx4 v[0:1], off
	v_lshl_add_u64 v[0:1], v[2:3], 0, s[28:29]
	s_mov_b32 m0, s48
	s_addc_u32 s1, s37, 0
	global_load_lds_dwordx4 v[0:1], off
	s_add_i32 m0, s31, 0x1c000
	v_lshl_add_u64 v[0:1], s[0:1], 0, v[184:185]
	global_load_lds_dwordx4 v[0:1], off
	v_lshl_add_u64 v[0:1], s[0:1], 0, v[136:137]
	s_add_i32 m0, s31, 0x1e000
	s_movk_i32 s0, 0x80
	global_load_lds_dwordx4 v[0:1], off
	v_lshlrev_b32_e32 v0, 6, v14
	v_bitop3_b32 v157, v0, 64, v15 bitop3:0x36
	v_bitop3_b32 v158, v0, s0, v15 bitop3:0x36
	v_lshlrev_b32_e32 v0, 17, v8
	v_and_b32_e32 v0, 0xfffc0000, v0
	v_lshl_add_u32 v0, v9, 14, v0
	v_and_b32_e32 v1, 1, v8
	s_cmpk_lt_u32 s6, 0x100
	v_lshl_or_b32 v0, v1, 6, v0
	s_cselect_b64 s[14:15], -1, 0
	s_ashr_i32 s50, s20, 31
	s_ashr_i32 s51, s17, 31
	s_lshl_b32 s0, s7, 2
	v_lshl_add_u32 v138, v10, 1, v0
	v_lshlrev_b32_e32 v0, 17, v11
	s_add_u32 s0, s10, s0
	v_and_b32_e32 v0, 0xfffc0000, v0
	s_waitcnt vmcnt(6)
	s_addc_u32 s1, s11, 0
	v_lshl_add_u32 v0, v12, 14, v0
	v_and_b32_e32 v1, 1, v11
	v_lshlrev_b32_e32 v16, 3, v14
	s_add_u32 s52, s0, 0x49c28000
	v_lshl_or_b32 v0, v1, 6, v0
	v_lshl_or_b32 v156, s7, 5, v16
	s_mov_b32 s49, 0
	v_cmp_eq_u32_e64 s[4:5], 0, v14
	s_addc_u32 s53, s1, 0
	v_mov_b32_e32 v139, v185
	v_lshl_add_u32 v140, v13, 1, v0
	v_mov_b32_e32 v141, v185
	v_add_u32_e32 v159, 0, v19
	s_barrier
	v_mbcnt_lo_u32_b32 v248, -1, 0
	v_mbcnt_hi_u32_b32 v248, -1, v248
	s_lshl_b32 s98, s90, 10
	s_add_i32 s98, s98, 0x22000
	v_lshl_add_u32 v246, v248, 4, s98
	v_and_b32_e32 v249, 15, v248
	v_lshrrev_b32_e32 v242, 4, v248
	v_lshrrev_b32_e32 v243, 2, v249
	v_lshl_add_u32 v242, v243, 4, v242
	v_and_b32_e32 v243, 3, v249
	v_lshl_add_u32 v242, v243, 2, v242
	v_lshl_add_u32 v247, v242, 4, s98
	v_lshrrev_b32_e32 v242, 4, v248
	v_bfe_u32 v243, v248, 2, 2
	v_lshl_add_u32 v243, v242, 2, v243
	v_sub_u32_e32 v243, v243, v249
	v_and_b32_e32 v249, 3, v248
	v_sub_u32_e32 v249, v249, v242
	v_lshlrev_b32_e32 v249, 4, v249
	s_movk_i32 s98, 0x1000
	v_mad_i32_i24 v240, v243, s98, v249
	v_ashrrev_i32_e32 v241, 31, v240
	s_cmp_ge_u32 s90, 4
	s_cbranch_scc0 .Lprio_1470_done
	s_setprio 1

; #define PG8_STAGE(bufoff, gbase, voff) do { _Pragma("unroll") for (int _i = 0; _i < 2; ++_i) \
;         __builtin_amdgcn_global_load_lds((const unsigned*)((const char*)(gbase) + (voff)[_i]), (LAS unsigned*)(lds + (bufoff) + ldsw + _i * 8192), 16, 0, 0); } while (0)
; #define PG8_LDA(dst, b, h) do { _Pragma("unroll") for (int m = 0; m < 4; ++m) _Pragma("unroll") for (int k = 0; k < 2; ++k) dst[m][k] = *(const LAS bf16x8*)(lds + PG8_SA(b, h) + aoff + m * 2048 + k * 1024); } while (0)
; #define PG8_LDB(dst, b, h) do { _Pragma("unroll") for (int n = 0; n < 2; ++n) _Pragma("unroll") for (int k = 0; k < 2; ++k) dst[n][k] = *(const LAS bf16x8*)(lds + PG8_SB(b, h) + boff + n * 2048 + k * 1024); } while (0)
; #define PG8_MMA(ai, bj, At, Bt) do { __builtin_amdgcn_s_setprio(1); _Pragma("unroll") for (int m = 0; m < 4; ++m) _Pragma("unroll") for (int n = 0; n < 2; ++n) _Pragma("unroll") for (int k = 0; k < 2; ++k) \
;         acc[ai][bj][m][n] = __builtin_amdgcn_mfma_f32_16x16x32_bf16(Bt[n][k], At[m][k], acc[ai][bj][m][n], 0, 0, 0); __builtin_amdgcn_s_setprio(0); } while (0)
; #define PG8_WAIT_V(n) asm volatile("s_waitcnt vmcnt(" #n ")" ::: "memory")
; #define PG8_WAIT_L(n) asm volatile("s_waitcnt lgkmcnt(" #n ")" ::: "memory")
; #define PG8_BAR __builtin_amdgcn_s_barrier()
; #define PG8_SCHED __builtin_amdgcn_sched_barrier(0)
; template <class Epi, class Sched>
; DI void gemm_phase(LAS unsigned char* lds, const int wv, const int lda, const int ldb, const Sched& S, const Epi& E) {
;     ...
;             const char* a1 = cA + (size_t)(t + 1) * kstep;
;             const char* a2 = last ? nA : cA + (size_t)(t + 2) * kstep; const char* b2 = last ? nB : cB + (size_t)(t + 2) * kstep;
;             const char* a3 = a2 + kstep; const char* b3 = b2 + kstep;
;             PG8_LDB(B0, 0, 0); PG8_LDB(B1, 0, 1); PG8_SCHED; PG8_LDA(At, 0, 0); PG8_STAGE(PG8_SA(1, 1), a1 + hstepA, voffA);
;             PG8_WAIT_V(8); PG8_WAIT_L(0); PG8_BAR; PG8_MMA(0, 0, At, B0); PG8_MMA(0, 1, At, B1); PG8_BAR; PG8_SCHED;
;             PG8_LDA(At, 0, 1); PG8_STAGE(PG8_SB(0, 0), b2, voffB); PG8_STAGE(PG8_SB(0, 1), b2 + hstepB, voffB); PG8_STAGE(PG8_SA(0, 0), a2, voffA);
;             PG8_WAIT_V(8); PG8_WAIT_L(0); PG8_BAR; PG8_MMA(1, 0, At, B0); PG8_MMA(1, 1, At, B1); PG8_BAR; PG8_SCHED;
.LBB0_1477:
	s_add_u32 s36, s34, 0xffe00080
	s_addc_u32 s37, s35, -1
	s_add_i32 s56, 0, 0x10000
	s_cmpk_eq_i32 s55, 0x7c
	s_cselect_b32 s39, s0, s37
	s_cselect_b32 s38, s1, s36
	s_cselect_b32 s37, s11, s54
	s_cselect_b32 s36, s19, s23
	s_add_i32 s58, 0, 0x14000
	v_add_u32_e32 v150, s56, v155
	v_add_u32_e32 v172, s58, v155
	ds_read_b128 v[128:131], v150
	ds_read_b128 v[142:145], v150 offset:1024
	ds_read_b128 v[146:149], v150 offset:2048
	ds_read_b128 v[150:153], v150 offset:3072
	ds_read_b128 v[160:163], v172
	ds_read_b128 v[164:167], v172 offset:1024
	ds_read_b128 v[168:171], v172 offset:2048
	ds_read_b128 v[172:175], v172 offset:3072
	v_lshl_add_u64 v[216:217], s[34:35], 0, v[138:139]
	s_add_i32 m0, s31, 0xc000
	ds_read_b128 v[176:179], v159
	ds_read_b128 v[180:183], v159 offset:1024
	ds_read_b128 v[188:191], v159 offset:2048
	ds_read_b128 v[196:199], v159 offset:3072
	ds_read_b128 v[200:203], v159 offset:4096
	ds_read_b128 v[204:207], v159 offset:5120
	ds_read_b128 v[208:211], v159 offset:6144
	ds_read_b128 v[212:215], v159 offset:7168
	global_load_lds_dwordx4 v[216:217], off
	v_lshl_add_u64 v[216:217], s[34:35], 0, v[140:141]
	s_add_i32 m0, s31, 0xe000
	s_nop 0
	global_load_lds_dwordx4 v[216:217], off
	s_waitcnt vmcnt(8)
	s_waitcnt lgkmcnt(0)
	s_barrier
	s_waitcnt lgkmcnt(0)
	v_mfma_f32_16x16x32_bf16 v[124:127], v[128:131], v[176:179], v[124:127]
	v_mfma_f32_16x16x32_bf16 v[120:123], v[146:149], v[176:179], v[120:123]
	v_mfma_f32_16x16x32_bf16 v[108:111], v[128:131], v[188:191], v[108:111]
	v_mfma_f32_16x16x32_bf16 v[104:107], v[146:149], v[188:191], v[104:107]
	v_mfma_f32_16x16x32_bf16 v[96:99], v[128:131], v[200:203], v[96:99]
	v_mfma_f32_16x16x32_bf16 v[88:91], v[146:149], v[200:203], v[88:91]
	v_mfma_f32_16x16x32_bf16 v[80:83], v[128:131], v[208:211], v[80:83]
	v_mfma_f32_16x16x32_bf16 v[72:75], v[146:149], v[208:211], v[72:75]
	v_mfma_f32_16x16x32_bf16 v[124:127], v[142:145], v[180:183], v[124:127]
	v_mfma_f32_16x16x32_bf16 v[120:123], v[150:153], v[180:183], v[120:123]
	v_mfma_f32_16x16x32_bf16 v[108:111], v[142:145], v[196:199], v[108:111]
	v_mfma_f32_16x16x32_bf16 v[104:107], v[150:153], v[196:199], v[104:107]
	v_mfma_f32_16x16x32_bf16 v[96:99], v[142:145], v[204:207], v[96:99]
	v_mfma_f32_16x16x32_bf16 v[88:91], v[150:153], v[204:207], v[88:91]
	v_mfma_f32_16x16x32_bf16 v[80:83], v[142:145], v[212:215], v[80:83]
	v_mfma_f32_16x16x32_bf16 v[72:75], v[150:153], v[212:215], v[72:75]
	v_mfma_f32_16x16x32_bf16 v[116:119], v[160:163], v[176:179], v[116:119]
	v_mfma_f32_16x16x32_bf16 v[112:115], v[168:171], v[176:179], v[112:115]
	v_mfma_f32_16x16x32_bf16 v[100:103], v[160:163], v[188:191], v[100:103]
	v_mfma_f32_16x16x32_bf16 v[92:95], v[168:171], v[188:191], v[92:95]
	v_mfma_f32_16x16x32_bf16 v[84:87], v[160:163], v[200:203], v[84:87]
	v_mfma_f32_16x16x32_bf16 v[76:79], v[168:171], v[200:203], v[76:79]
	v_mfma_f32_16x16x32_bf16 v[68:71], v[160:163], v[208:211], v[68:71]
	v_mfma_f32_16x16x32_bf16 v[64:67], v[168:171], v[208:211], v[64:67]
	v_mfma_f32_16x16x32_bf16 v[116:119], v[164:167], v[180:183], v[116:119]
	v_mfma_f32_16x16x32_bf16 v[112:115], v[172:175], v[180:183], v[112:115]
	v_mfma_f32_16x16x32_bf16 v[100:103], v[164:167], v[196:199], v[100:103]
	v_mfma_f32_16x16x32_bf16 v[92:95], v[172:175], v[196:199], v[92:95]
	v_mfma_f32_16x16x32_bf16 v[84:87], v[164:167], v[204:207], v[84:87]
	v_mfma_f32_16x16x32_bf16 v[76:79], v[172:175], v[204:207], v[76:79]
	v_mfma_f32_16x16x32_bf16 v[68:71], v[164:167], v[212:215], v[68:71]
	v_mfma_f32_16x16x32_bf16 v[64:67], v[172:175], v[212:215], v[64:67]
	s_barrier
	s_add_i32 s56, s56, s43
	v_lshl_add_u64 v[216:217], s[36:37], 0, v[184:185]
	s_mov_b32 m0, s56
	ds_read_b128 v[176:179], v159 offset:16384
	ds_read_b128 v[180:183], v159 offset:17408
	ds_read_b128 v[188:191], v159 offset:18432
	ds_read_b128 v[196:199], v159 offset:19456
	ds_read_b128 v[200:203], v159 offset:20480
	ds_read_b128 v[204:207], v159 offset:21504
	ds_read_b128 v[208:211], v159 offset:22528
	ds_read_b128 v[212:215], v159 offset:23552
	global_load_lds_dwordx4 v[216:217], off
	s_add_i32 m0, s56, 0x2000
	s_add_u32 s56, s36, 0x200000
	v_lshl_add_u64 v[218:219], s[36:37], 0, v[136:137]
	s_addc_u32 s57, s37, 0
	s_add_i32 s58, s58, s43
	global_load_lds_dwordx4 v[218:219], off
	v_lshl_add_u64 v[220:221], s[56:57], 0, v[184:185]
	s_mov_b32 m0, s58
	v_lshl_add_u64 v[222:223], s[38:39], 0, v[134:135]
	global_load_lds_dwordx4 v[220:221], off
	v_lshl_add_u64 v[220:221], s[56:57], 0, v[136:137]
	s_add_i32 m0, s58, 0x2000
	s_nop 0
	global_load_lds_dwordx4 v[220:221], off
	v_lshl_add_u64 v[220:221], s[38:39], 0, v[132:133]
	s_mov_b32 m0, s31
	s_nop 0
	global_load_lds_dwordx4 v[220:221], off
	s_mov_b32 m0, s44
	s_nop 0
	global_load_lds_dwordx4 v[222:223], off
	s_waitcnt vmcnt(8)
	s_waitcnt lgkmcnt(0)
	s_barrier
; #define PG8_STAGE(bufoff, gbase, voff) do { _Pragma("unroll") for (int _i = 0; _i < 2; ++_i) \
;         __builtin_amdgcn_global_load_lds((const unsigned*)((const char*)(gbase) + (voff)[_i]), (LAS unsigned*)(lds + (bufoff) + ldsw + _i * 8192), 16, 0, 0); } while (0)
; #define PG8_LDA(dst, b, h) do { _Pragma("unroll") for (int m = 0; m < 4; ++m) _Pragma("unroll") for (int k = 0; k < 2; ++k) dst[m][k] = *(const LAS bf16x8*)(lds + PG8_SA(b, h) + aoff + m * 2048 + k * 1024); } while (0)
; #define PG8_LDB(dst, b, h) do { _Pragma("unroll") for (int n = 0; n < 2; ++n) _Pragma("unroll") for (int k = 0; k < 2; ++k) dst[n][k] = *(const LAS bf16x8*)(lds + PG8_SB(b, h) + boff + n * 2048 + k * 1024); } while (0)
; #define PG8_MMA(ai, bj, At, Bt) do { __builtin_amdgcn_s_setprio(1); _Pragma("unroll") for (int m = 0; m < 4; ++m) _Pragma("unroll") for (int n = 0; n < 2; ++n) _Pragma("unroll") for (int k = 0; k < 2; ++k) \
;         acc[ai][bj][m][n] = __builtin_amdgcn_mfma_f32_16x16x32_bf16(Bt[n][k], At[m][k], acc[ai][bj][m][n], 0, 0, 0); __builtin_amdgcn_s_setprio(0); } while (0)
; #define PG8_WAIT_V(n) asm volatile("s_waitcnt vmcnt(" #n ")" ::: "memory")
; #define PG8_WAIT_L(n) asm volatile("s_waitcnt lgkmcnt(" #n ")" ::: "memory")
; #define PG8_BAR __builtin_amdgcn_s_barrier()
; #define PG8_SCHED __builtin_amdgcn_sched_barrier(0)
; template <class Epi, class Sched>
; DI void gemm_phase(LAS unsigned char* lds, const int wv, const int lda, const int ldb, const Sched& S, const Epi& E) {
;     ...
;             PG8_WAIT_V(8); PG8_WAIT_L(0); PG8_BAR; PG8_MMA(1, 0, At, B0); PG8_MMA(1, 1, At, B1); PG8_BAR; PG8_SCHED;
;             PG8_LDB(B0, 1, 0); PG8_LDB(B1, 1, 1); PG8_SCHED; PG8_LDA(At, 1, 0); PG8_STAGE(PG8_SA(0, 1), a2 + hstepA, voffA);
;             PG8_WAIT_V(8); PG8_WAIT_L(0); PG8_BAR; PG8_MMA(0, 0, At, B0); PG8_MMA(0, 1, At, B1); PG8_BAR; PG8_SCHED;
	s_waitcnt lgkmcnt(0)
	v_mfma_f32_16x16x32_bf16 v[60:63], v[128:131], v[176:179], v[60:63]
	v_mfma_f32_16x16x32_bf16 v[56:59], v[146:149], v[176:179], v[56:59]
	v_mfma_f32_16x16x32_bf16 v[48:51], v[128:131], v[188:191], v[48:51]
	v_mfma_f32_16x16x32_bf16 v[40:43], v[146:149], v[188:191], v[40:43]
	v_mfma_f32_16x16x32_bf16 v[32:35], v[128:131], v[200:203], v[32:35]
	v_mfma_f32_16x16x32_bf16 v[24:27], v[146:149], v[200:203], v[24:27]
	v_mfma_f32_16x16x32_bf16 v[16:19], v[128:131], v[208:211], v[16:19]
	v_mfma_f32_16x16x32_bf16 v[8:11], v[146:149], v[208:211], v[8:11]
	v_mfma_f32_16x16x32_bf16 v[60:63], v[142:145], v[180:183], v[60:63]
	v_mfma_f32_16x16x32_bf16 v[56:59], v[150:153], v[180:183], v[56:59]
	v_mfma_f32_16x16x32_bf16 v[48:51], v[142:145], v[196:199], v[48:51]
	v_mfma_f32_16x16x32_bf16 v[40:43], v[150:153], v[196:199], v[40:43]
	v_mfma_f32_16x16x32_bf16 v[32:35], v[142:145], v[204:207], v[32:35]
	v_mfma_f32_16x16x32_bf16 v[24:27], v[150:153], v[204:207], v[24:27]
	v_mfma_f32_16x16x32_bf16 v[16:19], v[142:145], v[212:215], v[16:19]
	v_mfma_f32_16x16x32_bf16 v[8:11], v[150:153], v[212:215], v[8:11]
	v_mfma_f32_16x16x32_bf16 v[52:55], v[160:163], v[176:179], v[52:55]
	v_mfma_f32_16x16x32_bf16 v[44:47], v[168:171], v[176:179], v[44:47]
	v_mfma_f32_16x16x32_bf16 v[36:39], v[160:163], v[188:191], v[36:39]
	v_mfma_f32_16x16x32_bf16 v[28:31], v[168:171], v[188:191], v[28:31]
	v_mfma_f32_16x16x32_bf16 v[20:23], v[160:163], v[200:203], v[20:23]
	v_mfma_f32_16x16x32_bf16 v[12:15], v[168:171], v[200:203], v[12:15]
	v_mfma_f32_16x16x32_bf16 v[4:7], v[160:163], v[208:211], v[4:7]
	v_mfma_f32_16x16x32_bf16 v[0:3], v[168:171], v[208:211], v[0:3]
	v_mfma_f32_16x16x32_bf16 v[52:55], v[164:167], v[180:183], v[52:55]
	v_mfma_f32_16x16x32_bf16 v[44:47], v[172:175], v[180:183], v[44:47]
	v_mfma_f32_16x16x32_bf16 v[36:39], v[164:167], v[196:199], v[36:39]
	v_mfma_f32_16x16x32_bf16 v[28:31], v[172:175], v[196:199], v[28:31]
	v_mfma_f32_16x16x32_bf16 v[20:23], v[164:167], v[204:207], v[20:23]
	v_mfma_f32_16x16x32_bf16 v[12:15], v[172:175], v[204:207], v[12:15]
	v_mfma_f32_16x16x32_bf16 v[4:7], v[164:167], v[212:215], v[4:7]
	v_mfma_f32_16x16x32_bf16 v[0:3], v[172:175], v[212:215], v[0:3]
	s_barrier
	s_add_i32 s56, 0, 0x18000
	s_add_i32 s57, 0, 0x1c000
	v_add_u32_e32 v150, s56, v155
	v_add_u32_e32 v172, s57, v155
	ds_read_b128 v[128:131], v150
	ds_read_b128 v[142:145], v150 offset:1024
	ds_read_b128 v[146:149], v150 offset:2048
	ds_read_b128 v[150:153], v150 offset:3072
	ds_read_b128 v[160:163], v172
	ds_read_b128 v[164:167], v172 offset:1024
	ds_read_b128 v[168:171], v172 offset:2048
	ds_read_b128 v[172:175], v172 offset:3072
	s_add_u32 s38, s38, 0x200000
	s_addc_u32 s39, s39, 0
	s_mov_b32 m0, s45
	v_lshl_add_u64 v[234:235], s[38:39], 0, v[132:133]
	ds_read_b128 v[176:179], v159 offset:32768
	ds_read_b128 v[180:183], v159 offset:33792
	ds_read_b128 v[188:191], v159 offset:34816
	ds_read_b128 v[196:199], v159 offset:35840
	ds_read_b128 v[200:203], v159 offset:36864
	ds_read_b128 v[204:207], v159 offset:37888
	ds_read_b128 v[208:211], v159 offset:38912
	ds_read_b128 v[212:215], v159 offset:39936
	global_load_lds_dwordx4 v[234:235], off
	v_lshl_add_u64 v[234:235], s[38:39], 0, v[134:135]
	s_mov_b32 m0, s46
	s_nop 0
	global_load_lds_dwordx4 v[234:235], off
	s_waitcnt vmcnt(8)
	s_waitcnt lgkmcnt(0)
	s_barrier
	s_waitcnt lgkmcnt(0)
	v_mfma_f32_16x16x32_bf16 v[124:127], v[128:131], v[176:179], v[124:127]
	v_mfma_f32_16x16x32_bf16 v[120:123], v[146:149], v[176:179], v[120:123]
	v_mfma_f32_16x16x32_bf16 v[108:111], v[128:131], v[188:191], v[108:111]
	v_mfma_f32_16x16x32_bf16 v[104:107], v[146:149], v[188:191], v[104:107]
	v_mfma_f32_16x16x32_bf16 v[96:99], v[128:131], v[200:203], v[96:99]
	v_mfma_f32_16x16x32_bf16 v[88:91], v[146:149], v[200:203], v[88:91]
	v_mfma_f32_16x16x32_bf16 v[80:83], v[128:131], v[208:211], v[80:83]
	v_mfma_f32_16x16x32_bf16 v[72:75], v[146:149], v[208:211], v[72:75]
	v_mfma_f32_16x16x32_bf16 v[124:127], v[142:145], v[180:183], v[124:127]
	v_mfma_f32_16x16x32_bf16 v[120:123], v[150:153], v[180:183], v[120:123]
	v_mfma_f32_16x16x32_bf16 v[108:111], v[142:145], v[196:199], v[108:111]
	v_mfma_f32_16x16x32_bf16 v[104:107], v[150:153], v[196:199], v[104:107]
	v_mfma_f32_16x16x32_bf16 v[96:99], v[142:145], v[204:207], v[96:99]
	v_mfma_f32_16x16x32_bf16 v[88:91], v[150:153], v[204:207], v[88:91]
	v_mfma_f32_16x16x32_bf16 v[80:83], v[142:145], v[212:215], v[80:83]
	v_mfma_f32_16x16x32_bf16 v[72:75], v[150:153], v[212:215], v[72:75]
	v_mfma_f32_16x16x32_bf16 v[116:119], v[160:163], v[176:179], v[116:119]
	v_mfma_f32_16x16x32_bf16 v[112:115], v[168:171], v[176:179], v[112:115]
	v_mfma_f32_16x16x32_bf16 v[100:103], v[160:163], v[188:191], v[100:103]
	v_mfma_f32_16x16x32_bf16 v[92:95], v[168:171], v[188:191], v[92:95]
	v_mfma_f32_16x16x32_bf16 v[84:87], v[160:163], v[200:203], v[84:87]
	v_mfma_f32_16x16x32_bf16 v[76:79], v[168:171], v[200:203], v[76:79]
	v_mfma_f32_16x16x32_bf16 v[68:71], v[160:163], v[208:211], v[68:71]
	v_mfma_f32_16x16x32_bf16 v[64:67], v[168:171], v[208:211], v[64:67]
	v_mfma_f32_16x16x32_bf16 v[116:119], v[164:167], v[180:183], v[116:119]
	v_mfma_f32_16x16x32_bf16 v[112:115], v[172:175], v[180:183], v[112:115]
	v_mfma_f32_16x16x32_bf16 v[100:103], v[164:167], v[196:199], v[100:103]
	v_mfma_f32_16x16x32_bf16 v[92:95], v[172:175], v[196:199], v[92:95]
	v_mfma_f32_16x16x32_bf16 v[84:87], v[164:167], v[204:207], v[84:87]
	v_mfma_f32_16x16x32_bf16 v[76:79], v[172:175], v[204:207], v[76:79]
	v_mfma_f32_16x16x32_bf16 v[68:71], v[164:167], v[212:215], v[68:71]
	v_mfma_f32_16x16x32_bf16 v[64:67], v[172:175], v[212:215], v[64:67]
	s_barrier
; #define PG8_STAGE(bufoff, gbase, voff) do { _Pragma("unroll") for (int _i = 0; _i < 2; ++_i) \
;         __builtin_amdgcn_global_load_lds((const unsigned*)((const char*)(gbase) + (voff)[_i]), (LAS unsigned*)(lds + (bufoff) + ldsw + _i * 8192), 16, 0, 0); } while (0)
; #define PG8_LDA(dst, b, h) do { _Pragma("unroll") for (int m = 0; m < 4; ++m) _Pragma("unroll") for (int k = 0; k < 2; ++k) dst[m][k] = *(const LAS bf16x8*)(lds + PG8_SA(b, h) + aoff + m * 2048 + k * 1024); } while (0)
; #define PG8_MMA(ai, bj, At, Bt) do { __builtin_amdgcn_s_setprio(1); _Pragma("unroll") for (int m = 0; m < 4; ++m) _Pragma("unroll") for (int n = 0; n < 2; ++n) _Pragma("unroll") for (int k = 0; k < 2; ++k) \
;         acc[ai][bj][m][n] = __builtin_amdgcn_mfma_f32_16x16x32_bf16(Bt[n][k], At[m][k], acc[ai][bj][m][n], 0, 0, 0); __builtin_amdgcn_s_setprio(0); } while (0)
; #define PG8_WAIT_V(n) asm volatile("s_waitcnt vmcnt(" #n ")" ::: "memory")
; #define PG8_WAIT_L(n) asm volatile("s_waitcnt lgkmcnt(" #n ")" ::: "memory")
; #define PG8_BAR __builtin_amdgcn_s_barrier()
; #define PG8_SCHED __builtin_amdgcn_sched_barrier(0)
; template <class Epi, class Sched>
; DI void gemm_phase(LAS unsigned char* lds, const int wv, const int lda, const int ldb, const Sched& S, const Epi& E) {
;     ...
;             PG8_LDA(At, 1, 1); PG8_STAGE(PG8_SB(1, 0), b3, voffB); PG8_STAGE(PG8_SB(1, 1), b3 + hstepB, voffB); PG8_STAGE(PG8_SA(1, 0), a3, voffA);
;             PG8_WAIT_V(8); PG8_WAIT_L(0); PG8_BAR; PG8_MMA(1, 0, At, B0); PG8_MMA(1, 1, At, B1); PG8_BAR; PG8_SCHED;
;         }
;         if (wr == 0) PG8_BAR;
	s_add_i32 s38, s56, s43
	v_lshl_add_u64 v[216:217], v[216:217], 0, s[28:29]
	s_mov_b32 m0, s38
	ds_read_b128 v[176:179], v159 offset:49152
	ds_read_b128 v[180:183], v159 offset:50176
	ds_read_b128 v[188:191], v159 offset:51200
	ds_read_b128 v[196:199], v159 offset:52224
	ds_read_b128 v[200:203], v159 offset:53248
	ds_read_b128 v[204:207], v159 offset:54272
	ds_read_b128 v[208:211], v159 offset:55296
	ds_read_b128 v[212:215], v159 offset:56320
	global_load_lds_dwordx4 v[216:217], off
	s_add_i32 m0, s38, 0x2000
	s_add_u32 s36, s36, 0x200080
	v_lshl_add_u64 v[216:217], v[218:219], 0, s[28:29]
	s_addc_u32 s37, s37, 0
	s_add_i32 s38, s57, s43
	global_load_lds_dwordx4 v[216:217], off
	v_lshl_add_u64 v[216:217], s[36:37], 0, v[184:185]
	s_mov_b32 m0, s38
	s_nop 0
	global_load_lds_dwordx4 v[216:217], off
	v_lshl_add_u64 v[216:217], s[36:37], 0, v[136:137]
	s_add_i32 m0, s38, 0x2000
	s_nop 0
	global_load_lds_dwordx4 v[216:217], off
	v_lshl_add_u64 v[216:217], v[220:221], 0, s[28:29]
	s_mov_b32 m0, s47
	s_nop 0
	global_load_lds_dwordx4 v[216:217], off
	v_lshl_add_u64 v[216:217], v[222:223], 0, s[28:29]
	s_mov_b32 m0, s48
	s_nop 0
	global_load_lds_dwordx4 v[216:217], off
	s_waitcnt vmcnt(8)
	s_waitcnt lgkmcnt(0)
	s_barrier
	s_waitcnt lgkmcnt(0)
	v_mfma_f32_16x16x32_bf16 v[60:63], v[128:131], v[176:179], v[60:63]
	v_mfma_f32_16x16x32_bf16 v[56:59], v[146:149], v[176:179], v[56:59]
	v_mfma_f32_16x16x32_bf16 v[48:51], v[128:131], v[188:191], v[48:51]
	v_mfma_f32_16x16x32_bf16 v[40:43], v[146:149], v[188:191], v[40:43]
	v_mfma_f32_16x16x32_bf16 v[32:35], v[128:131], v[200:203], v[32:35]
	v_mfma_f32_16x16x32_bf16 v[24:27], v[146:149], v[200:203], v[24:27]
	v_mfma_f32_16x16x32_bf16 v[16:19], v[128:131], v[208:211], v[16:19]
	v_mfma_f32_16x16x32_bf16 v[8:11], v[146:149], v[208:211], v[8:11]
	v_mfma_f32_16x16x32_bf16 v[60:63], v[142:145], v[180:183], v[60:63]
	v_mfma_f32_16x16x32_bf16 v[56:59], v[150:153], v[180:183], v[56:59]
	v_mfma_f32_16x16x32_bf16 v[48:51], v[142:145], v[196:199], v[48:51]
	v_mfma_f32_16x16x32_bf16 v[40:43], v[150:153], v[196:199], v[40:43]
	v_mfma_f32_16x16x32_bf16 v[32:35], v[142:145], v[204:207], v[32:35]
	v_mfma_f32_16x16x32_bf16 v[24:27], v[150:153], v[204:207], v[24:27]
	v_mfma_f32_16x16x32_bf16 v[16:19], v[142:145], v[212:215], v[16:19]
	v_mfma_f32_16x16x32_bf16 v[8:11], v[150:153], v[212:215], v[8:11]
	v_mfma_f32_16x16x32_bf16 v[52:55], v[160:163], v[176:179], v[52:55]
	v_mfma_f32_16x16x32_bf16 v[44:47], v[168:171], v[176:179], v[44:47]
	v_mfma_f32_16x16x32_bf16 v[36:39], v[160:163], v[188:191], v[36:39]
	v_mfma_f32_16x16x32_bf16 v[28:31], v[168:171], v[188:191], v[28:31]
	v_mfma_f32_16x16x32_bf16 v[20:23], v[160:163], v[200:203], v[20:23]
	v_mfma_f32_16x16x32_bf16 v[12:15], v[168:171], v[200:203], v[12:15]
	v_mfma_f32_16x16x32_bf16 v[4:7], v[160:163], v[208:211], v[4:7]
	v_mfma_f32_16x16x32_bf16 v[0:3], v[168:171], v[208:211], v[0:3]
	v_mfma_f32_16x16x32_bf16 v[52:55], v[164:167], v[180:183], v[52:55]
	v_mfma_f32_16x16x32_bf16 v[44:47], v[172:175], v[180:183], v[44:47]
	v_mfma_f32_16x16x32_bf16 v[36:39], v[164:167], v[196:199], v[36:39]
	v_mfma_f32_16x16x32_bf16 v[28:31], v[172:175], v[196:199], v[28:31]
	v_mfma_f32_16x16x32_bf16 v[20:23], v[164:167], v[204:207], v[20:23]
	v_mfma_f32_16x16x32_bf16 v[12:15], v[172:175], v[204:207], v[12:15]
	v_mfma_f32_16x16x32_bf16 v[4:7], v[164:167], v[212:215], v[4:7]
	v_mfma_f32_16x16x32_bf16 v[0:3], v[172:175], v[212:215], v[0:3]
	s_barrier
	s_add_i32 s55, s55, 2
	s_add_u32 s34, s34, 0x100
	s_addc_u32 s35, s35, 0
	s_add_u32 s23, s23, 0x100
	s_addc_u32 s54, s54, 0
	s_cmpk_gt_u32 s55, 0x7d
	s_cbranch_scc0 .LBB0_1477
	s_and_b64 vcc, exec, s[14:15]
	s_cbranch_vccz .LBB0_1480
	s_barrier

; DI int lane_id_fresh() { int l; asm volatile("v_mbcnt_lo_u32_b32 %0, -1, 0\n\tv_mbcnt_hi_u32_b32 %0, -1, %0" : "=v"(l)); return l; }
; #define SEAM(k) do { if (IN((k) + 1) && IN(k)) xcd_barrier(bar); } while (0)
; __device__ __forceinline__ void xcd_barrier(const XcdBarrier& b) {
;     asm volatile("s_waitcnt vmcnt(0)" ::: "memory");
;     __syncthreads();
;     if (b.w0 && lane_id_fresh() == 0) {
;         unsigned* bar = b.bar;
;         __builtin_amdgcn_s_waitcnt(0);
;         unsigned nloc = b.st[0], nx = b.st[1];
;         if (nloc == 0u) { xcd_barrier_complete(bar, b.x, nloc, nx); b.st[0] = nloc; b.st[1] = nx; }
; __global__ void __launch_bounds__(512, 2) trunk_fwd(Args args_unused) {
;     ...
;             SEAM(s0 + 11);
.LBB0_1500:
	s_setprio 0
	v_readlane_b32 s0, v254, 37
	v_readlane_b32 s4, v252, 10
	s_add_i32 s0, s0, 13
	v_readlane_b32 s7, v252, 13
	s_cmp_ge_i32 s0, s7
	s_movk_i32 s20, 0x5ff
	v_readlane_b32 s5, v252, 11
	v_readlane_b32 s6, v252, 12
	s_cbranch_scc0 .LBB0_1501
	s_getpc_b64 s[98:99]
